# K loops: LDS-read wait moved in front of the pre-MFMA barrier in the segments whose reads precede two DMA issues
# speedup vs baseline: 1.0347x; 1.0031x over previous
.Lpz_P2b:
	s_and_b64 s[6:7], s[6:7], exec
	s_cselect_b32 s37, s41, s45
	s_cselect_b32 s39, s40, s44
	s_cselect_b32 s51, s43, s47
	s_cselect_b32 s65, s42, s46
	s_add_u32 s66, s46, 0x100
	s_addc_u32 s67, s47, 0
	s_mov_b32 s46, 0
	ds_read_b128 v[144:147], v166
	ds_read_b128 v[148:151], v166 offset:1024
	ds_read_b128 v[152:155], v166 offset:2048
	ds_read_b128 v[156:159], v166 offset:3072
	s_add_i32 s68, s46, 2
	s_add_u32 s6, s44, 0x100
	s_addc_u32 s7, s45, 0
	s_cmp_eq_u32 s60, s46
	s_cselect_b32 s46, s65, s66
	s_cselect_b32 s49, s37, s7
	s_cselect_b32 s48, s39, s6
	s_cselect_b32 s47, s51, s67
	v_lshl_add_u64 v[160:161], s[44:45], 0, v[136:137]
	s_add_i32 m0, s35, 0xc000
	ds_read_b128 v[170:173], v167
	ds_read_b128 v[174:177], v167 offset:1024
	ds_read_b128 v[178:181], v167 offset:2048
	ds_read_b128 v[182:185], v167 offset:3072
	ds_read_b128 v[186:189], v167 offset:4096
	ds_read_b128 v[190:193], v167 offset:5120
	ds_read_b128 v[194:197], v167 offset:6144
	ds_read_b128 v[198:201], v167 offset:7168
	global_load_lds_dwordx4 v[160:161], off
	v_lshl_add_u64 v[160:161], s[44:45], 0, v[138:139]
	s_add_i32 m0, s35, 0xe000
	s_nop 0
	global_load_lds_dwordx4 v[160:161], off
	s_waitcnt lgkmcnt(8)
	s_setprio 1
	s_barrier
	s_waitcnt lgkmcnt(0)
	v_mfma_f32_16x16x32_bf16 v[100:103], v[144:147], v[170:173], 0
	v_mfma_f32_16x16x32_bf16 v[88:91], v[152:155], v[170:173], 0
	v_mfma_f32_16x16x32_bf16 v[96:99], v[144:147], v[178:181], 0
	v_mfma_f32_16x16x32_bf16 v[80:83], v[152:155], v[178:181], 0
	v_mfma_f32_16x16x32_bf16 v[72:75], v[144:147], v[186:189], 0
	v_mfma_f32_16x16x32_bf16 v[60:63], v[152:155], v[186:189], 0
	v_mfma_f32_16x16x32_bf16 v[56:59], v[144:147], v[194:197], 0
	v_mfma_f32_16x16x32_bf16 v[48:51], v[152:155], v[194:197], 0
	v_mfma_f32_16x16x32_bf16 v[100:103], v[148:151], v[174:177], v[100:103]
	v_mfma_f32_16x16x32_bf16 v[88:91], v[156:159], v[174:177], v[88:91]
	v_mfma_f32_16x16x32_bf16 v[96:99], v[148:151], v[182:185], v[96:99]
	v_mfma_f32_16x16x32_bf16 v[80:83], v[156:159], v[182:185], v[80:83]
	v_mfma_f32_16x16x32_bf16 v[72:75], v[148:151], v[190:193], v[72:75]
	v_mfma_f32_16x16x32_bf16 v[60:63], v[156:159], v[190:193], v[60:63]
	v_mfma_f32_16x16x32_bf16 v[56:59], v[148:151], v[198:201], v[56:59]
	v_mfma_f32_16x16x32_bf16 v[48:51], v[156:159], v[198:201], v[48:51]
	s_barrier
	s_setprio 0
	s_add_i32 s44, s62, s52
	v_lshl_add_u64 v[160:161], s[46:47], 0, v[132:133]
	s_mov_b32 m0, s44
	ds_read_b128 v[202:205], v168
	ds_read_b128 v[206:209], v168 offset:1024
	ds_read_b128 v[210:213], v168 offset:2048
	ds_read_b128 v[214:217], v168 offset:3072
	global_load_lds_dwordx4 v[160:161], off
	v_lshl_add_u64 v[218:219], s[46:47], 0, v[128:129]
	s_add_i32 m0, s44, 0x2000
	s_nop 0
	global_load_lds_dwordx4 v[218:219], off
	s_waitcnt lgkmcnt(0)
	s_setprio 1
	s_barrier
	v_mfma_f32_16x16x32_bf16 v[92:95], v[202:205], v[170:173], 0
	v_mfma_f32_16x16x32_bf16 v[108:111], v[210:213], v[170:173], 0
	v_mfma_f32_16x16x32_bf16 v[84:87], v[202:205], v[178:181], 0
	v_mfma_f32_16x16x32_bf16 v[104:107], v[210:213], v[178:181], 0
	v_mfma_f32_16x16x32_bf16 v[64:67], v[202:205], v[186:189], 0
	v_mfma_f32_16x16x32_bf16 v[76:79], v[210:213], v[186:189], 0
	v_mfma_f32_16x16x32_bf16 v[52:55], v[202:205], v[194:197], 0
	v_mfma_f32_16x16x32_bf16 v[68:71], v[210:213], v[194:197], 0
	v_mfma_f32_16x16x32_bf16 v[92:95], v[206:209], v[174:177], v[92:95]
	v_mfma_f32_16x16x32_bf16 v[108:111], v[214:217], v[174:177], v[108:111]
	v_mfma_f32_16x16x32_bf16 v[84:87], v[206:209], v[182:185], v[84:87]
	v_mfma_f32_16x16x32_bf16 v[104:107], v[214:217], v[182:185], v[104:107]
	v_mfma_f32_16x16x32_bf16 v[64:67], v[206:209], v[190:193], v[64:67]
	v_mfma_f32_16x16x32_bf16 v[76:79], v[214:217], v[190:193], v[76:79]
	v_mfma_f32_16x16x32_bf16 v[52:55], v[206:209], v[198:201], v[52:55]
	v_mfma_f32_16x16x32_bf16 v[68:71], v[214:217], v[198:201], v[68:71]
	s_mov_b32 m0, s35
	v_lshl_add_u64 v[220:221], s[48:49], 0, v[134:135]
	s_barrier
	s_setprio 0
	ds_read_b128 v[170:173], v167 offset:16384
	ds_read_b128 v[174:177], v167 offset:17408
	ds_read_b128 v[178:181], v167 offset:18432
	ds_read_b128 v[182:185], v167 offset:19456
	ds_read_b128 v[186:189], v167 offset:20480
	ds_read_b128 v[190:193], v167 offset:21504
	ds_read_b128 v[194:197], v167 offset:22528
	ds_read_b128 v[198:201], v167 offset:23552
	global_load_lds_dwordx4 v[220:221], off
	v_lshl_add_u64 v[224:225], s[48:49], 0, v[130:131]
	s_mov_b32 m0, s53
	s_nop 0
	global_load_lds_dwordx4 v[224:225], off
	s_waitcnt lgkmcnt(0)
	s_setprio 1
	s_barrier
	v_mfma_f32_16x16x32_bf16 v[40:43], v[144:147], v[170:173], 0
	v_mfma_f32_16x16x32_bf16 v[32:35], v[152:155], v[170:173], 0
	v_mfma_f32_16x16x32_bf16 v[24:27], v[144:147], v[178:181], 0
	v_mfma_f32_16x16x32_bf16 v[20:23], v[152:155], v[178:181], 0
	v_mfma_f32_16x16x32_bf16 v[4:7], v[144:147], v[186:189], 0
	v_mfma_f32_16x16x32_bf16 v[124:127], v[152:155], v[186:189], 0
	v_mfma_f32_16x16x32_bf16 v[0:3], v[144:147], v[194:197], 0
	v_mfma_f32_16x16x32_bf16 v[116:119], v[152:155], v[194:197], 0
	v_mfma_f32_16x16x32_bf16 v[40:43], v[148:151], v[174:177], v[40:43]
	v_mfma_f32_16x16x32_bf16 v[32:35], v[156:159], v[174:177], v[32:35]
	v_mfma_f32_16x16x32_bf16 v[24:27], v[148:151], v[182:185], v[24:27]
	v_mfma_f32_16x16x32_bf16 v[20:23], v[156:159], v[182:185], v[20:23]
	v_mfma_f32_16x16x32_bf16 v[4:7], v[148:151], v[190:193], v[4:7]
	v_mfma_f32_16x16x32_bf16 v[124:127], v[156:159], v[190:193], v[124:127]
	v_mfma_f32_16x16x32_bf16 v[0:3], v[148:151], v[198:201], v[0:3]
	v_mfma_f32_16x16x32_bf16 v[116:119], v[156:159], v[198:201], v[116:119]
	s_barrier
	s_setprio 0
	s_add_u32 s44, s46, 0x40000
	s_addc_u32 s45, s47, 0
	s_add_i32 s69, s64, s52
	v_lshl_add_u64 v[144:145], s[44:45], 0, v[132:133]
	s_mov_b32 m0, s69
	s_nop 0
	global_load_lds_dwordx4 v[144:145], off
	v_lshl_add_u64 v[144:145], s[44:45], 0, v[128:129]
	s_add_i32 m0, s69, 0x2000
	s_nop 0
	global_load_lds_dwordx4 v[144:145], off
	s_waitcnt vmcnt(6)
	s_setprio 1
	s_barrier
	v_mfma_f32_16x16x32_bf16 v[28:31], v[202:205], v[170:173], 0
	v_mfma_f32_16x16x32_bf16 v[44:47], v[210:213], v[170:173], 0
	v_mfma_f32_16x16x32_bf16 v[16:19], v[202:205], v[178:181], 0
	v_mfma_f32_16x16x32_bf16 v[36:39], v[210:213], v[178:181], 0
	v_mfma_f32_16x16x32_bf16 v[120:123], v[202:205], v[186:189], 0
	v_mfma_f32_16x16x32_bf16 v[12:15], v[210:213], v[186:189], 0
	v_mfma_f32_16x16x32_bf16 v[112:115], v[202:205], v[194:197], 0
	v_mfma_f32_16x16x32_bf16 v[8:11], v[210:213], v[194:197], 0
	v_mfma_f32_16x16x32_bf16 v[28:31], v[206:209], v[174:177], v[28:31]
	v_mfma_f32_16x16x32_bf16 v[44:47], v[214:217], v[174:177], v[44:47]
	v_mfma_f32_16x16x32_bf16 v[16:19], v[206:209], v[182:185], v[16:19]
	v_mfma_f32_16x16x32_bf16 v[36:39], v[214:217], v[182:185], v[36:39]
	v_mfma_f32_16x16x32_bf16 v[120:123], v[206:209], v[190:193], v[120:123]
	v_mfma_f32_16x16x32_bf16 v[12:15], v[214:217], v[190:193], v[12:15]
	v_mfma_f32_16x16x32_bf16 v[112:115], v[206:209], v[198:201], v[112:115]
	v_mfma_f32_16x16x32_bf16 v[8:11], v[214:217], v[198:201], v[8:11]
	s_add_i32 s69, 0, 0x18000
	v_add_u32_e32 v156, s69, v163
	s_barrier
	s_setprio 0
	ds_read_b128 v[144:147], v156
	ds_read_b128 v[148:151], v156 offset:1024
	ds_read_b128 v[152:155], v156 offset:2048
	ds_read_b128 v[156:159], v156 offset:3072
	s_add_u32 s44, s48, 0x2000
	s_addc_u32 s45, s49, 0
	s_mov_b32 m0, s54
	v_lshl_add_u64 v[202:203], s[44:45], 0, v[134:135]
	ds_read_b128 v[170:173], v167 offset:32768
	ds_read_b128 v[174:177], v167 offset:33792
	ds_read_b128 v[178:181], v167 offset:34816
	ds_read_b128 v[182:185], v167 offset:35840
	ds_read_b128 v[186:189], v167 offset:36864
	ds_read_b128 v[190:193], v167 offset:37888
	ds_read_b128 v[194:197], v167 offset:38912
	ds_read_b128 v[198:201], v167 offset:39936
	global_load_lds_dwordx4 v[202:203], off
	v_lshl_add_u64 v[202:203], s[44:45], 0, v[130:131]
	s_mov_b32 m0, s55
	s_nop 0
	global_load_lds_dwordx4 v[202:203], off
	s_waitcnt lgkmcnt(8)
	s_setprio 1
	s_barrier
	s_waitcnt lgkmcnt(0)
	v_mfma_f32_16x16x32_bf16 v[100:103], v[144:147], v[170:173], v[100:103]
	v_mfma_f32_16x16x32_bf16 v[88:91], v[152:155], v[170:173], v[88:91]
	v_mfma_f32_16x16x32_bf16 v[96:99], v[144:147], v[178:181], v[96:99]
	v_mfma_f32_16x16x32_bf16 v[80:83], v[152:155], v[178:181], v[80:83]
	v_mfma_f32_16x16x32_bf16 v[72:75], v[144:147], v[186:189], v[72:75]
	v_mfma_f32_16x16x32_bf16 v[60:63], v[152:155], v[186:189], v[60:63]
	v_mfma_f32_16x16x32_bf16 v[56:59], v[144:147], v[194:197], v[56:59]
	v_mfma_f32_16x16x32_bf16 v[48:51], v[152:155], v[194:197], v[48:51]
	v_mfma_f32_16x16x32_bf16 v[100:103], v[148:151], v[174:177], v[100:103]
	v_mfma_f32_16x16x32_bf16 v[88:91], v[156:159], v[174:177], v[88:91]
	v_mfma_f32_16x16x32_bf16 v[96:99], v[148:151], v[182:185], v[96:99]
	v_mfma_f32_16x16x32_bf16 v[80:83], v[156:159], v[182:185], v[80:83]
	v_mfma_f32_16x16x32_bf16 v[72:75], v[148:151], v[190:193], v[72:75]
	v_mfma_f32_16x16x32_bf16 v[60:63], v[156:159], v[190:193], v[60:63]
	v_mfma_f32_16x16x32_bf16 v[56:59], v[148:151], v[198:201], v[56:59]
	v_mfma_f32_16x16x32_bf16 v[48:51], v[156:159], v[198:201], v[48:51]
	s_barrier
	s_setprio 0
	s_add_i32 s48, 0, 0x1c000
	s_add_i32 s44, s69, s52
	v_add_u32_e32 v169, s48, v163
	v_lshl_add_u64 v[160:161], v[160:161], 0, s[20:21]
	s_mov_b32 m0, s44
	ds_read_b128 v[202:205], v169
	ds_read_b128 v[206:209], v169 offset:1024
	ds_read_b128 v[210:213], v169 offset:2048
	ds_read_b128 v[214:217], v169 offset:3072
	global_load_lds_dwordx4 v[160:161], off
	v_lshl_add_u64 v[160:161], v[218:219], 0, s[20:21]
	s_add_i32 m0, s44, 0x2000
	s_nop 0
	global_load_lds_dwordx4 v[160:161], off
	s_waitcnt lgkmcnt(0)
	s_setprio 1
	s_barrier
	v_mfma_f32_16x16x32_bf16 v[92:95], v[202:205], v[170:173], v[92:95]
	v_mfma_f32_16x16x32_bf16 v[108:111], v[210:213], v[170:173], v[108:111]
	v_mfma_f32_16x16x32_bf16 v[84:87], v[202:205], v[178:181], v[84:87]
	v_mfma_f32_16x16x32_bf16 v[104:107], v[210:213], v[178:181], v[104:107]
	v_mfma_f32_16x16x32_bf16 v[64:67], v[202:205], v[186:189], v[64:67]
	v_mfma_f32_16x16x32_bf16 v[76:79], v[210:213], v[186:189], v[76:79]
	v_mfma_f32_16x16x32_bf16 v[52:55], v[202:205], v[194:197], v[52:55]
	v_mfma_f32_16x16x32_bf16 v[68:71], v[210:213], v[194:197], v[68:71]
	v_mfma_f32_16x16x32_bf16 v[92:95], v[206:209], v[174:177], v[92:95]
	v_mfma_f32_16x16x32_bf16 v[108:111], v[214:217], v[174:177], v[108:111]
	v_mfma_f32_16x16x32_bf16 v[84:87], v[206:209], v[182:185], v[84:87]
	v_mfma_f32_16x16x32_bf16 v[104:107], v[214:217], v[182:185], v[104:107]
	v_mfma_f32_16x16x32_bf16 v[64:67], v[206:209], v[190:193], v[64:67]
	v_mfma_f32_16x16x32_bf16 v[76:79], v[214:217], v[190:193], v[76:79]
	v_mfma_f32_16x16x32_bf16 v[52:55], v[206:209], v[198:201], v[52:55]
	v_mfma_f32_16x16x32_bf16 v[68:71], v[214:217], v[198:201], v[68:71]
	s_mov_b32 m0, s57
	v_lshl_add_u64 v[160:161], v[220:221], 0, s[20:21]
	s_barrier
	s_setprio 0
	ds_read_b128 v[170:173], v167 offset:49152
	ds_read_b128 v[174:177], v167 offset:50176
	ds_read_b128 v[178:181], v167 offset:51200
	ds_read_b128 v[182:185], v167 offset:52224
	ds_read_b128 v[186:189], v167 offset:53248
	ds_read_b128 v[190:193], v167 offset:54272
	ds_read_b128 v[194:197], v167 offset:55296
	ds_read_b128 v[198:201], v167 offset:56320
	global_load_lds_dwordx4 v[160:161], off
	v_lshl_add_u64 v[160:161], v[224:225], 0, s[20:21]
	s_mov_b32 m0, s58
	s_nop 0
	global_load_lds_dwordx4 v[160:161], off
	s_waitcnt lgkmcnt(0)
	s_setprio 1
	s_barrier
	v_mfma_f32_16x16x32_bf16 v[40:43], v[144:147], v[170:173], v[40:43]
	v_mfma_f32_16x16x32_bf16 v[32:35], v[152:155], v[170:173], v[32:35]
	v_mfma_f32_16x16x32_bf16 v[24:27], v[144:147], v[178:181], v[24:27]
	v_mfma_f32_16x16x32_bf16 v[20:23], v[152:155], v[178:181], v[20:23]
	v_mfma_f32_16x16x32_bf16 v[4:7], v[144:147], v[186:189], v[4:7]
	v_mfma_f32_16x16x32_bf16 v[124:127], v[152:155], v[186:189], v[124:127]
	v_mfma_f32_16x16x32_bf16 v[0:3], v[144:147], v[194:197], v[0:3]
	v_mfma_f32_16x16x32_bf16 v[116:119], v[152:155], v[194:197], v[116:119]
	v_mfma_f32_16x16x32_bf16 v[40:43], v[148:151], v[174:177], v[40:43]
	v_mfma_f32_16x16x32_bf16 v[32:35], v[156:159], v[174:177], v[32:35]
	v_mfma_f32_16x16x32_bf16 v[24:27], v[148:151], v[182:185], v[24:27]
	v_mfma_f32_16x16x32_bf16 v[20:23], v[156:159], v[182:185], v[20:23]
	v_mfma_f32_16x16x32_bf16 v[4:7], v[148:151], v[190:193], v[4:7]
	v_mfma_f32_16x16x32_bf16 v[124:127], v[156:159], v[190:193], v[124:127]
	v_mfma_f32_16x16x32_bf16 v[0:3], v[148:151], v[198:201], v[0:3]
	v_mfma_f32_16x16x32_bf16 v[116:119], v[156:159], v[198:201], v[116:119]
	s_barrier
	s_setprio 0
	s_add_u32 s44, s46, 0x40080
	s_addc_u32 s45, s47, 0
	s_add_i32 s46, s48, s52
	v_lshl_add_u64 v[144:145], s[44:45], 0, v[132:133]
	s_mov_b32 m0, s46
	s_nop 0
	global_load_lds_dwordx4 v[144:145], off
	v_lshl_add_u64 v[144:145], s[44:45], 0, v[128:129]
	s_add_i32 m0, s46, 0x2000
	s_nop 0
	global_load_lds_dwordx4 v[144:145], off
	s_waitcnt vmcnt(6)
	s_setprio 1
	s_barrier
	v_mfma_f32_16x16x32_bf16 v[28:31], v[202:205], v[170:173], v[28:31]
	v_mfma_f32_16x16x32_bf16 v[44:47], v[210:213], v[170:173], v[44:47]
	v_mfma_f32_16x16x32_bf16 v[16:19], v[202:205], v[178:181], v[16:19]
	v_mfma_f32_16x16x32_bf16 v[36:39], v[210:213], v[178:181], v[36:39]
	v_mfma_f32_16x16x32_bf16 v[120:123], v[202:205], v[186:189], v[120:123]
	v_mfma_f32_16x16x32_bf16 v[12:15], v[210:213], v[186:189], v[12:15]
	v_mfma_f32_16x16x32_bf16 v[112:115], v[202:205], v[194:197], v[112:115]
	v_mfma_f32_16x16x32_bf16 v[8:11], v[210:213], v[194:197], v[8:11]
	v_mfma_f32_16x16x32_bf16 v[28:31], v[206:209], v[174:177], v[28:31]
	v_mfma_f32_16x16x32_bf16 v[44:47], v[214:217], v[174:177], v[44:47]
	v_mfma_f32_16x16x32_bf16 v[16:19], v[206:209], v[182:185], v[16:19]
	v_mfma_f32_16x16x32_bf16 v[36:39], v[214:217], v[182:185], v[36:39]
	v_mfma_f32_16x16x32_bf16 v[120:123], v[206:209], v[190:193], v[120:123]
	v_mfma_f32_16x16x32_bf16 v[12:15], v[214:217], v[190:193], v[12:15]
	v_mfma_f32_16x16x32_bf16 v[112:115], v[206:209], v[198:201], v[112:115]
	v_mfma_f32_16x16x32_bf16 v[8:11], v[214:217], v[198:201], v[8:11]
	s_add_u32 s66, s66, 0x100
	s_addc_u32 s67, s67, 0
	s_cmp_lt_i32 s68, s56
	s_mov_b64 s[44:45], s[6:7]
	s_mov_b32 s46, s68
	s_barrier
	s_setprio 0
	s_cbranch_scc0 .Lpeel_done_P2b
.LBB0_312:
	ds_read_b128 v[144:147], v166
	ds_read_b128 v[148:151], v166 offset:1024
	ds_read_b128 v[152:155], v166 offset:2048
	ds_read_b128 v[156:159], v166 offset:3072
	s_add_i32 s68, s46, 2
	s_add_u32 s6, s44, 0x100
	s_addc_u32 s7, s45, 0
	s_cmp_eq_u32 s60, s46
	s_cselect_b32 s46, s65, s66
	s_cselect_b32 s49, s37, s7
	s_cselect_b32 s48, s39, s6
	s_cselect_b32 s47, s51, s67
	v_lshl_add_u64 v[160:161], s[44:45], 0, v[136:137]
	s_add_i32 m0, s35, 0xc000
	ds_read_b128 v[170:173], v167
	ds_read_b128 v[174:177], v167 offset:1024
	ds_read_b128 v[178:181], v167 offset:2048
	ds_read_b128 v[182:185], v167 offset:3072
	ds_read_b128 v[186:189], v167 offset:4096
	ds_read_b128 v[190:193], v167 offset:5120
	ds_read_b128 v[194:197], v167 offset:6144
	ds_read_b128 v[198:201], v167 offset:7168
	global_load_lds_dwordx4 v[160:161], off
	v_lshl_add_u64 v[160:161], s[44:45], 0, v[138:139]
	s_add_i32 m0, s35, 0xe000
	s_nop 0
	global_load_lds_dwordx4 v[160:161], off
	s_waitcnt lgkmcnt(8)
	s_setprio 1
	s_barrier
	s_waitcnt lgkmcnt(0)
	v_mfma_f32_16x16x32_bf16 v[100:103], v[144:147], v[170:173], v[100:103]
	v_mfma_f32_16x16x32_bf16 v[88:91], v[152:155], v[170:173], v[88:91]
	v_mfma_f32_16x16x32_bf16 v[96:99], v[144:147], v[178:181], v[96:99]
	v_mfma_f32_16x16x32_bf16 v[80:83], v[152:155], v[178:181], v[80:83]
	v_mfma_f32_16x16x32_bf16 v[72:75], v[144:147], v[186:189], v[72:75]
	v_mfma_f32_16x16x32_bf16 v[60:63], v[152:155], v[186:189], v[60:63]
	v_mfma_f32_16x16x32_bf16 v[56:59], v[144:147], v[194:197], v[56:59]
	v_mfma_f32_16x16x32_bf16 v[48:51], v[152:155], v[194:197], v[48:51]
	v_mfma_f32_16x16x32_bf16 v[100:103], v[148:151], v[174:177], v[100:103]
	v_mfma_f32_16x16x32_bf16 v[88:91], v[156:159], v[174:177], v[88:91]
	v_mfma_f32_16x16x32_bf16 v[96:99], v[148:151], v[182:185], v[96:99]
	v_mfma_f32_16x16x32_bf16 v[80:83], v[156:159], v[182:185], v[80:83]
	v_mfma_f32_16x16x32_bf16 v[72:75], v[148:151], v[190:193], v[72:75]
	v_mfma_f32_16x16x32_bf16 v[60:63], v[156:159], v[190:193], v[60:63]
	v_mfma_f32_16x16x32_bf16 v[56:59], v[148:151], v[198:201], v[56:59]
	v_mfma_f32_16x16x32_bf16 v[48:51], v[156:159], v[198:201], v[48:51]
	s_barrier
	s_setprio 0
	s_add_i32 s44, s62, s52
	v_lshl_add_u64 v[160:161], s[46:47], 0, v[132:133]
	s_mov_b32 m0, s44
	ds_read_b128 v[202:205], v168
	ds_read_b128 v[206:209], v168 offset:1024
	ds_read_b128 v[210:213], v168 offset:2048
	ds_read_b128 v[214:217], v168 offset:3072
	global_load_lds_dwordx4 v[160:161], off
	v_lshl_add_u64 v[218:219], s[46:47], 0, v[128:129]
	s_add_i32 m0, s44, 0x2000
	s_nop 0
	global_load_lds_dwordx4 v[218:219], off
	s_waitcnt lgkmcnt(0)
	s_setprio 1
	s_barrier
	v_mfma_f32_16x16x32_bf16 v[92:95], v[202:205], v[170:173], v[92:95]
	v_mfma_f32_16x16x32_bf16 v[108:111], v[210:213], v[170:173], v[108:111]
	v_mfma_f32_16x16x32_bf16 v[84:87], v[202:205], v[178:181], v[84:87]
	v_mfma_f32_16x16x32_bf16 v[104:107], v[210:213], v[178:181], v[104:107]
	v_mfma_f32_16x16x32_bf16 v[64:67], v[202:205], v[186:189], v[64:67]
	v_mfma_f32_16x16x32_bf16 v[76:79], v[210:213], v[186:189], v[76:79]
	v_mfma_f32_16x16x32_bf16 v[52:55], v[202:205], v[194:197], v[52:55]
	v_mfma_f32_16x16x32_bf16 v[68:71], v[210:213], v[194:197], v[68:71]
	v_mfma_f32_16x16x32_bf16 v[92:95], v[206:209], v[174:177], v[92:95]
	v_mfma_f32_16x16x32_bf16 v[108:111], v[214:217], v[174:177], v[108:111]
	v_mfma_f32_16x16x32_bf16 v[84:87], v[206:209], v[182:185], v[84:87]
	v_mfma_f32_16x16x32_bf16 v[104:107], v[214:217], v[182:185], v[104:107]
	v_mfma_f32_16x16x32_bf16 v[64:67], v[206:209], v[190:193], v[64:67]
	v_mfma_f32_16x16x32_bf16 v[76:79], v[214:217], v[190:193], v[76:79]
	v_mfma_f32_16x16x32_bf16 v[52:55], v[206:209], v[198:201], v[52:55]
	v_mfma_f32_16x16x32_bf16 v[68:71], v[214:217], v[198:201], v[68:71]
	s_mov_b32 m0, s35
	v_lshl_add_u64 v[220:221], s[48:49], 0, v[134:135]
	s_barrier
	s_setprio 0
	ds_read_b128 v[170:173], v167 offset:16384
	ds_read_b128 v[174:177], v167 offset:17408
	ds_read_b128 v[178:181], v167 offset:18432
	ds_read_b128 v[182:185], v167 offset:19456
	ds_read_b128 v[186:189], v167 offset:20480
	ds_read_b128 v[190:193], v167 offset:21504
	ds_read_b128 v[194:197], v167 offset:22528
	ds_read_b128 v[198:201], v167 offset:23552
	global_load_lds_dwordx4 v[220:221], off
	v_lshl_add_u64 v[224:225], s[48:49], 0, v[130:131]
	s_mov_b32 m0, s53
	s_nop 0
	global_load_lds_dwordx4 v[224:225], off
	s_waitcnt lgkmcnt(0)
	s_setprio 1
	s_barrier
	v_mfma_f32_16x16x32_bf16 v[40:43], v[144:147], v[170:173], v[40:43]
	v_mfma_f32_16x16x32_bf16 v[32:35], v[152:155], v[170:173], v[32:35]
	v_mfma_f32_16x16x32_bf16 v[24:27], v[144:147], v[178:181], v[24:27]
	v_mfma_f32_16x16x32_bf16 v[20:23], v[152:155], v[178:181], v[20:23]
	v_mfma_f32_16x16x32_bf16 v[4:7], v[144:147], v[186:189], v[4:7]
	v_mfma_f32_16x16x32_bf16 v[124:127], v[152:155], v[186:189], v[124:127]
	v_mfma_f32_16x16x32_bf16 v[0:3], v[144:147], v[194:197], v[0:3]
	v_mfma_f32_16x16x32_bf16 v[116:119], v[152:155], v[194:197], v[116:119]
	v_mfma_f32_16x16x32_bf16 v[40:43], v[148:151], v[174:177], v[40:43]
	v_mfma_f32_16x16x32_bf16 v[32:35], v[156:159], v[174:177], v[32:35]
	v_mfma_f32_16x16x32_bf16 v[24:27], v[148:151], v[182:185], v[24:27]
	v_mfma_f32_16x16x32_bf16 v[20:23], v[156:159], v[182:185], v[20:23]
	v_mfma_f32_16x16x32_bf16 v[4:7], v[148:151], v[190:193], v[4:7]
	v_mfma_f32_16x16x32_bf16 v[124:127], v[156:159], v[190:193], v[124:127]
	v_mfma_f32_16x16x32_bf16 v[0:3], v[148:151], v[198:201], v[0:3]
	v_mfma_f32_16x16x32_bf16 v[116:119], v[156:159], v[198:201], v[116:119]
	s_barrier
	s_setprio 0
	s_add_u32 s44, s46, 0x40000
	s_addc_u32 s45, s47, 0
	s_add_i32 s69, s64, s52
	v_lshl_add_u64 v[144:145], s[44:45], 0, v[132:133]
	s_mov_b32 m0, s69
	s_nop 0
	global_load_lds_dwordx4 v[144:145], off
	v_lshl_add_u64 v[144:145], s[44:45], 0, v[128:129]
	s_add_i32 m0, s69, 0x2000
	s_nop 0
	global_load_lds_dwordx4 v[144:145], off
	s_waitcnt vmcnt(6)
	s_setprio 1
	s_barrier
	v_mfma_f32_16x16x32_bf16 v[28:31], v[202:205], v[170:173], v[28:31]
	v_mfma_f32_16x16x32_bf16 v[44:47], v[210:213], v[170:173], v[44:47]
	v_mfma_f32_16x16x32_bf16 v[16:19], v[202:205], v[178:181], v[16:19]
	v_mfma_f32_16x16x32_bf16 v[36:39], v[210:213], v[178:181], v[36:39]
	v_mfma_f32_16x16x32_bf16 v[120:123], v[202:205], v[186:189], v[120:123]
	v_mfma_f32_16x16x32_bf16 v[12:15], v[210:213], v[186:189], v[12:15]
	v_mfma_f32_16x16x32_bf16 v[112:115], v[202:205], v[194:197], v[112:115]
	v_mfma_f32_16x16x32_bf16 v[8:11], v[210:213], v[194:197], v[8:11]
	v_mfma_f32_16x16x32_bf16 v[28:31], v[206:209], v[174:177], v[28:31]
	v_mfma_f32_16x16x32_bf16 v[44:47], v[214:217], v[174:177], v[44:47]
	v_mfma_f32_16x16x32_bf16 v[16:19], v[206:209], v[182:185], v[16:19]
	v_mfma_f32_16x16x32_bf16 v[36:39], v[214:217], v[182:185], v[36:39]
	v_mfma_f32_16x16x32_bf16 v[120:123], v[206:209], v[190:193], v[120:123]
	v_mfma_f32_16x16x32_bf16 v[12:15], v[214:217], v[190:193], v[12:15]
	v_mfma_f32_16x16x32_bf16 v[112:115], v[206:209], v[198:201], v[112:115]
	v_mfma_f32_16x16x32_bf16 v[8:11], v[214:217], v[198:201], v[8:11]
	s_add_i32 s69, 0, 0x18000
	v_add_u32_e32 v156, s69, v163
	s_barrier
	s_setprio 0
	ds_read_b128 v[144:147], v156
	ds_read_b128 v[148:151], v156 offset:1024
	ds_read_b128 v[152:155], v156 offset:2048
	ds_read_b128 v[156:159], v156 offset:3072
	s_add_u32 s44, s48, 0x2000
	s_addc_u32 s45, s49, 0
	s_mov_b32 m0, s54
	v_lshl_add_u64 v[202:203], s[44:45], 0, v[134:135]
	ds_read_b128 v[170:173], v167 offset:32768
	ds_read_b128 v[174:177], v167 offset:33792
	ds_read_b128 v[178:181], v167 offset:34816
	ds_read_b128 v[182:185], v167 offset:35840
	ds_read_b128 v[186:189], v167 offset:36864
	ds_read_b128 v[190:193], v167 offset:37888
	ds_read_b128 v[194:197], v167 offset:38912
	ds_read_b128 v[198:201], v167 offset:39936
	global_load_lds_dwordx4 v[202:203], off
	v_lshl_add_u64 v[202:203], s[44:45], 0, v[130:131]
	s_mov_b32 m0, s55
	s_nop 0
	global_load_lds_dwordx4 v[202:203], off
	s_waitcnt lgkmcnt(8)
	s_setprio 1
	s_barrier
	s_waitcnt lgkmcnt(0)
	v_mfma_f32_16x16x32_bf16 v[100:103], v[144:147], v[170:173], v[100:103]
	v_mfma_f32_16x16x32_bf16 v[88:91], v[152:155], v[170:173], v[88:91]
	v_mfma_f32_16x16x32_bf16 v[96:99], v[144:147], v[178:181], v[96:99]
	v_mfma_f32_16x16x32_bf16 v[80:83], v[152:155], v[178:181], v[80:83]
	v_mfma_f32_16x16x32_bf16 v[72:75], v[144:147], v[186:189], v[72:75]
	v_mfma_f32_16x16x32_bf16 v[60:63], v[152:155], v[186:189], v[60:63]
	v_mfma_f32_16x16x32_bf16 v[56:59], v[144:147], v[194:197], v[56:59]
	v_mfma_f32_16x16x32_bf16 v[48:51], v[152:155], v[194:197], v[48:51]
	v_mfma_f32_16x16x32_bf16 v[100:103], v[148:151], v[174:177], v[100:103]
	v_mfma_f32_16x16x32_bf16 v[88:91], v[156:159], v[174:177], v[88:91]
	v_mfma_f32_16x16x32_bf16 v[96:99], v[148:151], v[182:185], v[96:99]
	v_mfma_f32_16x16x32_bf16 v[80:83], v[156:159], v[182:185], v[80:83]
	v_mfma_f32_16x16x32_bf16 v[72:75], v[148:151], v[190:193], v[72:75]
	v_mfma_f32_16x16x32_bf16 v[60:63], v[156:159], v[190:193], v[60:63]
	v_mfma_f32_16x16x32_bf16 v[56:59], v[148:151], v[198:201], v[56:59]
	v_mfma_f32_16x16x32_bf16 v[48:51], v[156:159], v[198:201], v[48:51]
	s_barrier
	s_setprio 0
	s_add_i32 s48, 0, 0x1c000
	s_add_i32 s44, s69, s52
	v_add_u32_e32 v169, s48, v163
	v_lshl_add_u64 v[160:161], v[160:161], 0, s[20:21]
	s_mov_b32 m0, s44
	ds_read_b128 v[202:205], v169
	ds_read_b128 v[206:209], v169 offset:1024
	ds_read_b128 v[210:213], v169 offset:2048
	ds_read_b128 v[214:217], v169 offset:3072
	global_load_lds_dwordx4 v[160:161], off
	v_lshl_add_u64 v[160:161], v[218:219], 0, s[20:21]
	s_add_i32 m0, s44, 0x2000
	s_nop 0
	global_load_lds_dwordx4 v[160:161], off
	s_waitcnt lgkmcnt(0)
	s_setprio 1
	s_barrier
	v_mfma_f32_16x16x32_bf16 v[92:95], v[202:205], v[170:173], v[92:95]
	v_mfma_f32_16x16x32_bf16 v[108:111], v[210:213], v[170:173], v[108:111]
	v_mfma_f32_16x16x32_bf16 v[84:87], v[202:205], v[178:181], v[84:87]
	v_mfma_f32_16x16x32_bf16 v[104:107], v[210:213], v[178:181], v[104:107]
	v_mfma_f32_16x16x32_bf16 v[64:67], v[202:205], v[186:189], v[64:67]
	v_mfma_f32_16x16x32_bf16 v[76:79], v[210:213], v[186:189], v[76:79]
	v_mfma_f32_16x16x32_bf16 v[52:55], v[202:205], v[194:197], v[52:55]
	v_mfma_f32_16x16x32_bf16 v[68:71], v[210:213], v[194:197], v[68:71]
	v_mfma_f32_16x16x32_bf16 v[92:95], v[206:209], v[174:177], v[92:95]
	v_mfma_f32_16x16x32_bf16 v[108:111], v[214:217], v[174:177], v[108:111]
	v_mfma_f32_16x16x32_bf16 v[84:87], v[206:209], v[182:185], v[84:87]
	v_mfma_f32_16x16x32_bf16 v[104:107], v[214:217], v[182:185], v[104:107]
	v_mfma_f32_16x16x32_bf16 v[64:67], v[206:209], v[190:193], v[64:67]
	v_mfma_f32_16x16x32_bf16 v[76:79], v[214:217], v[190:193], v[76:79]
	v_mfma_f32_16x16x32_bf16 v[52:55], v[206:209], v[198:201], v[52:55]
	v_mfma_f32_16x16x32_bf16 v[68:71], v[214:217], v[198:201], v[68:71]
	s_mov_b32 m0, s57
	v_lshl_add_u64 v[160:161], v[220:221], 0, s[20:21]
	s_barrier
	s_setprio 0
	ds_read_b128 v[170:173], v167 offset:49152
	ds_read_b128 v[174:177], v167 offset:50176
	ds_read_b128 v[178:181], v167 offset:51200
	ds_read_b128 v[182:185], v167 offset:52224
	ds_read_b128 v[186:189], v167 offset:53248
	ds_read_b128 v[190:193], v167 offset:54272
	ds_read_b128 v[194:197], v167 offset:55296
	ds_read_b128 v[198:201], v167 offset:56320
	global_load_lds_dwordx4 v[160:161], off
	v_lshl_add_u64 v[160:161], v[224:225], 0, s[20:21]
	s_mov_b32 m0, s58
	s_nop 0
	global_load_lds_dwordx4 v[160:161], off
	s_waitcnt lgkmcnt(0)
	s_setprio 1
	s_barrier
	v_mfma_f32_16x16x32_bf16 v[40:43], v[144:147], v[170:173], v[40:43]
	v_mfma_f32_16x16x32_bf16 v[32:35], v[152:155], v[170:173], v[32:35]
	v_mfma_f32_16x16x32_bf16 v[24:27], v[144:147], v[178:181], v[24:27]
	v_mfma_f32_16x16x32_bf16 v[20:23], v[152:155], v[178:181], v[20:23]
	v_mfma_f32_16x16x32_bf16 v[4:7], v[144:147], v[186:189], v[4:7]
	v_mfma_f32_16x16x32_bf16 v[124:127], v[152:155], v[186:189], v[124:127]
	v_mfma_f32_16x16x32_bf16 v[0:3], v[144:147], v[194:197], v[0:3]
	v_mfma_f32_16x16x32_bf16 v[116:119], v[152:155], v[194:197], v[116:119]
	v_mfma_f32_16x16x32_bf16 v[40:43], v[148:151], v[174:177], v[40:43]
	v_mfma_f32_16x16x32_bf16 v[32:35], v[156:159], v[174:177], v[32:35]
	v_mfma_f32_16x16x32_bf16 v[24:27], v[148:151], v[182:185], v[24:27]
	v_mfma_f32_16x16x32_bf16 v[20:23], v[156:159], v[182:185], v[20:23]
	v_mfma_f32_16x16x32_bf16 v[4:7], v[148:151], v[190:193], v[4:7]
	v_mfma_f32_16x16x32_bf16 v[124:127], v[156:159], v[190:193], v[124:127]
	v_mfma_f32_16x16x32_bf16 v[0:3], v[148:151], v[198:201], v[0:3]
	v_mfma_f32_16x16x32_bf16 v[116:119], v[156:159], v[198:201], v[116:119]
	s_barrier
	s_setprio 0
	s_add_u32 s44, s46, 0x40080
	s_addc_u32 s45, s47, 0
	s_add_i32 s46, s48, s52
	v_lshl_add_u64 v[144:145], s[44:45], 0, v[132:133]
	s_mov_b32 m0, s46
	s_nop 0
	global_load_lds_dwordx4 v[144:145], off
	v_lshl_add_u64 v[144:145], s[44:45], 0, v[128:129]
	s_add_i32 m0, s46, 0x2000
	s_nop 0
	global_load_lds_dwordx4 v[144:145], off
	s_waitcnt vmcnt(6)
	s_setprio 1
	s_barrier
	v_mfma_f32_16x16x32_bf16 v[28:31], v[202:205], v[170:173], v[28:31]
	v_mfma_f32_16x16x32_bf16 v[44:47], v[210:213], v[170:173], v[44:47]
	v_mfma_f32_16x16x32_bf16 v[16:19], v[202:205], v[178:181], v[16:19]
	v_mfma_f32_16x16x32_bf16 v[36:39], v[210:213], v[178:181], v[36:39]
	v_mfma_f32_16x16x32_bf16 v[120:123], v[202:205], v[186:189], v[120:123]
	v_mfma_f32_16x16x32_bf16 v[12:15], v[210:213], v[186:189], v[12:15]
	v_mfma_f32_16x16x32_bf16 v[112:115], v[202:205], v[194:197], v[112:115]
	v_mfma_f32_16x16x32_bf16 v[8:11], v[210:213], v[194:197], v[8:11]
	v_mfma_f32_16x16x32_bf16 v[28:31], v[206:209], v[174:177], v[28:31]
	v_mfma_f32_16x16x32_bf16 v[44:47], v[214:217], v[174:177], v[44:47]
	v_mfma_f32_16x16x32_bf16 v[16:19], v[206:209], v[182:185], v[16:19]
	v_mfma_f32_16x16x32_bf16 v[36:39], v[214:217], v[182:185], v[36:39]
	v_mfma_f32_16x16x32_bf16 v[120:123], v[206:209], v[190:193], v[120:123]
	v_mfma_f32_16x16x32_bf16 v[12:15], v[214:217], v[190:193], v[12:15]
	v_mfma_f32_16x16x32_bf16 v[112:115], v[206:209], v[198:201], v[112:115]
	v_mfma_f32_16x16x32_bf16 v[8:11], v[214:217], v[198:201], v[8:11]
	s_add_u32 s66, s66, 0x100
	s_addc_u32 s67, s67, 0
	s_cmp_lt_i32 s68, s56
	s_mov_b64 s[44:45], s[6:7]
	s_mov_b32 s46, s68
	s_barrier
	s_setprio 0
	s_cbranch_scc1 .LBB0_312

.Lzskip_P2g:
	s_and_b64 s[6:7], s[6:7], exec
	s_cselect_b32 s45, s49, s57
	s_cselect_b32 s47, s48, s56
	s_cselect_b32 s71, s51, s55
	s_cselect_b32 s72, s50, s54
	s_add_u32 s6, s56, 0x20080
	s_addc_u32 s7, s57, 0
	s_add_u32 s73, s54, 0x100
	s_addc_u32 s74, s55, 0
	s_mov_b32 s54, 0
	v_add_u32_e32 v154, s64, v195
	ds_read_b128 v[142:145], v154
	ds_read_b128 v[146:149], v154 offset:1024
	ds_read_b128 v[150:153], v154 offset:2048
	ds_read_b128 v[154:157], v154 offset:3072
	s_add_i32 s75, s54, 2
	s_add_u32 s55, s6, 0xfffe0080
	s_addc_u32 s56, s7, -1
	s_cmp_eq_u32 s63, s54
	s_cselect_b32 s54, s72, s73
	s_cselect_b32 s57, s45, s56
	s_cselect_b32 s56, s47, s55
	s_cselect_b32 s55, s71, s74
	v_lshl_add_u64 v[190:191], s[6:7], 0, v[134:135]
	s_add_i32 m0, s19, 0xc000
	ds_read_b128 v[158:161], v201
	ds_read_b128 v[162:165], v201 offset:1024
	ds_read_b128 v[166:169], v201 offset:2048
	ds_read_b128 v[170:173], v201 offset:3072
	ds_read_b128 v[174:177], v201 offset:4096
	ds_read_b128 v[178:181], v201 offset:5120
	ds_read_b128 v[182:185], v201 offset:6144
	ds_read_b128 v[186:189], v201 offset:7168
	global_load_lds_dwordx4 v[190:191], off
	v_lshl_add_u64 v[190:191], s[6:7], 0, v[136:137]
	s_add_i32 m0, s19, 0xe000
	s_nop 0
	global_load_lds_dwordx4 v[190:191], off
	s_waitcnt lgkmcnt(8)
	s_setprio 1
	s_barrier
	s_waitcnt lgkmcnt(0)
	v_mfma_i32_16x16x64_i8 v[124:127], v[142:145], v[158:161], 0
	v_mfma_i32_16x16x64_i8 v[120:123], v[150:153], v[158:161], 0
	v_mfma_i32_16x16x64_i8 v[116:119], v[142:145], v[166:169], 0
	v_mfma_i32_16x16x64_i8 v[112:115], v[150:153], v[166:169], 0
	v_mfma_i32_16x16x64_i8 v[108:111], v[142:145], v[174:177], 0
	v_mfma_i32_16x16x64_i8 v[104:107], v[150:153], v[174:177], 0
	v_mfma_i32_16x16x64_i8 v[100:103], v[142:145], v[182:185], 0
	v_mfma_i32_16x16x64_i8 v[96:99], v[150:153], v[182:185], 0
	v_mfma_i32_16x16x64_i8 v[124:127], v[146:149], v[162:165], v[124:127]
	v_mfma_i32_16x16x64_i8 v[120:123], v[154:157], v[162:165], v[120:123]
	v_mfma_i32_16x16x64_i8 v[116:119], v[146:149], v[170:173], v[116:119]
	v_mfma_i32_16x16x64_i8 v[112:115], v[154:157], v[170:173], v[112:115]
	v_mfma_i32_16x16x64_i8 v[108:111], v[146:149], v[178:181], v[108:111]
	v_mfma_i32_16x16x64_i8 v[104:107], v[154:157], v[178:181], v[104:107]
	v_mfma_i32_16x16x64_i8 v[100:103], v[146:149], v[186:189], v[100:103]
	v_mfma_i32_16x16x64_i8 v[96:99], v[154:157], v[186:189], v[96:99]
	s_barrier
	s_setprio 0
	v_add_u32_e32 v190, s65, v195
	s_add_i32 s76, s64, s18
	ds_read_b128 v[204:207], v190
	ds_read_b128 v[208:211], v190 offset:1024
	ds_read_b128 v[212:215], v190 offset:2048
	ds_read_b128 v[216:219], v190 offset:3072
	v_lshl_add_u64 v[190:191], s[54:55], 0, v[130:131]
	s_mov_b32 m0, s76
	v_lshl_add_u64 v[220:221], s[54:55], 0, v[128:129]
	global_load_lds_dwordx4 v[190:191], off
	s_add_i32 m0, s76, 0x2000
	s_nop 0
	global_load_lds_dwordx4 v[220:221], off
	s_waitcnt lgkmcnt(0)
	s_setprio 1
	s_barrier
	v_mfma_i32_16x16x64_i8 v[92:95], v[204:207], v[158:161], 0
	v_mfma_i32_16x16x64_i8 v[88:91], v[212:215], v[158:161], 0
	v_mfma_i32_16x16x64_i8 v[84:87], v[204:207], v[166:169], 0
	v_mfma_i32_16x16x64_i8 v[80:83], v[212:215], v[166:169], 0
	v_mfma_i32_16x16x64_i8 v[76:79], v[204:207], v[174:177], 0
	v_mfma_i32_16x16x64_i8 v[72:75], v[212:215], v[174:177], 0
	v_mfma_i32_16x16x64_i8 v[68:71], v[204:207], v[182:185], 0
	v_mfma_i32_16x16x64_i8 v[64:67], v[212:215], v[182:185], 0
	v_mfma_i32_16x16x64_i8 v[92:95], v[208:211], v[162:165], v[92:95]
	v_mfma_i32_16x16x64_i8 v[88:91], v[216:219], v[162:165], v[88:91]
	v_mfma_i32_16x16x64_i8 v[84:87], v[208:211], v[170:173], v[84:87]
	v_mfma_i32_16x16x64_i8 v[80:83], v[216:219], v[170:173], v[80:83]
	v_mfma_i32_16x16x64_i8 v[76:79], v[208:211], v[178:181], v[76:79]
	v_mfma_i32_16x16x64_i8 v[72:75], v[216:219], v[178:181], v[72:75]
	v_mfma_i32_16x16x64_i8 v[68:71], v[208:211], v[186:189], v[68:71]
	v_mfma_i32_16x16x64_i8 v[64:67], v[216:219], v[186:189], v[64:67]
	s_mov_b32 m0, s19
	v_lshl_add_u64 v[224:225], s[56:57], 0, v[130:131]
	s_barrier
	s_setprio 0
	ds_read_b128 v[158:161], v201 offset:16384
	ds_read_b128 v[162:165], v201 offset:17408
	ds_read_b128 v[166:169], v201 offset:18432
	ds_read_b128 v[170:173], v201 offset:19456
	ds_read_b128 v[174:177], v201 offset:20480
	ds_read_b128 v[178:181], v201 offset:21504
	ds_read_b128 v[182:185], v201 offset:22528
	ds_read_b128 v[186:189], v201 offset:23552
	global_load_lds_dwordx4 v[224:225], off
	v_lshl_add_u64 v[228:229], s[56:57], 0, v[128:129]
	s_mov_b32 m0, s53
	s_nop 0
	global_load_lds_dwordx4 v[228:229], off
	s_waitcnt lgkmcnt(0)
	s_setprio 1
	s_barrier
	v_mfma_i32_16x16x64_i8 v[60:63], v[142:145], v[158:161], 0
	v_mfma_i32_16x16x64_i8 v[56:59], v[150:153], v[158:161], 0
	v_mfma_i32_16x16x64_i8 v[52:55], v[142:145], v[166:169], 0
	v_mfma_i32_16x16x64_i8 v[48:51], v[150:153], v[166:169], 0
	v_mfma_i32_16x16x64_i8 v[44:47], v[142:145], v[174:177], 0
	v_mfma_i32_16x16x64_i8 v[40:43], v[150:153], v[174:177], 0
	v_mfma_i32_16x16x64_i8 v[36:39], v[142:145], v[182:185], 0
	v_mfma_i32_16x16x64_i8 v[32:35], v[150:153], v[182:185], 0
	v_mfma_i32_16x16x64_i8 v[60:63], v[146:149], v[162:165], v[60:63]
	v_mfma_i32_16x16x64_i8 v[56:59], v[154:157], v[162:165], v[56:59]
	v_mfma_i32_16x16x64_i8 v[52:55], v[146:149], v[170:173], v[52:55]
	v_mfma_i32_16x16x64_i8 v[48:51], v[154:157], v[170:173], v[48:51]
	v_mfma_i32_16x16x64_i8 v[44:47], v[146:149], v[178:181], v[44:47]
	v_mfma_i32_16x16x64_i8 v[40:43], v[154:157], v[178:181], v[40:43]
	v_mfma_i32_16x16x64_i8 v[36:39], v[146:149], v[186:189], v[36:39]
	v_mfma_i32_16x16x64_i8 v[32:35], v[154:157], v[186:189], v[32:35]
	s_barrier
	s_setprio 0
	s_add_u32 s76, s54, 0x20000
	s_addc_u32 s77, s55, 0
	s_add_i32 s78, s65, s18
	v_lshl_add_u64 v[142:143], s[76:77], 0, v[130:131]
	s_mov_b32 m0, s78
	s_nop 0
	global_load_lds_dwordx4 v[142:143], off
	v_lshl_add_u64 v[142:143], s[76:77], 0, v[128:129]
	s_add_i32 m0, s78, 0x2000
	s_nop 0
	global_load_lds_dwordx4 v[142:143], off
	s_waitcnt vmcnt(6)
	s_setprio 1
	s_barrier
	v_mfma_i32_16x16x64_i8 v[28:31], v[204:207], v[158:161], 0
	v_mfma_i32_16x16x64_i8 v[24:27], v[212:215], v[158:161], 0
	v_mfma_i32_16x16x64_i8 v[20:23], v[204:207], v[166:169], 0
	v_mfma_i32_16x16x64_i8 v[16:19], v[212:215], v[166:169], 0
	v_mfma_i32_16x16x64_i8 v[12:15], v[204:207], v[174:177], 0
	v_mfma_i32_16x16x64_i8 v[8:11], v[212:215], v[174:177], 0
	v_mfma_i32_16x16x64_i8 v[4:7], v[204:207], v[182:185], 0
	v_mfma_i32_16x16x64_i8 v[0:3], v[212:215], v[182:185], 0
	v_mfma_i32_16x16x64_i8 v[28:31], v[208:211], v[162:165], v[28:31]
	v_mfma_i32_16x16x64_i8 v[24:27], v[216:219], v[162:165], v[24:27]
	v_mfma_i32_16x16x64_i8 v[20:23], v[208:211], v[170:173], v[20:23]
	v_mfma_i32_16x16x64_i8 v[16:19], v[216:219], v[170:173], v[16:19]
	v_mfma_i32_16x16x64_i8 v[12:15], v[208:211], v[178:181], v[12:15]
	v_mfma_i32_16x16x64_i8 v[8:11], v[216:219], v[178:181], v[8:11]
	v_mfma_i32_16x16x64_i8 v[4:7], v[208:211], v[186:189], v[4:7]
	v_mfma_i32_16x16x64_i8 v[0:3], v[216:219], v[186:189], v[0:3]
	s_add_i32 s76, 0, 0x18000
	v_add_u32_e32 v154, s76, v195
	s_barrier
	s_setprio 0
	ds_read_b128 v[142:145], v154
	ds_read_b128 v[146:149], v154 offset:1024
	ds_read_b128 v[150:153], v154 offset:2048
	ds_read_b128 v[154:157], v154 offset:3072
	s_add_u32 s56, s56, 0x20000
	s_addc_u32 s57, s57, 0
	s_mov_b32 m0, s58
	v_lshl_add_u64 v[204:205], s[56:57], 0, v[130:131]
	ds_read_b128 v[158:161], v201 offset:32768
	ds_read_b128 v[162:165], v201 offset:33792
	ds_read_b128 v[166:169], v201 offset:34816
	ds_read_b128 v[170:173], v201 offset:35840
	ds_read_b128 v[174:177], v201 offset:36864
	ds_read_b128 v[178:181], v201 offset:37888
	ds_read_b128 v[182:185], v201 offset:38912
	ds_read_b128 v[186:189], v201 offset:39936
	global_load_lds_dwordx4 v[204:205], off
	v_lshl_add_u64 v[204:205], s[56:57], 0, v[128:129]
	s_mov_b32 m0, s59
	s_nop 0
	global_load_lds_dwordx4 v[204:205], off
	s_waitcnt lgkmcnt(8)
	s_setprio 1
	s_barrier
	s_waitcnt lgkmcnt(0)
	v_mfma_i32_16x16x64_i8 v[124:127], v[142:145], v[158:161], v[124:127]
	v_mfma_i32_16x16x64_i8 v[120:123], v[150:153], v[158:161], v[120:123]
	v_mfma_i32_16x16x64_i8 v[116:119], v[142:145], v[166:169], v[116:119]
	v_mfma_i32_16x16x64_i8 v[112:115], v[150:153], v[166:169], v[112:115]
	v_mfma_i32_16x16x64_i8 v[108:111], v[142:145], v[174:177], v[108:111]
	v_mfma_i32_16x16x64_i8 v[104:107], v[150:153], v[174:177], v[104:107]
	v_mfma_i32_16x16x64_i8 v[100:103], v[142:145], v[182:185], v[100:103]
	v_mfma_i32_16x16x64_i8 v[96:99], v[150:153], v[182:185], v[96:99]
	v_mfma_i32_16x16x64_i8 v[124:127], v[146:149], v[162:165], v[124:127]
	v_mfma_i32_16x16x64_i8 v[120:123], v[154:157], v[162:165], v[120:123]
	v_mfma_i32_16x16x64_i8 v[116:119], v[146:149], v[170:173], v[116:119]
	v_mfma_i32_16x16x64_i8 v[112:115], v[154:157], v[170:173], v[112:115]
	v_mfma_i32_16x16x64_i8 v[108:111], v[146:149], v[178:181], v[108:111]
	v_mfma_i32_16x16x64_i8 v[104:107], v[154:157], v[178:181], v[104:107]
	v_mfma_i32_16x16x64_i8 v[100:103], v[146:149], v[186:189], v[100:103]
	v_mfma_i32_16x16x64_i8 v[96:99], v[154:157], v[186:189], v[96:99]
	s_barrier
	s_setprio 0
	s_add_i32 s56, 0, 0x1c000
	s_add_i32 s57, s76, s18
	v_add_u32_e32 v192, s56, v195
	v_lshl_add_u64 v[190:191], v[190:191], 0, s[30:31]
	s_mov_b32 m0, s57
	ds_read_b128 v[204:207], v192
	ds_read_b128 v[208:211], v192 offset:1024
	ds_read_b128 v[212:215], v192 offset:2048
	ds_read_b128 v[216:219], v192 offset:3072
	global_load_lds_dwordx4 v[190:191], off
	v_lshl_add_u64 v[190:191], v[220:221], 0, s[30:31]
	s_add_i32 m0, s57, 0x2000
	s_nop 0
	global_load_lds_dwordx4 v[190:191], off
	s_waitcnt lgkmcnt(0)
	s_setprio 1
	s_barrier
	v_mfma_i32_16x16x64_i8 v[92:95], v[204:207], v[158:161], v[92:95]
	v_mfma_i32_16x16x64_i8 v[88:91], v[212:215], v[158:161], v[88:91]
	v_mfma_i32_16x16x64_i8 v[84:87], v[204:207], v[166:169], v[84:87]
	v_mfma_i32_16x16x64_i8 v[80:83], v[212:215], v[166:169], v[80:83]
	v_mfma_i32_16x16x64_i8 v[76:79], v[204:207], v[174:177], v[76:79]
	v_mfma_i32_16x16x64_i8 v[72:75], v[212:215], v[174:177], v[72:75]
	v_mfma_i32_16x16x64_i8 v[68:71], v[204:207], v[182:185], v[68:71]
	v_mfma_i32_16x16x64_i8 v[64:67], v[212:215], v[182:185], v[64:67]
	v_mfma_i32_16x16x64_i8 v[92:95], v[208:211], v[162:165], v[92:95]
	v_mfma_i32_16x16x64_i8 v[88:91], v[216:219], v[162:165], v[88:91]
	v_mfma_i32_16x16x64_i8 v[84:87], v[208:211], v[170:173], v[84:87]
	v_mfma_i32_16x16x64_i8 v[80:83], v[216:219], v[170:173], v[80:83]
	v_mfma_i32_16x16x64_i8 v[76:79], v[208:211], v[178:181], v[76:79]
	v_mfma_i32_16x16x64_i8 v[72:75], v[216:219], v[178:181], v[72:75]
	v_mfma_i32_16x16x64_i8 v[68:71], v[208:211], v[186:189], v[68:71]
	v_mfma_i32_16x16x64_i8 v[64:67], v[216:219], v[186:189], v[64:67]
	s_mov_b32 m0, s61
	v_lshl_add_u64 v[190:191], v[224:225], 0, s[30:31]
	s_barrier
	s_setprio 0
	ds_read_b128 v[158:161], v201 offset:49152
	ds_read_b128 v[162:165], v201 offset:50176
	ds_read_b128 v[166:169], v201 offset:51200
	ds_read_b128 v[170:173], v201 offset:52224
	ds_read_b128 v[174:177], v201 offset:53248
	ds_read_b128 v[178:181], v201 offset:54272
	ds_read_b128 v[182:185], v201 offset:55296
	ds_read_b128 v[186:189], v201 offset:56320
	global_load_lds_dwordx4 v[190:191], off
	v_lshl_add_u64 v[190:191], v[228:229], 0, s[30:31]
	s_mov_b32 m0, s62
	s_nop 0
	global_load_lds_dwordx4 v[190:191], off
	s_waitcnt lgkmcnt(0)
	s_setprio 1
	s_barrier
	v_mfma_i32_16x16x64_i8 v[60:63], v[142:145], v[158:161], v[60:63]
	v_mfma_i32_16x16x64_i8 v[56:59], v[150:153], v[158:161], v[56:59]
	v_mfma_i32_16x16x64_i8 v[52:55], v[142:145], v[166:169], v[52:55]
	v_mfma_i32_16x16x64_i8 v[48:51], v[150:153], v[166:169], v[48:51]
	v_mfma_i32_16x16x64_i8 v[44:47], v[142:145], v[174:177], v[44:47]
	v_mfma_i32_16x16x64_i8 v[40:43], v[150:153], v[174:177], v[40:43]
	v_mfma_i32_16x16x64_i8 v[36:39], v[142:145], v[182:185], v[36:39]
	v_mfma_i32_16x16x64_i8 v[32:35], v[150:153], v[182:185], v[32:35]
	v_mfma_i32_16x16x64_i8 v[60:63], v[146:149], v[162:165], v[60:63]
	v_mfma_i32_16x16x64_i8 v[56:59], v[154:157], v[162:165], v[56:59]
	v_mfma_i32_16x16x64_i8 v[52:55], v[146:149], v[170:173], v[52:55]
	v_mfma_i32_16x16x64_i8 v[48:51], v[154:157], v[170:173], v[48:51]
	v_mfma_i32_16x16x64_i8 v[44:47], v[146:149], v[178:181], v[44:47]
	v_mfma_i32_16x16x64_i8 v[40:43], v[154:157], v[178:181], v[40:43]
	v_mfma_i32_16x16x64_i8 v[36:39], v[146:149], v[186:189], v[36:39]
	v_mfma_i32_16x16x64_i8 v[32:35], v[154:157], v[186:189], v[32:35]
	s_barrier
	s_setprio 0
	s_add_u32 s54, s54, 0x20080
	s_addc_u32 s55, s55, 0
	s_add_i32 s56, s56, s18
	v_lshl_add_u64 v[142:143], s[54:55], 0, v[130:131]
	s_mov_b32 m0, s56
	s_nop 0
	global_load_lds_dwordx4 v[142:143], off
	v_lshl_add_u64 v[142:143], s[54:55], 0, v[128:129]
	s_add_i32 m0, s56, 0x2000
	s_nop 0
	global_load_lds_dwordx4 v[142:143], off
	s_waitcnt vmcnt(6)
	s_setprio 1
	s_barrier
	v_mfma_i32_16x16x64_i8 v[28:31], v[204:207], v[158:161], v[28:31]
	v_mfma_i32_16x16x64_i8 v[24:27], v[212:215], v[158:161], v[24:27]
	v_mfma_i32_16x16x64_i8 v[20:23], v[204:207], v[166:169], v[20:23]
	v_mfma_i32_16x16x64_i8 v[16:19], v[212:215], v[166:169], v[16:19]
	v_mfma_i32_16x16x64_i8 v[12:15], v[204:207], v[174:177], v[12:15]
	v_mfma_i32_16x16x64_i8 v[8:11], v[212:215], v[174:177], v[8:11]
	v_mfma_i32_16x16x64_i8 v[4:7], v[204:207], v[182:185], v[4:7]
	v_mfma_i32_16x16x64_i8 v[0:3], v[212:215], v[182:185], v[0:3]
	v_mfma_i32_16x16x64_i8 v[28:31], v[208:211], v[162:165], v[28:31]
	v_mfma_i32_16x16x64_i8 v[24:27], v[216:219], v[162:165], v[24:27]
	v_mfma_i32_16x16x64_i8 v[20:23], v[208:211], v[170:173], v[20:23]
	v_mfma_i32_16x16x64_i8 v[16:19], v[216:219], v[170:173], v[16:19]
	v_mfma_i32_16x16x64_i8 v[12:15], v[208:211], v[178:181], v[12:15]
	v_mfma_i32_16x16x64_i8 v[8:11], v[216:219], v[178:181], v[8:11]
	v_mfma_i32_16x16x64_i8 v[4:7], v[208:211], v[186:189], v[4:7]
	v_mfma_i32_16x16x64_i8 v[0:3], v[216:219], v[186:189], v[0:3]
	s_add_u32 s6, s6, 0x100
	s_addc_u32 s7, s7, 0
	s_add_u32 s73, s73, 0x100
	s_addc_u32 s74, s74, 0
	s_cmp_ge_i32 s75, s60
	s_mov_b32 s54, s75
	s_barrier
	s_setprio 0
	s_cbranch_scc1 .Lpeel_done_P2g
.LBB0_341:
	v_add_u32_e32 v154, s64, v195
	ds_read_b128 v[142:145], v154
	ds_read_b128 v[146:149], v154 offset:1024
	ds_read_b128 v[150:153], v154 offset:2048
	ds_read_b128 v[154:157], v154 offset:3072
	s_add_i32 s75, s54, 2
	s_add_u32 s55, s6, 0xfffe0080
	s_addc_u32 s56, s7, -1
	s_cmp_eq_u32 s63, s54
	s_cselect_b32 s54, s72, s73
	s_cselect_b32 s57, s45, s56
	s_cselect_b32 s56, s47, s55
	s_cselect_b32 s55, s71, s74
	v_lshl_add_u64 v[190:191], s[6:7], 0, v[134:135]
	s_add_i32 m0, s19, 0xc000
	ds_read_b128 v[158:161], v201
	ds_read_b128 v[162:165], v201 offset:1024
	ds_read_b128 v[166:169], v201 offset:2048
	ds_read_b128 v[170:173], v201 offset:3072
	ds_read_b128 v[174:177], v201 offset:4096
	ds_read_b128 v[178:181], v201 offset:5120
	ds_read_b128 v[182:185], v201 offset:6144
	ds_read_b128 v[186:189], v201 offset:7168
	global_load_lds_dwordx4 v[190:191], off
	v_lshl_add_u64 v[190:191], s[6:7], 0, v[136:137]
	s_add_i32 m0, s19, 0xe000
	s_nop 0
	global_load_lds_dwordx4 v[190:191], off
	s_waitcnt lgkmcnt(8)
	s_setprio 1
	s_barrier
	s_waitcnt lgkmcnt(0)
	v_mfma_i32_16x16x64_i8 v[124:127], v[142:145], v[158:161], v[124:127]
	v_mfma_i32_16x16x64_i8 v[120:123], v[150:153], v[158:161], v[120:123]
	v_mfma_i32_16x16x64_i8 v[116:119], v[142:145], v[166:169], v[116:119]
	v_mfma_i32_16x16x64_i8 v[112:115], v[150:153], v[166:169], v[112:115]
	v_mfma_i32_16x16x64_i8 v[108:111], v[142:145], v[174:177], v[108:111]
	v_mfma_i32_16x16x64_i8 v[104:107], v[150:153], v[174:177], v[104:107]
	v_mfma_i32_16x16x64_i8 v[100:103], v[142:145], v[182:185], v[100:103]
	v_mfma_i32_16x16x64_i8 v[96:99], v[150:153], v[182:185], v[96:99]
	v_mfma_i32_16x16x64_i8 v[124:127], v[146:149], v[162:165], v[124:127]
	v_mfma_i32_16x16x64_i8 v[120:123], v[154:157], v[162:165], v[120:123]
	v_mfma_i32_16x16x64_i8 v[116:119], v[146:149], v[170:173], v[116:119]
	v_mfma_i32_16x16x64_i8 v[112:115], v[154:157], v[170:173], v[112:115]
	v_mfma_i32_16x16x64_i8 v[108:111], v[146:149], v[178:181], v[108:111]
	v_mfma_i32_16x16x64_i8 v[104:107], v[154:157], v[178:181], v[104:107]
	v_mfma_i32_16x16x64_i8 v[100:103], v[146:149], v[186:189], v[100:103]
	v_mfma_i32_16x16x64_i8 v[96:99], v[154:157], v[186:189], v[96:99]
	s_barrier
	s_setprio 0
	v_add_u32_e32 v190, s65, v195
	s_add_i32 s76, s64, s18
	ds_read_b128 v[204:207], v190
	ds_read_b128 v[208:211], v190 offset:1024
	ds_read_b128 v[212:215], v190 offset:2048
	ds_read_b128 v[216:219], v190 offset:3072
	v_lshl_add_u64 v[190:191], s[54:55], 0, v[130:131]
	s_mov_b32 m0, s76
	v_lshl_add_u64 v[220:221], s[54:55], 0, v[128:129]
	global_load_lds_dwordx4 v[190:191], off
	s_add_i32 m0, s76, 0x2000
	s_nop 0
	global_load_lds_dwordx4 v[220:221], off
	s_waitcnt lgkmcnt(0)
	s_setprio 1
	s_barrier
	v_mfma_i32_16x16x64_i8 v[92:95], v[204:207], v[158:161], v[92:95]
	v_mfma_i32_16x16x64_i8 v[88:91], v[212:215], v[158:161], v[88:91]
	v_mfma_i32_16x16x64_i8 v[84:87], v[204:207], v[166:169], v[84:87]
	v_mfma_i32_16x16x64_i8 v[80:83], v[212:215], v[166:169], v[80:83]
	v_mfma_i32_16x16x64_i8 v[76:79], v[204:207], v[174:177], v[76:79]
	v_mfma_i32_16x16x64_i8 v[72:75], v[212:215], v[174:177], v[72:75]
	v_mfma_i32_16x16x64_i8 v[68:71], v[204:207], v[182:185], v[68:71]
	v_mfma_i32_16x16x64_i8 v[64:67], v[212:215], v[182:185], v[64:67]
	v_mfma_i32_16x16x64_i8 v[92:95], v[208:211], v[162:165], v[92:95]
	v_mfma_i32_16x16x64_i8 v[88:91], v[216:219], v[162:165], v[88:91]
	v_mfma_i32_16x16x64_i8 v[84:87], v[208:211], v[170:173], v[84:87]
	v_mfma_i32_16x16x64_i8 v[80:83], v[216:219], v[170:173], v[80:83]
	v_mfma_i32_16x16x64_i8 v[76:79], v[208:211], v[178:181], v[76:79]
	v_mfma_i32_16x16x64_i8 v[72:75], v[216:219], v[178:181], v[72:75]
	v_mfma_i32_16x16x64_i8 v[68:71], v[208:211], v[186:189], v[68:71]
	v_mfma_i32_16x16x64_i8 v[64:67], v[216:219], v[186:189], v[64:67]
	s_mov_b32 m0, s19
	v_lshl_add_u64 v[224:225], s[56:57], 0, v[130:131]
	s_barrier
	s_setprio 0
	ds_read_b128 v[158:161], v201 offset:16384
	ds_read_b128 v[162:165], v201 offset:17408
	ds_read_b128 v[166:169], v201 offset:18432
	ds_read_b128 v[170:173], v201 offset:19456
	ds_read_b128 v[174:177], v201 offset:20480
	ds_read_b128 v[178:181], v201 offset:21504
	ds_read_b128 v[182:185], v201 offset:22528
	ds_read_b128 v[186:189], v201 offset:23552
	global_load_lds_dwordx4 v[224:225], off
	v_lshl_add_u64 v[228:229], s[56:57], 0, v[128:129]
	s_mov_b32 m0, s53
	s_nop 0
	global_load_lds_dwordx4 v[228:229], off
	s_waitcnt lgkmcnt(0)
	s_setprio 1
	s_barrier
	v_mfma_i32_16x16x64_i8 v[60:63], v[142:145], v[158:161], v[60:63]
	v_mfma_i32_16x16x64_i8 v[56:59], v[150:153], v[158:161], v[56:59]
	v_mfma_i32_16x16x64_i8 v[52:55], v[142:145], v[166:169], v[52:55]
	v_mfma_i32_16x16x64_i8 v[48:51], v[150:153], v[166:169], v[48:51]
	v_mfma_i32_16x16x64_i8 v[44:47], v[142:145], v[174:177], v[44:47]
	v_mfma_i32_16x16x64_i8 v[40:43], v[150:153], v[174:177], v[40:43]
	v_mfma_i32_16x16x64_i8 v[36:39], v[142:145], v[182:185], v[36:39]
	v_mfma_i32_16x16x64_i8 v[32:35], v[150:153], v[182:185], v[32:35]
	v_mfma_i32_16x16x64_i8 v[60:63], v[146:149], v[162:165], v[60:63]
	v_mfma_i32_16x16x64_i8 v[56:59], v[154:157], v[162:165], v[56:59]
	v_mfma_i32_16x16x64_i8 v[52:55], v[146:149], v[170:173], v[52:55]
	v_mfma_i32_16x16x64_i8 v[48:51], v[154:157], v[170:173], v[48:51]
	v_mfma_i32_16x16x64_i8 v[44:47], v[146:149], v[178:181], v[44:47]
	v_mfma_i32_16x16x64_i8 v[40:43], v[154:157], v[178:181], v[40:43]
	v_mfma_i32_16x16x64_i8 v[36:39], v[146:149], v[186:189], v[36:39]
	v_mfma_i32_16x16x64_i8 v[32:35], v[154:157], v[186:189], v[32:35]
	s_barrier
	s_setprio 0
	s_add_u32 s76, s54, 0x20000
	s_addc_u32 s77, s55, 0
	s_add_i32 s78, s65, s18
	v_lshl_add_u64 v[142:143], s[76:77], 0, v[130:131]
	s_mov_b32 m0, s78
	s_nop 0
	global_load_lds_dwordx4 v[142:143], off
	v_lshl_add_u64 v[142:143], s[76:77], 0, v[128:129]
	s_add_i32 m0, s78, 0x2000
	s_nop 0
	global_load_lds_dwordx4 v[142:143], off
	s_waitcnt vmcnt(6)
	s_setprio 1
	s_barrier
	v_mfma_i32_16x16x64_i8 v[28:31], v[204:207], v[158:161], v[28:31]
	v_mfma_i32_16x16x64_i8 v[24:27], v[212:215], v[158:161], v[24:27]
	v_mfma_i32_16x16x64_i8 v[20:23], v[204:207], v[166:169], v[20:23]
	v_mfma_i32_16x16x64_i8 v[16:19], v[212:215], v[166:169], v[16:19]
	v_mfma_i32_16x16x64_i8 v[12:15], v[204:207], v[174:177], v[12:15]
	v_mfma_i32_16x16x64_i8 v[8:11], v[212:215], v[174:177], v[8:11]
	v_mfma_i32_16x16x64_i8 v[4:7], v[204:207], v[182:185], v[4:7]
	v_mfma_i32_16x16x64_i8 v[0:3], v[212:215], v[182:185], v[0:3]
	v_mfma_i32_16x16x64_i8 v[28:31], v[208:211], v[162:165], v[28:31]
	v_mfma_i32_16x16x64_i8 v[24:27], v[216:219], v[162:165], v[24:27]
	v_mfma_i32_16x16x64_i8 v[20:23], v[208:211], v[170:173], v[20:23]
	v_mfma_i32_16x16x64_i8 v[16:19], v[216:219], v[170:173], v[16:19]
	v_mfma_i32_16x16x64_i8 v[12:15], v[208:211], v[178:181], v[12:15]
	v_mfma_i32_16x16x64_i8 v[8:11], v[216:219], v[178:181], v[8:11]
	v_mfma_i32_16x16x64_i8 v[4:7], v[208:211], v[186:189], v[4:7]
	v_mfma_i32_16x16x64_i8 v[0:3], v[216:219], v[186:189], v[0:3]
	s_add_i32 s76, 0, 0x18000
	v_add_u32_e32 v154, s76, v195
	s_barrier
	s_setprio 0
	ds_read_b128 v[142:145], v154
	ds_read_b128 v[146:149], v154 offset:1024
	ds_read_b128 v[150:153], v154 offset:2048
	ds_read_b128 v[154:157], v154 offset:3072
	s_add_u32 s56, s56, 0x20000
	s_addc_u32 s57, s57, 0
	s_mov_b32 m0, s58
	v_lshl_add_u64 v[204:205], s[56:57], 0, v[130:131]
	ds_read_b128 v[158:161], v201 offset:32768
	ds_read_b128 v[162:165], v201 offset:33792
	ds_read_b128 v[166:169], v201 offset:34816
	ds_read_b128 v[170:173], v201 offset:35840
	ds_read_b128 v[174:177], v201 offset:36864
	ds_read_b128 v[178:181], v201 offset:37888
	ds_read_b128 v[182:185], v201 offset:38912
	ds_read_b128 v[186:189], v201 offset:39936
	global_load_lds_dwordx4 v[204:205], off
	v_lshl_add_u64 v[204:205], s[56:57], 0, v[128:129]
	s_mov_b32 m0, s59
	s_nop 0
	global_load_lds_dwordx4 v[204:205], off
	s_waitcnt lgkmcnt(8)
	s_setprio 1
	s_barrier
	s_waitcnt lgkmcnt(0)
	v_mfma_i32_16x16x64_i8 v[124:127], v[142:145], v[158:161], v[124:127]
	v_mfma_i32_16x16x64_i8 v[120:123], v[150:153], v[158:161], v[120:123]
	v_mfma_i32_16x16x64_i8 v[116:119], v[142:145], v[166:169], v[116:119]
	v_mfma_i32_16x16x64_i8 v[112:115], v[150:153], v[166:169], v[112:115]
	v_mfma_i32_16x16x64_i8 v[108:111], v[142:145], v[174:177], v[108:111]
	v_mfma_i32_16x16x64_i8 v[104:107], v[150:153], v[174:177], v[104:107]
	v_mfma_i32_16x16x64_i8 v[100:103], v[142:145], v[182:185], v[100:103]
	v_mfma_i32_16x16x64_i8 v[96:99], v[150:153], v[182:185], v[96:99]
	v_mfma_i32_16x16x64_i8 v[124:127], v[146:149], v[162:165], v[124:127]
	v_mfma_i32_16x16x64_i8 v[120:123], v[154:157], v[162:165], v[120:123]
	v_mfma_i32_16x16x64_i8 v[116:119], v[146:149], v[170:173], v[116:119]
	v_mfma_i32_16x16x64_i8 v[112:115], v[154:157], v[170:173], v[112:115]
	v_mfma_i32_16x16x64_i8 v[108:111], v[146:149], v[178:181], v[108:111]
	v_mfma_i32_16x16x64_i8 v[104:107], v[154:157], v[178:181], v[104:107]
	v_mfma_i32_16x16x64_i8 v[100:103], v[146:149], v[186:189], v[100:103]
	v_mfma_i32_16x16x64_i8 v[96:99], v[154:157], v[186:189], v[96:99]
	s_barrier
	s_setprio 0
	s_add_i32 s56, 0, 0x1c000
	s_add_i32 s57, s76, s18
	v_add_u32_e32 v192, s56, v195
	v_lshl_add_u64 v[190:191], v[190:191], 0, s[30:31]
	s_mov_b32 m0, s57
	ds_read_b128 v[204:207], v192
	ds_read_b128 v[208:211], v192 offset:1024
	ds_read_b128 v[212:215], v192 offset:2048
	ds_read_b128 v[216:219], v192 offset:3072
	global_load_lds_dwordx4 v[190:191], off
	v_lshl_add_u64 v[190:191], v[220:221], 0, s[30:31]
	s_add_i32 m0, s57, 0x2000
	s_nop 0
	global_load_lds_dwordx4 v[190:191], off
	s_waitcnt lgkmcnt(0)
	s_setprio 1
	s_barrier
	v_mfma_i32_16x16x64_i8 v[92:95], v[204:207], v[158:161], v[92:95]
	v_mfma_i32_16x16x64_i8 v[88:91], v[212:215], v[158:161], v[88:91]
	v_mfma_i32_16x16x64_i8 v[84:87], v[204:207], v[166:169], v[84:87]
	v_mfma_i32_16x16x64_i8 v[80:83], v[212:215], v[166:169], v[80:83]
	v_mfma_i32_16x16x64_i8 v[76:79], v[204:207], v[174:177], v[76:79]
	v_mfma_i32_16x16x64_i8 v[72:75], v[212:215], v[174:177], v[72:75]
	v_mfma_i32_16x16x64_i8 v[68:71], v[204:207], v[182:185], v[68:71]
	v_mfma_i32_16x16x64_i8 v[64:67], v[212:215], v[182:185], v[64:67]
	v_mfma_i32_16x16x64_i8 v[92:95], v[208:211], v[162:165], v[92:95]
	v_mfma_i32_16x16x64_i8 v[88:91], v[216:219], v[162:165], v[88:91]
	v_mfma_i32_16x16x64_i8 v[84:87], v[208:211], v[170:173], v[84:87]
	v_mfma_i32_16x16x64_i8 v[80:83], v[216:219], v[170:173], v[80:83]
	v_mfma_i32_16x16x64_i8 v[76:79], v[208:211], v[178:181], v[76:79]
	v_mfma_i32_16x16x64_i8 v[72:75], v[216:219], v[178:181], v[72:75]
	v_mfma_i32_16x16x64_i8 v[68:71], v[208:211], v[186:189], v[68:71]
	v_mfma_i32_16x16x64_i8 v[64:67], v[216:219], v[186:189], v[64:67]
	s_mov_b32 m0, s61
	v_lshl_add_u64 v[190:191], v[224:225], 0, s[30:31]
	s_barrier
	s_setprio 0
	ds_read_b128 v[158:161], v201 offset:49152
	ds_read_b128 v[162:165], v201 offset:50176
	ds_read_b128 v[166:169], v201 offset:51200
	ds_read_b128 v[170:173], v201 offset:52224
	ds_read_b128 v[174:177], v201 offset:53248
	ds_read_b128 v[178:181], v201 offset:54272
	ds_read_b128 v[182:185], v201 offset:55296
	ds_read_b128 v[186:189], v201 offset:56320
	global_load_lds_dwordx4 v[190:191], off
	v_lshl_add_u64 v[190:191], v[228:229], 0, s[30:31]
	s_mov_b32 m0, s62
	s_nop 0
	global_load_lds_dwordx4 v[190:191], off
	s_waitcnt lgkmcnt(0)
	s_setprio 1
	s_barrier
	v_mfma_i32_16x16x64_i8 v[60:63], v[142:145], v[158:161], v[60:63]
	v_mfma_i32_16x16x64_i8 v[56:59], v[150:153], v[158:161], v[56:59]
	v_mfma_i32_16x16x64_i8 v[52:55], v[142:145], v[166:169], v[52:55]
	v_mfma_i32_16x16x64_i8 v[48:51], v[150:153], v[166:169], v[48:51]
	v_mfma_i32_16x16x64_i8 v[44:47], v[142:145], v[174:177], v[44:47]
	v_mfma_i32_16x16x64_i8 v[40:43], v[150:153], v[174:177], v[40:43]
	v_mfma_i32_16x16x64_i8 v[36:39], v[142:145], v[182:185], v[36:39]
	v_mfma_i32_16x16x64_i8 v[32:35], v[150:153], v[182:185], v[32:35]
	v_mfma_i32_16x16x64_i8 v[60:63], v[146:149], v[162:165], v[60:63]
	v_mfma_i32_16x16x64_i8 v[56:59], v[154:157], v[162:165], v[56:59]
	v_mfma_i32_16x16x64_i8 v[52:55], v[146:149], v[170:173], v[52:55]
	v_mfma_i32_16x16x64_i8 v[48:51], v[154:157], v[170:173], v[48:51]
	v_mfma_i32_16x16x64_i8 v[44:47], v[146:149], v[178:181], v[44:47]
	v_mfma_i32_16x16x64_i8 v[40:43], v[154:157], v[178:181], v[40:43]
	v_mfma_i32_16x16x64_i8 v[36:39], v[146:149], v[186:189], v[36:39]
	v_mfma_i32_16x16x64_i8 v[32:35], v[154:157], v[186:189], v[32:35]
	s_barrier
	s_setprio 0
	s_add_u32 s54, s54, 0x20080
	s_addc_u32 s55, s55, 0
	s_add_i32 s56, s56, s18
	v_lshl_add_u64 v[142:143], s[54:55], 0, v[130:131]
	s_mov_b32 m0, s56
	s_nop 0
	global_load_lds_dwordx4 v[142:143], off
	v_lshl_add_u64 v[142:143], s[54:55], 0, v[128:129]
	s_add_i32 m0, s56, 0x2000
	s_nop 0
	global_load_lds_dwordx4 v[142:143], off
	s_waitcnt vmcnt(6)
	s_setprio 1
	s_barrier
	v_mfma_i32_16x16x64_i8 v[28:31], v[204:207], v[158:161], v[28:31]
	v_mfma_i32_16x16x64_i8 v[24:27], v[212:215], v[158:161], v[24:27]
	v_mfma_i32_16x16x64_i8 v[20:23], v[204:207], v[166:169], v[20:23]
	v_mfma_i32_16x16x64_i8 v[16:19], v[212:215], v[166:169], v[16:19]
	v_mfma_i32_16x16x64_i8 v[12:15], v[204:207], v[174:177], v[12:15]
	v_mfma_i32_16x16x64_i8 v[8:11], v[212:215], v[174:177], v[8:11]
	v_mfma_i32_16x16x64_i8 v[4:7], v[204:207], v[182:185], v[4:7]
	v_mfma_i32_16x16x64_i8 v[0:3], v[212:215], v[182:185], v[0:3]
	v_mfma_i32_16x16x64_i8 v[28:31], v[208:211], v[162:165], v[28:31]
	v_mfma_i32_16x16x64_i8 v[24:27], v[216:219], v[162:165], v[24:27]
	v_mfma_i32_16x16x64_i8 v[20:23], v[208:211], v[170:173], v[20:23]
	v_mfma_i32_16x16x64_i8 v[16:19], v[216:219], v[170:173], v[16:19]
	v_mfma_i32_16x16x64_i8 v[12:15], v[208:211], v[178:181], v[12:15]
	v_mfma_i32_16x16x64_i8 v[8:11], v[216:219], v[178:181], v[8:11]
	v_mfma_i32_16x16x64_i8 v[4:7], v[208:211], v[186:189], v[4:7]
	v_mfma_i32_16x16x64_i8 v[0:3], v[216:219], v[186:189], v[0:3]
	s_add_u32 s6, s6, 0x100
	s_addc_u32 s7, s7, 0
	s_add_u32 s73, s73, 0x100
	s_addc_u32 s74, s74, 0
	s_cmp_ge_i32 s75, s60
	s_mov_b32 s54, s75
	s_barrier
	s_setprio 0
	s_cbranch_scc0 .LBB0_341

.Lzskip_P2r:
	s_and_b64 s[8:9], s[8:9], exec
	s_cselect_b32 s47, s51, s57
	s_cselect_b32 s49, s50, s56
	s_cselect_b32 s73, s53, s59
	s_cselect_b32 s74, s52, s58
	s_add_u32 s75, s58, 0x100
	s_addc_u32 s76, s59, 0
	s_mov_b32 s58, 0
	v_add_u32_e32 v156, s71, v224
	ds_read_b128 v[144:147], v156
	ds_read_b128 v[148:151], v156 offset:1024
	ds_read_b128 v[152:155], v156 offset:2048
	ds_read_b128 v[156:159], v156 offset:3072
	s_add_i32 s77, s58, 2
	s_add_u32 s8, s56, 0x100
	s_addc_u32 s9, s57, 0
	s_cmp_eq_u32 s70, s58
	s_cselect_b32 s58, s74, s75
	s_cselect_b32 s61, s47, s9
	s_cselect_b32 s60, s49, s8
	s_cselect_b32 s59, s73, s76
	v_lshl_add_u64 v[192:193], s[56:57], 0, v[136:137]
	s_add_i32 m0, s62, 0xc000
	ds_read_b128 v[160:163], v232
	ds_read_b128 v[164:167], v232 offset:1024
	ds_read_b128 v[168:171], v232 offset:2048
	ds_read_b128 v[172:175], v232 offset:3072
	ds_read_b128 v[176:179], v232 offset:4096
	ds_read_b128 v[180:183], v232 offset:5120
	ds_read_b128 v[184:187], v232 offset:6144
	ds_read_b128 v[188:191], v232 offset:7168
	global_load_lds_dwordx4 v[192:193], off
	v_lshl_add_u64 v[192:193], s[56:57], 0, v[138:139]
	s_add_i32 m0, s62, 0xe000
	s_nop 0
	global_load_lds_dwordx4 v[192:193], off
	s_waitcnt lgkmcnt(8)
	s_setprio 1
	s_barrier
	s_waitcnt lgkmcnt(0)
	v_mfma_i32_16x16x64_i8 v[124:127], v[144:147], v[160:163], 0
	v_mfma_i32_16x16x64_i8 v[112:115], v[152:155], v[160:163], 0
	v_mfma_i32_16x16x64_i8 v[120:123], v[144:147], v[168:171], 0
	v_mfma_i32_16x16x64_i8 v[104:107], v[152:155], v[168:171], 0
	v_mfma_i32_16x16x64_i8 v[116:119], v[144:147], v[176:179], 0
	v_mfma_i32_16x16x64_i8 v[100:103], v[152:155], v[176:179], 0
	v_mfma_i32_16x16x64_i8 v[108:111], v[144:147], v[184:187], 0
	v_mfma_i32_16x16x64_i8 v[96:99], v[152:155], v[184:187], 0
	v_mfma_i32_16x16x64_i8 v[124:127], v[148:151], v[164:167], v[124:127]
	v_mfma_i32_16x16x64_i8 v[112:115], v[156:159], v[164:167], v[112:115]
	v_mfma_i32_16x16x64_i8 v[120:123], v[148:151], v[172:175], v[120:123]
	v_mfma_i32_16x16x64_i8 v[104:107], v[156:159], v[172:175], v[104:107]
	v_mfma_i32_16x16x64_i8 v[116:119], v[148:151], v[180:183], v[116:119]
	v_mfma_i32_16x16x64_i8 v[100:103], v[156:159], v[180:183], v[100:103]
	v_mfma_i32_16x16x64_i8 v[108:111], v[148:151], v[188:191], v[108:111]
	v_mfma_i32_16x16x64_i8 v[96:99], v[156:159], v[188:191], v[96:99]
	s_barrier
	s_setprio 0
	s_add_i32 s20, s71, s19
	v_add_u32_e32 v204, s72, v224
	v_lshl_add_u64 v[208:209], s[58:59], 0, v[132:133]
	s_mov_b32 m0, s20
	ds_read_b128 v[192:195], v204
	ds_read_b128 v[196:199], v204 offset:1024
	ds_read_b128 v[200:203], v204 offset:2048
	ds_read_b128 v[204:207], v204 offset:3072
	global_load_lds_dwordx4 v[208:209], off
	v_lshl_add_u64 v[210:211], s[58:59], 0, v[128:129]
	s_add_i32 m0, s20, 0x2000
	s_nop 0
	global_load_lds_dwordx4 v[210:211], off
	s_waitcnt lgkmcnt(0)
	s_setprio 1
	s_barrier
	v_mfma_i32_16x16x64_i8 v[84:87], v[192:195], v[160:163], 0
	v_mfma_i32_16x16x64_i8 v[56:59], v[200:203], v[160:163], 0
	v_mfma_i32_16x16x64_i8 v[76:79], v[192:195], v[168:171], 0
	v_mfma_i32_16x16x64_i8 v[44:47], v[200:203], v[168:171], 0
	v_mfma_i32_16x16x64_i8 v[64:67], v[192:195], v[176:179], 0
	v_mfma_i32_16x16x64_i8 v[36:39], v[200:203], v[176:179], 0
	v_mfma_i32_16x16x64_i8 v[52:55], v[192:195], v[184:187], 0
	v_mfma_i32_16x16x64_i8 v[28:31], v[200:203], v[184:187], 0
	v_mfma_i32_16x16x64_i8 v[84:87], v[196:199], v[164:167], v[84:87]
	v_mfma_i32_16x16x64_i8 v[56:59], v[204:207], v[164:167], v[56:59]
	v_mfma_i32_16x16x64_i8 v[76:79], v[196:199], v[172:175], v[76:79]
	v_mfma_i32_16x16x64_i8 v[44:47], v[204:207], v[172:175], v[44:47]
	v_mfma_i32_16x16x64_i8 v[64:67], v[196:199], v[180:183], v[64:67]
	v_mfma_i32_16x16x64_i8 v[36:39], v[204:207], v[180:183], v[36:39]
	v_mfma_i32_16x16x64_i8 v[52:55], v[196:199], v[188:191], v[52:55]
	v_mfma_i32_16x16x64_i8 v[28:31], v[204:207], v[188:191], v[28:31]
	s_mov_b32 m0, s62
	v_lshl_add_u64 v[212:213], s[60:61], 0, v[134:135]
	s_barrier
	s_setprio 0
	ds_read_b128 v[160:163], v232 offset:16384
	ds_read_b128 v[164:167], v232 offset:17408
	ds_read_b128 v[168:171], v232 offset:18432
	ds_read_b128 v[172:175], v232 offset:19456
	ds_read_b128 v[176:179], v232 offset:20480
	ds_read_b128 v[180:183], v232 offset:21504
	ds_read_b128 v[184:187], v232 offset:22528
	ds_read_b128 v[188:191], v232 offset:23552
	global_load_lds_dwordx4 v[212:213], off
	v_lshl_add_u64 v[214:215], s[60:61], 0, v[130:131]
	s_mov_b32 m0, s63
	s_nop 0
	global_load_lds_dwordx4 v[214:215], off
	s_waitcnt lgkmcnt(0)
	s_setprio 1
	s_barrier
	v_mfma_i32_16x16x64_i8 v[92:95], v[144:147], v[160:163], 0
	v_mfma_i32_16x16x64_i8 v[72:75], v[152:155], v[160:163], 0
	v_mfma_i32_16x16x64_i8 v[88:91], v[144:147], v[168:171], 0
	v_mfma_i32_16x16x64_i8 v[60:63], v[152:155], v[168:171], 0
	v_mfma_i32_16x16x64_i8 v[80:83], v[144:147], v[176:179], 0
	v_mfma_i32_16x16x64_i8 v[48:51], v[152:155], v[176:179], 0
	v_mfma_i32_16x16x64_i8 v[68:71], v[144:147], v[184:187], 0
	v_mfma_i32_16x16x64_i8 v[40:43], v[152:155], v[184:187], 0
	v_mfma_i32_16x16x64_i8 v[92:95], v[148:151], v[164:167], v[92:95]
	v_mfma_i32_16x16x64_i8 v[72:75], v[156:159], v[164:167], v[72:75]
	v_mfma_i32_16x16x64_i8 v[88:91], v[148:151], v[172:175], v[88:91]
	v_mfma_i32_16x16x64_i8 v[60:63], v[156:159], v[172:175], v[60:63]
	v_mfma_i32_16x16x64_i8 v[80:83], v[148:151], v[180:183], v[80:83]
	v_mfma_i32_16x16x64_i8 v[48:51], v[156:159], v[180:183], v[48:51]
	v_mfma_i32_16x16x64_i8 v[68:71], v[148:151], v[188:191], v[68:71]
	v_mfma_i32_16x16x64_i8 v[40:43], v[156:159], v[188:191], v[40:43]
	s_barrier
	s_setprio 0
	s_add_u32 s20, s58, 0x20000
	s_addc_u32 s21, s59, 0
	s_add_i32 s56, s72, s19
	v_lshl_add_u64 v[144:145], s[20:21], 0, v[132:133]
	s_mov_b32 m0, s56
	s_nop 0
	global_load_lds_dwordx4 v[144:145], off
	v_lshl_add_u64 v[144:145], s[20:21], 0, v[128:129]
	s_add_i32 m0, s56, 0x2000
	s_nop 0
	global_load_lds_dwordx4 v[144:145], off
	s_waitcnt vmcnt(6)
	s_setprio 1
	s_barrier
	v_mfma_i32_16x16x64_i8 v[32:35], v[192:195], v[160:163], 0
	v_mfma_i32_16x16x64_i8 v[8:11], v[200:203], v[160:163], 0
	v_mfma_i32_16x16x64_i8 v[24:27], v[192:195], v[168:171], 0
	v_mfma_i32_16x16x64_i8 v[12:15], v[200:203], v[168:171], 0
	v_mfma_i32_16x16x64_i8 v[20:23], v[192:195], v[176:179], 0
	v_mfma_i32_16x16x64_i8 v[4:7], v[200:203], v[176:179], 0
	v_mfma_i32_16x16x64_i8 v[16:19], v[192:195], v[184:187], 0
	v_mfma_i32_16x16x64_i8 v[0:3], v[200:203], v[184:187], 0
	v_mfma_i32_16x16x64_i8 v[32:35], v[196:199], v[164:167], v[32:35]
	v_mfma_i32_16x16x64_i8 v[8:11], v[204:207], v[164:167], v[8:11]
	v_mfma_i32_16x16x64_i8 v[24:27], v[196:199], v[172:175], v[24:27]
	v_mfma_i32_16x16x64_i8 v[12:15], v[204:207], v[172:175], v[12:15]
	v_mfma_i32_16x16x64_i8 v[20:23], v[196:199], v[180:183], v[20:23]
	v_mfma_i32_16x16x64_i8 v[4:7], v[204:207], v[180:183], v[4:7]
	v_mfma_i32_16x16x64_i8 v[16:19], v[196:199], v[188:191], v[16:19]
	v_mfma_i32_16x16x64_i8 v[0:3], v[204:207], v[188:191], v[0:3]
	s_add_i32 s56, 0, 0x18000
	v_add_u32_e32 v156, s56, v224
	s_barrier
	s_setprio 0
	ds_read_b128 v[144:147], v156
	ds_read_b128 v[148:151], v156 offset:1024
	ds_read_b128 v[152:155], v156 offset:2048
	ds_read_b128 v[156:159], v156 offset:3072
	s_add_u32 s20, s60, 0x1000
	s_addc_u32 s21, s61, 0
	s_mov_b32 m0, s64
	v_lshl_add_u64 v[192:193], s[20:21], 0, v[134:135]
	ds_read_b128 v[160:163], v232 offset:32768
	ds_read_b128 v[164:167], v232 offset:33792
	ds_read_b128 v[168:171], v232 offset:34816
	ds_read_b128 v[172:175], v232 offset:35840
	ds_read_b128 v[176:179], v232 offset:36864
	ds_read_b128 v[180:183], v232 offset:37888
	ds_read_b128 v[184:187], v232 offset:38912
	ds_read_b128 v[188:191], v232 offset:39936
	global_load_lds_dwordx4 v[192:193], off
	v_lshl_add_u64 v[192:193], s[20:21], 0, v[130:131]
	s_mov_b32 m0, s65
	s_nop 0
	global_load_lds_dwordx4 v[192:193], off
	s_waitcnt lgkmcnt(8)
	s_setprio 1
	s_barrier
	s_waitcnt lgkmcnt(0)
	v_mfma_i32_16x16x64_i8 v[124:127], v[144:147], v[160:163], v[124:127]
	v_mfma_i32_16x16x64_i8 v[112:115], v[152:155], v[160:163], v[112:115]
	v_mfma_i32_16x16x64_i8 v[120:123], v[144:147], v[168:171], v[120:123]
	v_mfma_i32_16x16x64_i8 v[104:107], v[152:155], v[168:171], v[104:107]
	v_mfma_i32_16x16x64_i8 v[116:119], v[144:147], v[176:179], v[116:119]
	v_mfma_i32_16x16x64_i8 v[100:103], v[152:155], v[176:179], v[100:103]
	v_mfma_i32_16x16x64_i8 v[108:111], v[144:147], v[184:187], v[108:111]
	v_mfma_i32_16x16x64_i8 v[96:99], v[152:155], v[184:187], v[96:99]
	v_mfma_i32_16x16x64_i8 v[124:127], v[148:151], v[164:167], v[124:127]
	v_mfma_i32_16x16x64_i8 v[112:115], v[156:159], v[164:167], v[112:115]
	v_mfma_i32_16x16x64_i8 v[120:123], v[148:151], v[172:175], v[120:123]
	v_mfma_i32_16x16x64_i8 v[104:107], v[156:159], v[172:175], v[104:107]
	v_mfma_i32_16x16x64_i8 v[116:119], v[148:151], v[180:183], v[116:119]
	v_mfma_i32_16x16x64_i8 v[100:103], v[156:159], v[180:183], v[100:103]
	v_mfma_i32_16x16x64_i8 v[108:111], v[148:151], v[188:191], v[108:111]
	v_mfma_i32_16x16x64_i8 v[96:99], v[156:159], v[188:191], v[96:99]
	s_barrier
	s_setprio 0
	s_add_i32 s57, 0, 0x1c000
	s_add_i32 s20, s56, s19
	v_add_u32_e32 v204, s57, v224
	v_lshl_add_u64 v[208:209], v[208:209], 0, s[34:35]
	s_mov_b32 m0, s20
	ds_read_b128 v[192:195], v204
	ds_read_b128 v[196:199], v204 offset:1024
	ds_read_b128 v[200:203], v204 offset:2048
	ds_read_b128 v[204:207], v204 offset:3072
	global_load_lds_dwordx4 v[208:209], off
	v_lshl_add_u64 v[208:209], v[210:211], 0, s[34:35]
	s_add_i32 m0, s20, 0x2000
	s_nop 0
	global_load_lds_dwordx4 v[208:209], off
	s_waitcnt lgkmcnt(0)
	s_setprio 1
	s_barrier
	v_mfma_i32_16x16x64_i8 v[84:87], v[192:195], v[160:163], v[84:87]
	v_mfma_i32_16x16x64_i8 v[56:59], v[200:203], v[160:163], v[56:59]
	v_mfma_i32_16x16x64_i8 v[76:79], v[192:195], v[168:171], v[76:79]
	v_mfma_i32_16x16x64_i8 v[44:47], v[200:203], v[168:171], v[44:47]
	v_mfma_i32_16x16x64_i8 v[64:67], v[192:195], v[176:179], v[64:67]
	v_mfma_i32_16x16x64_i8 v[36:39], v[200:203], v[176:179], v[36:39]
	v_mfma_i32_16x16x64_i8 v[52:55], v[192:195], v[184:187], v[52:55]
	v_mfma_i32_16x16x64_i8 v[28:31], v[200:203], v[184:187], v[28:31]
	v_mfma_i32_16x16x64_i8 v[84:87], v[196:199], v[164:167], v[84:87]
	v_mfma_i32_16x16x64_i8 v[56:59], v[204:207], v[164:167], v[56:59]
	v_mfma_i32_16x16x64_i8 v[76:79], v[196:199], v[172:175], v[76:79]
	v_mfma_i32_16x16x64_i8 v[44:47], v[204:207], v[172:175], v[44:47]
	v_mfma_i32_16x16x64_i8 v[64:67], v[196:199], v[180:183], v[64:67]
	v_mfma_i32_16x16x64_i8 v[36:39], v[204:207], v[180:183], v[36:39]
	v_mfma_i32_16x16x64_i8 v[52:55], v[196:199], v[188:191], v[52:55]
	v_mfma_i32_16x16x64_i8 v[28:31], v[204:207], v[188:191], v[28:31]
	s_mov_b32 m0, s68
	v_lshl_add_u64 v[208:209], v[212:213], 0, s[34:35]
	s_barrier
	s_setprio 0
	ds_read_b128 v[160:163], v232 offset:49152
	ds_read_b128 v[164:167], v232 offset:50176
	ds_read_b128 v[168:171], v232 offset:51200
	ds_read_b128 v[172:175], v232 offset:52224
	ds_read_b128 v[176:179], v232 offset:53248
	ds_read_b128 v[180:183], v232 offset:54272
	ds_read_b128 v[184:187], v232 offset:55296
	ds_read_b128 v[188:191], v232 offset:56320
	global_load_lds_dwordx4 v[208:209], off
	v_lshl_add_u64 v[208:209], v[214:215], 0, s[34:35]
	s_mov_b32 m0, s69
	s_nop 0
	global_load_lds_dwordx4 v[208:209], off
	s_waitcnt lgkmcnt(0)
	s_setprio 1
	s_barrier
	v_mfma_i32_16x16x64_i8 v[92:95], v[144:147], v[160:163], v[92:95]
	v_mfma_i32_16x16x64_i8 v[72:75], v[152:155], v[160:163], v[72:75]
	v_mfma_i32_16x16x64_i8 v[88:91], v[144:147], v[168:171], v[88:91]
	v_mfma_i32_16x16x64_i8 v[60:63], v[152:155], v[168:171], v[60:63]
	v_mfma_i32_16x16x64_i8 v[80:83], v[144:147], v[176:179], v[80:83]
	v_mfma_i32_16x16x64_i8 v[48:51], v[152:155], v[176:179], v[48:51]
	v_mfma_i32_16x16x64_i8 v[68:71], v[144:147], v[184:187], v[68:71]
	v_mfma_i32_16x16x64_i8 v[40:43], v[152:155], v[184:187], v[40:43]
	v_mfma_i32_16x16x64_i8 v[92:95], v[148:151], v[164:167], v[92:95]
	v_mfma_i32_16x16x64_i8 v[72:75], v[156:159], v[164:167], v[72:75]
	v_mfma_i32_16x16x64_i8 v[88:91], v[148:151], v[172:175], v[88:91]
	v_mfma_i32_16x16x64_i8 v[60:63], v[156:159], v[172:175], v[60:63]
	v_mfma_i32_16x16x64_i8 v[80:83], v[148:151], v[180:183], v[80:83]
	v_mfma_i32_16x16x64_i8 v[48:51], v[156:159], v[180:183], v[48:51]
	v_mfma_i32_16x16x64_i8 v[68:71], v[148:151], v[188:191], v[68:71]
	v_mfma_i32_16x16x64_i8 v[40:43], v[156:159], v[188:191], v[40:43]
	s_barrier
	s_setprio 0
	s_add_u32 s20, s58, 0x20080
	s_addc_u32 s21, s59, 0
	s_add_i32 s56, s57, s19
	v_lshl_add_u64 v[144:145], s[20:21], 0, v[132:133]
	s_mov_b32 m0, s56
	s_nop 0
	global_load_lds_dwordx4 v[144:145], off
	v_lshl_add_u64 v[144:145], s[20:21], 0, v[128:129]
	s_add_i32 m0, s56, 0x2000
	s_nop 0
	global_load_lds_dwordx4 v[144:145], off
	s_waitcnt vmcnt(6)
	s_setprio 1
	s_barrier
	v_mfma_i32_16x16x64_i8 v[32:35], v[192:195], v[160:163], v[32:35]
	v_mfma_i32_16x16x64_i8 v[8:11], v[200:203], v[160:163], v[8:11]
	v_mfma_i32_16x16x64_i8 v[24:27], v[192:195], v[168:171], v[24:27]
	v_mfma_i32_16x16x64_i8 v[12:15], v[200:203], v[168:171], v[12:15]
	v_mfma_i32_16x16x64_i8 v[20:23], v[192:195], v[176:179], v[20:23]
	v_mfma_i32_16x16x64_i8 v[4:7], v[200:203], v[176:179], v[4:7]
	v_mfma_i32_16x16x64_i8 v[16:19], v[192:195], v[184:187], v[16:19]
	v_mfma_i32_16x16x64_i8 v[0:3], v[200:203], v[184:187], v[0:3]
	v_mfma_i32_16x16x64_i8 v[32:35], v[196:199], v[164:167], v[32:35]
	v_mfma_i32_16x16x64_i8 v[8:11], v[204:207], v[164:167], v[8:11]
	v_mfma_i32_16x16x64_i8 v[24:27], v[196:199], v[172:175], v[24:27]
	v_mfma_i32_16x16x64_i8 v[12:15], v[204:207], v[172:175], v[12:15]
	v_mfma_i32_16x16x64_i8 v[20:23], v[196:199], v[180:183], v[20:23]
	v_mfma_i32_16x16x64_i8 v[4:7], v[204:207], v[180:183], v[4:7]
	v_mfma_i32_16x16x64_i8 v[16:19], v[196:199], v[188:191], v[16:19]
	v_mfma_i32_16x16x64_i8 v[0:3], v[204:207], v[188:191], v[0:3]
	s_add_u32 s75, s75, 0x100
	s_addc_u32 s76, s76, 0
	s_cmp_ge_i32 s77, s67
	s_mov_b64 s[56:57], s[8:9]
	s_mov_b32 s58, s77
	s_barrier
	s_setprio 0
	s_cbranch_scc1 .Lpeel_done_P2r
.LBB0_371:
	v_add_u32_e32 v156, s71, v224
	ds_read_b128 v[144:147], v156
	ds_read_b128 v[148:151], v156 offset:1024
	ds_read_b128 v[152:155], v156 offset:2048
	ds_read_b128 v[156:159], v156 offset:3072
	s_add_i32 s77, s58, 2
	s_add_u32 s8, s56, 0x100
	s_addc_u32 s9, s57, 0
	s_cmp_eq_u32 s70, s58
	s_cselect_b32 s58, s74, s75
	s_cselect_b32 s61, s47, s9
	s_cselect_b32 s60, s49, s8
	s_cselect_b32 s59, s73, s76
	v_lshl_add_u64 v[192:193], s[56:57], 0, v[136:137]
	s_add_i32 m0, s62, 0xc000
	ds_read_b128 v[160:163], v232
	ds_read_b128 v[164:167], v232 offset:1024
	ds_read_b128 v[168:171], v232 offset:2048
	ds_read_b128 v[172:175], v232 offset:3072
	ds_read_b128 v[176:179], v232 offset:4096
	ds_read_b128 v[180:183], v232 offset:5120
	ds_read_b128 v[184:187], v232 offset:6144
	ds_read_b128 v[188:191], v232 offset:7168
	global_load_lds_dwordx4 v[192:193], off
	v_lshl_add_u64 v[192:193], s[56:57], 0, v[138:139]
	s_add_i32 m0, s62, 0xe000
	s_nop 0
	global_load_lds_dwordx4 v[192:193], off
	s_waitcnt lgkmcnt(8)
	s_setprio 1
	s_barrier
	s_waitcnt lgkmcnt(0)
	v_mfma_i32_16x16x64_i8 v[124:127], v[144:147], v[160:163], v[124:127]
	v_mfma_i32_16x16x64_i8 v[112:115], v[152:155], v[160:163], v[112:115]
	v_mfma_i32_16x16x64_i8 v[120:123], v[144:147], v[168:171], v[120:123]
	v_mfma_i32_16x16x64_i8 v[104:107], v[152:155], v[168:171], v[104:107]
	v_mfma_i32_16x16x64_i8 v[116:119], v[144:147], v[176:179], v[116:119]
	v_mfma_i32_16x16x64_i8 v[100:103], v[152:155], v[176:179], v[100:103]
	v_mfma_i32_16x16x64_i8 v[108:111], v[144:147], v[184:187], v[108:111]
	v_mfma_i32_16x16x64_i8 v[96:99], v[152:155], v[184:187], v[96:99]
	v_mfma_i32_16x16x64_i8 v[124:127], v[148:151], v[164:167], v[124:127]
	v_mfma_i32_16x16x64_i8 v[112:115], v[156:159], v[164:167], v[112:115]
	v_mfma_i32_16x16x64_i8 v[120:123], v[148:151], v[172:175], v[120:123]
	v_mfma_i32_16x16x64_i8 v[104:107], v[156:159], v[172:175], v[104:107]
	v_mfma_i32_16x16x64_i8 v[116:119], v[148:151], v[180:183], v[116:119]
	v_mfma_i32_16x16x64_i8 v[100:103], v[156:159], v[180:183], v[100:103]
	v_mfma_i32_16x16x64_i8 v[108:111], v[148:151], v[188:191], v[108:111]
	v_mfma_i32_16x16x64_i8 v[96:99], v[156:159], v[188:191], v[96:99]
	s_barrier
	s_setprio 0
	s_add_i32 s20, s71, s19
	v_add_u32_e32 v204, s72, v224
	v_lshl_add_u64 v[208:209], s[58:59], 0, v[132:133]
	s_mov_b32 m0, s20
	ds_read_b128 v[192:195], v204
	ds_read_b128 v[196:199], v204 offset:1024
	ds_read_b128 v[200:203], v204 offset:2048
	ds_read_b128 v[204:207], v204 offset:3072
	global_load_lds_dwordx4 v[208:209], off
	v_lshl_add_u64 v[210:211], s[58:59], 0, v[128:129]
	s_add_i32 m0, s20, 0x2000
	s_nop 0
	global_load_lds_dwordx4 v[210:211], off
	s_waitcnt lgkmcnt(0)
	s_setprio 1
	s_barrier
	v_mfma_i32_16x16x64_i8 v[84:87], v[192:195], v[160:163], v[84:87]
	v_mfma_i32_16x16x64_i8 v[56:59], v[200:203], v[160:163], v[56:59]
	v_mfma_i32_16x16x64_i8 v[76:79], v[192:195], v[168:171], v[76:79]
	v_mfma_i32_16x16x64_i8 v[44:47], v[200:203], v[168:171], v[44:47]
	v_mfma_i32_16x16x64_i8 v[64:67], v[192:195], v[176:179], v[64:67]
	v_mfma_i32_16x16x64_i8 v[36:39], v[200:203], v[176:179], v[36:39]
	v_mfma_i32_16x16x64_i8 v[52:55], v[192:195], v[184:187], v[52:55]
	v_mfma_i32_16x16x64_i8 v[28:31], v[200:203], v[184:187], v[28:31]
	v_mfma_i32_16x16x64_i8 v[84:87], v[196:199], v[164:167], v[84:87]
	v_mfma_i32_16x16x64_i8 v[56:59], v[204:207], v[164:167], v[56:59]
	v_mfma_i32_16x16x64_i8 v[76:79], v[196:199], v[172:175], v[76:79]
	v_mfma_i32_16x16x64_i8 v[44:47], v[204:207], v[172:175], v[44:47]
	v_mfma_i32_16x16x64_i8 v[64:67], v[196:199], v[180:183], v[64:67]
	v_mfma_i32_16x16x64_i8 v[36:39], v[204:207], v[180:183], v[36:39]
	v_mfma_i32_16x16x64_i8 v[52:55], v[196:199], v[188:191], v[52:55]
	v_mfma_i32_16x16x64_i8 v[28:31], v[204:207], v[188:191], v[28:31]
	s_mov_b32 m0, s62
	v_lshl_add_u64 v[212:213], s[60:61], 0, v[134:135]
	s_barrier
	s_setprio 0
	ds_read_b128 v[160:163], v232 offset:16384
	ds_read_b128 v[164:167], v232 offset:17408
	ds_read_b128 v[168:171], v232 offset:18432
	ds_read_b128 v[172:175], v232 offset:19456
	ds_read_b128 v[176:179], v232 offset:20480
	ds_read_b128 v[180:183], v232 offset:21504
	ds_read_b128 v[184:187], v232 offset:22528
	ds_read_b128 v[188:191], v232 offset:23552
	global_load_lds_dwordx4 v[212:213], off
	v_lshl_add_u64 v[214:215], s[60:61], 0, v[130:131]
	s_mov_b32 m0, s63
	s_nop 0
	global_load_lds_dwordx4 v[214:215], off
	s_waitcnt lgkmcnt(0)
	s_setprio 1
	s_barrier
	v_mfma_i32_16x16x64_i8 v[92:95], v[144:147], v[160:163], v[92:95]
	v_mfma_i32_16x16x64_i8 v[72:75], v[152:155], v[160:163], v[72:75]
	v_mfma_i32_16x16x64_i8 v[88:91], v[144:147], v[168:171], v[88:91]
	v_mfma_i32_16x16x64_i8 v[60:63], v[152:155], v[168:171], v[60:63]
	v_mfma_i32_16x16x64_i8 v[80:83], v[144:147], v[176:179], v[80:83]
	v_mfma_i32_16x16x64_i8 v[48:51], v[152:155], v[176:179], v[48:51]
	v_mfma_i32_16x16x64_i8 v[68:71], v[144:147], v[184:187], v[68:71]
	v_mfma_i32_16x16x64_i8 v[40:43], v[152:155], v[184:187], v[40:43]
	v_mfma_i32_16x16x64_i8 v[92:95], v[148:151], v[164:167], v[92:95]
	v_mfma_i32_16x16x64_i8 v[72:75], v[156:159], v[164:167], v[72:75]
	v_mfma_i32_16x16x64_i8 v[88:91], v[148:151], v[172:175], v[88:91]
	v_mfma_i32_16x16x64_i8 v[60:63], v[156:159], v[172:175], v[60:63]
	v_mfma_i32_16x16x64_i8 v[80:83], v[148:151], v[180:183], v[80:83]
	v_mfma_i32_16x16x64_i8 v[48:51], v[156:159], v[180:183], v[48:51]
	v_mfma_i32_16x16x64_i8 v[68:71], v[148:151], v[188:191], v[68:71]
	v_mfma_i32_16x16x64_i8 v[40:43], v[156:159], v[188:191], v[40:43]
	s_barrier
	s_setprio 0
	s_add_u32 s20, s58, 0x20000
	s_addc_u32 s21, s59, 0
	s_add_i32 s56, s72, s19
	v_lshl_add_u64 v[144:145], s[20:21], 0, v[132:133]
	s_mov_b32 m0, s56
	s_nop 0
	global_load_lds_dwordx4 v[144:145], off
	v_lshl_add_u64 v[144:145], s[20:21], 0, v[128:129]
	s_add_i32 m0, s56, 0x2000
	s_nop 0
	global_load_lds_dwordx4 v[144:145], off
	s_waitcnt vmcnt(6)
	s_setprio 1
	s_barrier
	v_mfma_i32_16x16x64_i8 v[32:35], v[192:195], v[160:163], v[32:35]
	v_mfma_i32_16x16x64_i8 v[8:11], v[200:203], v[160:163], v[8:11]
	v_mfma_i32_16x16x64_i8 v[24:27], v[192:195], v[168:171], v[24:27]
	v_mfma_i32_16x16x64_i8 v[12:15], v[200:203], v[168:171], v[12:15]
	v_mfma_i32_16x16x64_i8 v[20:23], v[192:195], v[176:179], v[20:23]
	v_mfma_i32_16x16x64_i8 v[4:7], v[200:203], v[176:179], v[4:7]
	v_mfma_i32_16x16x64_i8 v[16:19], v[192:195], v[184:187], v[16:19]
	v_mfma_i32_16x16x64_i8 v[0:3], v[200:203], v[184:187], v[0:3]
	v_mfma_i32_16x16x64_i8 v[32:35], v[196:199], v[164:167], v[32:35]
	v_mfma_i32_16x16x64_i8 v[8:11], v[204:207], v[164:167], v[8:11]
	v_mfma_i32_16x16x64_i8 v[24:27], v[196:199], v[172:175], v[24:27]
	v_mfma_i32_16x16x64_i8 v[12:15], v[204:207], v[172:175], v[12:15]
	v_mfma_i32_16x16x64_i8 v[20:23], v[196:199], v[180:183], v[20:23]
	v_mfma_i32_16x16x64_i8 v[4:7], v[204:207], v[180:183], v[4:7]
	v_mfma_i32_16x16x64_i8 v[16:19], v[196:199], v[188:191], v[16:19]
	v_mfma_i32_16x16x64_i8 v[0:3], v[204:207], v[188:191], v[0:3]
	s_add_i32 s56, 0, 0x18000
	v_add_u32_e32 v156, s56, v224
	s_barrier
	s_setprio 0
	ds_read_b128 v[144:147], v156
	ds_read_b128 v[148:151], v156 offset:1024
	ds_read_b128 v[152:155], v156 offset:2048
	ds_read_b128 v[156:159], v156 offset:3072
	s_add_u32 s20, s60, 0x1000
	s_addc_u32 s21, s61, 0
	s_mov_b32 m0, s64
	v_lshl_add_u64 v[192:193], s[20:21], 0, v[134:135]
	ds_read_b128 v[160:163], v232 offset:32768
	ds_read_b128 v[164:167], v232 offset:33792
	ds_read_b128 v[168:171], v232 offset:34816
	ds_read_b128 v[172:175], v232 offset:35840
	ds_read_b128 v[176:179], v232 offset:36864
	ds_read_b128 v[180:183], v232 offset:37888
	ds_read_b128 v[184:187], v232 offset:38912
	ds_read_b128 v[188:191], v232 offset:39936
	global_load_lds_dwordx4 v[192:193], off
	v_lshl_add_u64 v[192:193], s[20:21], 0, v[130:131]
	s_mov_b32 m0, s65
	s_nop 0
	global_load_lds_dwordx4 v[192:193], off
	s_waitcnt lgkmcnt(8)
	s_setprio 1
	s_barrier
	s_waitcnt lgkmcnt(0)
	v_mfma_i32_16x16x64_i8 v[124:127], v[144:147], v[160:163], v[124:127]
	v_mfma_i32_16x16x64_i8 v[112:115], v[152:155], v[160:163], v[112:115]
	v_mfma_i32_16x16x64_i8 v[120:123], v[144:147], v[168:171], v[120:123]
	v_mfma_i32_16x16x64_i8 v[104:107], v[152:155], v[168:171], v[104:107]
	v_mfma_i32_16x16x64_i8 v[116:119], v[144:147], v[176:179], v[116:119]
	v_mfma_i32_16x16x64_i8 v[100:103], v[152:155], v[176:179], v[100:103]
	v_mfma_i32_16x16x64_i8 v[108:111], v[144:147], v[184:187], v[108:111]
	v_mfma_i32_16x16x64_i8 v[96:99], v[152:155], v[184:187], v[96:99]
	v_mfma_i32_16x16x64_i8 v[124:127], v[148:151], v[164:167], v[124:127]
	v_mfma_i32_16x16x64_i8 v[112:115], v[156:159], v[164:167], v[112:115]
	v_mfma_i32_16x16x64_i8 v[120:123], v[148:151], v[172:175], v[120:123]
	v_mfma_i32_16x16x64_i8 v[104:107], v[156:159], v[172:175], v[104:107]
	v_mfma_i32_16x16x64_i8 v[116:119], v[148:151], v[180:183], v[116:119]
	v_mfma_i32_16x16x64_i8 v[100:103], v[156:159], v[180:183], v[100:103]
	v_mfma_i32_16x16x64_i8 v[108:111], v[148:151], v[188:191], v[108:111]
	v_mfma_i32_16x16x64_i8 v[96:99], v[156:159], v[188:191], v[96:99]
	s_barrier
	s_setprio 0
	s_add_i32 s57, 0, 0x1c000
	s_add_i32 s20, s56, s19
	v_add_u32_e32 v204, s57, v224
	v_lshl_add_u64 v[208:209], v[208:209], 0, s[34:35]
	s_mov_b32 m0, s20
	ds_read_b128 v[192:195], v204
	ds_read_b128 v[196:199], v204 offset:1024
	ds_read_b128 v[200:203], v204 offset:2048
	ds_read_b128 v[204:207], v204 offset:3072
	global_load_lds_dwordx4 v[208:209], off
	v_lshl_add_u64 v[208:209], v[210:211], 0, s[34:35]
	s_add_i32 m0, s20, 0x2000
	s_nop 0
	global_load_lds_dwordx4 v[208:209], off
	s_waitcnt lgkmcnt(0)
	s_setprio 1
	s_barrier
	v_mfma_i32_16x16x64_i8 v[84:87], v[192:195], v[160:163], v[84:87]
	v_mfma_i32_16x16x64_i8 v[56:59], v[200:203], v[160:163], v[56:59]
	v_mfma_i32_16x16x64_i8 v[76:79], v[192:195], v[168:171], v[76:79]
	v_mfma_i32_16x16x64_i8 v[44:47], v[200:203], v[168:171], v[44:47]
	v_mfma_i32_16x16x64_i8 v[64:67], v[192:195], v[176:179], v[64:67]
	v_mfma_i32_16x16x64_i8 v[36:39], v[200:203], v[176:179], v[36:39]
	v_mfma_i32_16x16x64_i8 v[52:55], v[192:195], v[184:187], v[52:55]
	v_mfma_i32_16x16x64_i8 v[28:31], v[200:203], v[184:187], v[28:31]
	v_mfma_i32_16x16x64_i8 v[84:87], v[196:199], v[164:167], v[84:87]
	v_mfma_i32_16x16x64_i8 v[56:59], v[204:207], v[164:167], v[56:59]
	v_mfma_i32_16x16x64_i8 v[76:79], v[196:199], v[172:175], v[76:79]
	v_mfma_i32_16x16x64_i8 v[44:47], v[204:207], v[172:175], v[44:47]
	v_mfma_i32_16x16x64_i8 v[64:67], v[196:199], v[180:183], v[64:67]
	v_mfma_i32_16x16x64_i8 v[36:39], v[204:207], v[180:183], v[36:39]
	v_mfma_i32_16x16x64_i8 v[52:55], v[196:199], v[188:191], v[52:55]
	v_mfma_i32_16x16x64_i8 v[28:31], v[204:207], v[188:191], v[28:31]
	s_mov_b32 m0, s68
	v_lshl_add_u64 v[208:209], v[212:213], 0, s[34:35]
	s_barrier
	s_setprio 0
	ds_read_b128 v[160:163], v232 offset:49152
	ds_read_b128 v[164:167], v232 offset:50176
	ds_read_b128 v[168:171], v232 offset:51200
	ds_read_b128 v[172:175], v232 offset:52224
	ds_read_b128 v[176:179], v232 offset:53248
	ds_read_b128 v[180:183], v232 offset:54272
	ds_read_b128 v[184:187], v232 offset:55296
	ds_read_b128 v[188:191], v232 offset:56320
	global_load_lds_dwordx4 v[208:209], off
	v_lshl_add_u64 v[208:209], v[214:215], 0, s[34:35]
	s_mov_b32 m0, s69
	s_nop 0
	global_load_lds_dwordx4 v[208:209], off
	s_waitcnt lgkmcnt(0)
	s_setprio 1
	s_barrier
	v_mfma_i32_16x16x64_i8 v[92:95], v[144:147], v[160:163], v[92:95]
	v_mfma_i32_16x16x64_i8 v[72:75], v[152:155], v[160:163], v[72:75]
	v_mfma_i32_16x16x64_i8 v[88:91], v[144:147], v[168:171], v[88:91]
	v_mfma_i32_16x16x64_i8 v[60:63], v[152:155], v[168:171], v[60:63]
	v_mfma_i32_16x16x64_i8 v[80:83], v[144:147], v[176:179], v[80:83]
	v_mfma_i32_16x16x64_i8 v[48:51], v[152:155], v[176:179], v[48:51]
	v_mfma_i32_16x16x64_i8 v[68:71], v[144:147], v[184:187], v[68:71]
	v_mfma_i32_16x16x64_i8 v[40:43], v[152:155], v[184:187], v[40:43]
	v_mfma_i32_16x16x64_i8 v[92:95], v[148:151], v[164:167], v[92:95]
	v_mfma_i32_16x16x64_i8 v[72:75], v[156:159], v[164:167], v[72:75]
	v_mfma_i32_16x16x64_i8 v[88:91], v[148:151], v[172:175], v[88:91]
	v_mfma_i32_16x16x64_i8 v[60:63], v[156:159], v[172:175], v[60:63]
	v_mfma_i32_16x16x64_i8 v[80:83], v[148:151], v[180:183], v[80:83]
	v_mfma_i32_16x16x64_i8 v[48:51], v[156:159], v[180:183], v[48:51]
	v_mfma_i32_16x16x64_i8 v[68:71], v[148:151], v[188:191], v[68:71]
	v_mfma_i32_16x16x64_i8 v[40:43], v[156:159], v[188:191], v[40:43]
	s_barrier
	s_setprio 0
	s_add_u32 s20, s58, 0x20080
	s_addc_u32 s21, s59, 0
	s_add_i32 s56, s57, s19
	v_lshl_add_u64 v[144:145], s[20:21], 0, v[132:133]
	s_mov_b32 m0, s56
	s_nop 0
	global_load_lds_dwordx4 v[144:145], off
	v_lshl_add_u64 v[144:145], s[20:21], 0, v[128:129]
	s_add_i32 m0, s56, 0x2000
	s_nop 0
	global_load_lds_dwordx4 v[144:145], off
	s_waitcnt vmcnt(6)
	s_setprio 1
	s_barrier
	v_mfma_i32_16x16x64_i8 v[32:35], v[192:195], v[160:163], v[32:35]
	v_mfma_i32_16x16x64_i8 v[8:11], v[200:203], v[160:163], v[8:11]
	v_mfma_i32_16x16x64_i8 v[24:27], v[192:195], v[168:171], v[24:27]
	v_mfma_i32_16x16x64_i8 v[12:15], v[200:203], v[168:171], v[12:15]
	v_mfma_i32_16x16x64_i8 v[20:23], v[192:195], v[176:179], v[20:23]
	v_mfma_i32_16x16x64_i8 v[4:7], v[200:203], v[176:179], v[4:7]
	v_mfma_i32_16x16x64_i8 v[16:19], v[192:195], v[184:187], v[16:19]
	v_mfma_i32_16x16x64_i8 v[0:3], v[200:203], v[184:187], v[0:3]
	v_mfma_i32_16x16x64_i8 v[32:35], v[196:199], v[164:167], v[32:35]
	v_mfma_i32_16x16x64_i8 v[8:11], v[204:207], v[164:167], v[8:11]
	v_mfma_i32_16x16x64_i8 v[24:27], v[196:199], v[172:175], v[24:27]
	v_mfma_i32_16x16x64_i8 v[12:15], v[204:207], v[172:175], v[12:15]
	v_mfma_i32_16x16x64_i8 v[20:23], v[196:199], v[180:183], v[20:23]
	v_mfma_i32_16x16x64_i8 v[4:7], v[204:207], v[180:183], v[4:7]
	v_mfma_i32_16x16x64_i8 v[16:19], v[196:199], v[188:191], v[16:19]
	v_mfma_i32_16x16x64_i8 v[0:3], v[204:207], v[188:191], v[0:3]
	s_add_u32 s75, s75, 0x100
	s_addc_u32 s76, s76, 0
	s_cmp_ge_i32 s77, s67
	s_mov_b64 s[56:57], s[8:9]
	s_mov_b32 s58, s77
	s_barrier
	s_setprio 0
	s_cbranch_scc0 .LBB0_371

.Lpz_P4:
	s_and_b64 s[4:5], s[4:5], exec
	s_cselect_b32 s53, s59, s9
	s_cselect_b32 s55, s58, s8
	s_add_u32 s64, s8, 0x100
	s_addc_u32 s65, s9, 0
	s_mov_b32 s8, 0
	ds_read_b128 v[92:95], v229
	ds_read_b128 v[112:115], v229 offset:1024
	ds_read_b128 v[132:135], v229 offset:2048
	ds_read_b128 v[140:143], v229 offset:3072
	s_add_i32 s66, s8, 2
	s_add_u32 s4, s6, 0x100
	s_addc_u32 s5, s7, 0
	s_cmp_eq_u32 s19, s8
	s_cselect_b32 s8, s55, s64
	s_cselect_b32 s61, s57, s5
	s_cselect_b32 s60, s56, s4
	s_cselect_b32 s9, s53, s65
	v_lshl_add_u64 v[190:191], s[6:7], 0, v[166:167]
	s_add_i32 m0, s93, 0xc000
	ds_read_b128 v[144:147], v230
	ds_read_b128 v[148:151], v230 offset:1024
	ds_read_b128 v[152:155], v230 offset:2048
	ds_read_b128 v[170:173], v230 offset:3072
	ds_read_b128 v[174:177], v230 offset:4096
	ds_read_b128 v[178:181], v230 offset:5120
	ds_read_b128 v[182:185], v230 offset:6144
	ds_read_b128 v[186:189], v230 offset:7168
	global_load_lds_dwordx4 v[190:191], off
	v_lshl_add_u64 v[190:191], s[6:7], 0, v[168:169]
	s_add_i32 m0, s93, 0xe000
	s_nop 0
	global_load_lds_dwordx4 v[190:191], off
	s_waitcnt lgkmcnt(8)
	s_setprio 1
	s_barrier
	s_waitcnt lgkmcnt(0)
	v_mfma_f32_16x16x32_bf16 v[136:139], v[92:95], v[144:147], 0
	v_mfma_f32_16x16x32_bf16 v[124:127], v[132:135], v[144:147], 0
	v_mfma_f32_16x16x32_bf16 v[116:119], v[92:95], v[152:155], 0
	v_mfma_f32_16x16x32_bf16 v[104:107], v[132:135], v[152:155], 0
	v_mfma_f32_16x16x32_bf16 v[96:99], v[92:95], v[174:177], 0
	v_mfma_f32_16x16x32_bf16 v[84:87], v[132:135], v[174:177], 0
	v_mfma_f32_16x16x32_bf16 v[76:79], v[92:95], v[182:185], 0
	v_mfma_f32_16x16x32_bf16 v[68:71], v[132:135], v[182:185], 0
	v_mfma_f32_16x16x32_bf16 v[136:139], v[112:115], v[148:151], v[136:139]
	v_mfma_f32_16x16x32_bf16 v[124:127], v[140:143], v[148:151], v[124:127]
	v_mfma_f32_16x16x32_bf16 v[116:119], v[112:115], v[170:173], v[116:119]
	v_mfma_f32_16x16x32_bf16 v[104:107], v[140:143], v[170:173], v[104:107]
	v_mfma_f32_16x16x32_bf16 v[96:99], v[112:115], v[178:181], v[96:99]
	v_mfma_f32_16x16x32_bf16 v[84:87], v[140:143], v[178:181], v[84:87]
	v_mfma_f32_16x16x32_bf16 v[76:79], v[112:115], v[186:189], v[76:79]
	v_mfma_f32_16x16x32_bf16 v[68:71], v[140:143], v[186:189], v[68:71]
	s_barrier
	s_setprio 0
	s_add_i32 s6, s88, s92
	v_lshl_add_u64 v[206:207], s[8:9], 0, v[158:159]
	s_mov_b32 m0, s6
	ds_read_b128 v[190:193], v231
	ds_read_b128 v[194:197], v231 offset:1024
	ds_read_b128 v[198:201], v231 offset:2048
	ds_read_b128 v[202:205], v231 offset:3072
	global_load_lds_dwordx4 v[206:207], off
	v_lshl_add_u64 v[208:209], s[8:9], 0, v[162:163]
	s_add_i32 m0, s6, 0x2000
	s_nop 0
	global_load_lds_dwordx4 v[208:209], off
	s_waitcnt lgkmcnt(0)
	s_setprio 1
	s_barrier
	v_mfma_f32_16x16x32_bf16 v[128:131], v[190:193], v[144:147], 0
	v_mfma_f32_16x16x32_bf16 v[120:123], v[198:201], v[144:147], 0
	v_mfma_f32_16x16x32_bf16 v[108:111], v[190:193], v[152:155], 0
	v_mfma_f32_16x16x32_bf16 v[100:103], v[198:201], v[152:155], 0
	v_mfma_f32_16x16x32_bf16 v[88:91], v[190:193], v[174:177], 0
	v_mfma_f32_16x16x32_bf16 v[80:83], v[198:201], v[174:177], 0
	v_mfma_f32_16x16x32_bf16 v[72:75], v[190:193], v[182:185], 0
	v_mfma_f32_16x16x32_bf16 v[64:67], v[198:201], v[182:185], 0
	v_mfma_f32_16x16x32_bf16 v[128:131], v[194:197], v[148:151], v[128:131]
	v_mfma_f32_16x16x32_bf16 v[120:123], v[202:205], v[148:151], v[120:123]
	v_mfma_f32_16x16x32_bf16 v[108:111], v[194:197], v[170:173], v[108:111]
	v_mfma_f32_16x16x32_bf16 v[100:103], v[202:205], v[170:173], v[100:103]
	v_mfma_f32_16x16x32_bf16 v[88:91], v[194:197], v[178:181], v[88:91]
	v_mfma_f32_16x16x32_bf16 v[80:83], v[202:205], v[178:181], v[80:83]
	v_mfma_f32_16x16x32_bf16 v[72:75], v[194:197], v[186:189], v[72:75]
	v_mfma_f32_16x16x32_bf16 v[64:67], v[202:205], v[186:189], v[64:67]
	s_mov_b32 m0, s93
	v_lshl_add_u64 v[210:211], s[60:61], 0, v[156:157]
	s_barrier
	s_setprio 0
	ds_read_b128 v[144:147], v230 offset:16384
	ds_read_b128 v[148:151], v230 offset:17408
	ds_read_b128 v[152:155], v230 offset:18432
	ds_read_b128 v[170:173], v230 offset:19456
	ds_read_b128 v[174:177], v230 offset:20480
	ds_read_b128 v[178:181], v230 offset:21504
	ds_read_b128 v[182:185], v230 offset:22528
	ds_read_b128 v[186:189], v230 offset:23552
	global_load_lds_dwordx4 v[210:211], off
	v_lshl_add_u64 v[212:213], s[60:61], 0, v[160:161]
	s_mov_b32 m0, s84
	s_nop 0
	global_load_lds_dwordx4 v[212:213], off
	s_waitcnt lgkmcnt(0)
	s_setprio 1
	s_barrier
	v_mfma_f32_16x16x32_bf16 v[60:63], v[92:95], v[144:147], 0
	v_mfma_f32_16x16x32_bf16 v[52:55], v[132:135], v[144:147], 0
	v_mfma_f32_16x16x32_bf16 v[44:47], v[92:95], v[152:155], 0
	v_mfma_f32_16x16x32_bf16 v[36:39], v[132:135], v[152:155], 0
	v_mfma_f32_16x16x32_bf16 v[28:31], v[92:95], v[174:177], 0
	v_mfma_f32_16x16x32_bf16 v[20:23], v[132:135], v[174:177], 0
	v_mfma_f32_16x16x32_bf16 v[12:15], v[92:95], v[182:185], 0
	v_mfma_f32_16x16x32_bf16 v[4:7], v[132:135], v[182:185], 0
	v_mfma_f32_16x16x32_bf16 v[60:63], v[112:115], v[148:151], v[60:63]
	v_mfma_f32_16x16x32_bf16 v[52:55], v[140:143], v[148:151], v[52:55]
	v_mfma_f32_16x16x32_bf16 v[44:47], v[112:115], v[170:173], v[44:47]
	v_mfma_f32_16x16x32_bf16 v[36:39], v[140:143], v[170:173], v[36:39]
	v_mfma_f32_16x16x32_bf16 v[28:31], v[112:115], v[178:181], v[28:31]
	v_mfma_f32_16x16x32_bf16 v[20:23], v[140:143], v[178:181], v[20:23]
	v_mfma_f32_16x16x32_bf16 v[12:15], v[112:115], v[186:189], v[12:15]
	v_mfma_f32_16x16x32_bf16 v[4:7], v[140:143], v[186:189], v[4:7]
	s_barrier
	s_setprio 0
	s_add_u32 s6, s8, 0x10000
	s_addc_u32 s7, s9, 0
	s_add_i32 s20, s89, s92
	v_lshl_add_u64 v[92:93], s[6:7], 0, v[158:159]
	s_mov_b32 m0, s20
	s_nop 0
	global_load_lds_dwordx4 v[92:93], off
	v_lshl_add_u64 v[92:93], s[6:7], 0, v[162:163]
	s_add_i32 m0, s20, 0x2000
	s_nop 0
	global_load_lds_dwordx4 v[92:93], off
	s_waitcnt vmcnt(6)
	s_setprio 1
	s_barrier
	v_mfma_f32_16x16x32_bf16 v[56:59], v[190:193], v[144:147], 0
	v_mfma_f32_16x16x32_bf16 v[48:51], v[198:201], v[144:147], 0
	v_mfma_f32_16x16x32_bf16 v[40:43], v[190:193], v[152:155], 0
	v_mfma_f32_16x16x32_bf16 v[32:35], v[198:201], v[152:155], 0
	v_mfma_f32_16x16x32_bf16 v[24:27], v[190:193], v[174:177], 0
	v_mfma_f32_16x16x32_bf16 v[16:19], v[198:201], v[174:177], 0
	v_mfma_f32_16x16x32_bf16 v[8:11], v[190:193], v[182:185], 0
	v_mfma_f32_16x16x32_bf16 v[0:3], v[198:201], v[182:185], 0
	v_mfma_f32_16x16x32_bf16 v[56:59], v[194:197], v[148:151], v[56:59]
	v_mfma_f32_16x16x32_bf16 v[48:51], v[202:205], v[148:151], v[48:51]
	v_mfma_f32_16x16x32_bf16 v[40:43], v[194:197], v[170:173], v[40:43]
	v_mfma_f32_16x16x32_bf16 v[32:35], v[202:205], v[170:173], v[32:35]
	v_mfma_f32_16x16x32_bf16 v[24:27], v[194:197], v[178:181], v[24:27]
	v_mfma_f32_16x16x32_bf16 v[16:19], v[202:205], v[178:181], v[16:19]
	v_mfma_f32_16x16x32_bf16 v[8:11], v[194:197], v[186:189], v[8:11]
	v_mfma_f32_16x16x32_bf16 v[0:3], v[202:205], v[186:189], v[0:3]
	s_add_i32 s20, 0, 0x18000
	v_add_u32_e32 v140, s20, v228
	s_barrier
	s_setprio 0
	ds_read_b128 v[92:95], v140
	ds_read_b128 v[112:115], v140 offset:1024
	ds_read_b128 v[132:135], v140 offset:2048
	ds_read_b128 v[140:143], v140 offset:3072
	s_add_u32 s6, s60, 0x2000
	s_addc_u32 s7, s61, 0
	s_mov_b32 m0, s86
	v_lshl_add_u64 v[190:191], s[6:7], 0, v[156:157]
	ds_read_b128 v[144:147], v230 offset:32768
	ds_read_b128 v[148:151], v230 offset:33792
	ds_read_b128 v[152:155], v230 offset:34816
	ds_read_b128 v[170:173], v230 offset:35840
	ds_read_b128 v[174:177], v230 offset:36864
	ds_read_b128 v[178:181], v230 offset:37888
	ds_read_b128 v[182:185], v230 offset:38912
	ds_read_b128 v[186:189], v230 offset:39936
	global_load_lds_dwordx4 v[190:191], off
	v_lshl_add_u64 v[190:191], s[6:7], 0, v[160:161]
	s_mov_b32 m0, s87
	s_nop 0
	global_load_lds_dwordx4 v[190:191], off
	s_waitcnt lgkmcnt(8)
	s_setprio 1
	s_barrier
	s_waitcnt lgkmcnt(0)
	v_mfma_f32_16x16x32_bf16 v[136:139], v[92:95], v[144:147], v[136:139]
	v_mfma_f32_16x16x32_bf16 v[124:127], v[132:135], v[144:147], v[124:127]
	v_mfma_f32_16x16x32_bf16 v[116:119], v[92:95], v[152:155], v[116:119]
	v_mfma_f32_16x16x32_bf16 v[104:107], v[132:135], v[152:155], v[104:107]
	v_mfma_f32_16x16x32_bf16 v[96:99], v[92:95], v[174:177], v[96:99]
	v_mfma_f32_16x16x32_bf16 v[84:87], v[132:135], v[174:177], v[84:87]
	v_mfma_f32_16x16x32_bf16 v[76:79], v[92:95], v[182:185], v[76:79]
	v_mfma_f32_16x16x32_bf16 v[68:71], v[132:135], v[182:185], v[68:71]
	v_mfma_f32_16x16x32_bf16 v[136:139], v[112:115], v[148:151], v[136:139]
	v_mfma_f32_16x16x32_bf16 v[124:127], v[140:143], v[148:151], v[124:127]
	v_mfma_f32_16x16x32_bf16 v[116:119], v[112:115], v[170:173], v[116:119]
	v_mfma_f32_16x16x32_bf16 v[104:107], v[140:143], v[170:173], v[104:107]
	v_mfma_f32_16x16x32_bf16 v[96:99], v[112:115], v[178:181], v[96:99]
	v_mfma_f32_16x16x32_bf16 v[84:87], v[140:143], v[178:181], v[84:87]
	v_mfma_f32_16x16x32_bf16 v[76:79], v[112:115], v[186:189], v[76:79]
	v_mfma_f32_16x16x32_bf16 v[68:71], v[140:143], v[186:189], v[68:71]
	s_barrier
	s_setprio 0
	s_add_i32 s21, 0, 0x1c000
	s_add_i32 s6, s20, s92
	v_add_u32_e32 v164, s21, v228
	v_lshl_add_u64 v[206:207], v[206:207], 0, s[42:43]
	s_mov_b32 m0, s6
	ds_read_b128 v[190:193], v164
	ds_read_b128 v[194:197], v164 offset:1024
	ds_read_b128 v[198:201], v164 offset:2048
	ds_read_b128 v[202:205], v164 offset:3072
	global_load_lds_dwordx4 v[206:207], off
	v_lshl_add_u64 v[206:207], v[208:209], 0, s[42:43]
	s_add_i32 m0, s6, 0x2000
	s_nop 0
	global_load_lds_dwordx4 v[206:207], off
	s_waitcnt lgkmcnt(0)
	s_setprio 1
	s_barrier
	v_mfma_f32_16x16x32_bf16 v[128:131], v[190:193], v[144:147], v[128:131]
	v_mfma_f32_16x16x32_bf16 v[120:123], v[198:201], v[144:147], v[120:123]
	v_mfma_f32_16x16x32_bf16 v[108:111], v[190:193], v[152:155], v[108:111]
	v_mfma_f32_16x16x32_bf16 v[100:103], v[198:201], v[152:155], v[100:103]
	v_mfma_f32_16x16x32_bf16 v[88:91], v[190:193], v[174:177], v[88:91]
	v_mfma_f32_16x16x32_bf16 v[80:83], v[198:201], v[174:177], v[80:83]
	v_mfma_f32_16x16x32_bf16 v[72:75], v[190:193], v[182:185], v[72:75]
	v_mfma_f32_16x16x32_bf16 v[64:67], v[198:201], v[182:185], v[64:67]
	v_mfma_f32_16x16x32_bf16 v[128:131], v[194:197], v[148:151], v[128:131]
	v_mfma_f32_16x16x32_bf16 v[120:123], v[202:205], v[148:151], v[120:123]
	v_mfma_f32_16x16x32_bf16 v[108:111], v[194:197], v[170:173], v[108:111]
	v_mfma_f32_16x16x32_bf16 v[100:103], v[202:205], v[170:173], v[100:103]
	v_mfma_f32_16x16x32_bf16 v[88:91], v[194:197], v[178:181], v[88:91]
	v_mfma_f32_16x16x32_bf16 v[80:83], v[202:205], v[178:181], v[80:83]
	v_mfma_f32_16x16x32_bf16 v[72:75], v[194:197], v[186:189], v[72:75]
	v_mfma_f32_16x16x32_bf16 v[64:67], v[202:205], v[186:189], v[64:67]
	s_mov_b32 m0, s97
	v_lshl_add_u64 v[206:207], v[210:211], 0, s[42:43]
	s_barrier
	s_setprio 0
	ds_read_b128 v[144:147], v230 offset:49152
	ds_read_b128 v[148:151], v230 offset:50176
	ds_read_b128 v[152:155], v230 offset:51200
	ds_read_b128 v[170:173], v230 offset:52224
	ds_read_b128 v[174:177], v230 offset:53248
	ds_read_b128 v[178:181], v230 offset:54272
	ds_read_b128 v[182:185], v230 offset:55296
	ds_read_b128 v[186:189], v230 offset:56320
	global_load_lds_dwordx4 v[206:207], off
	v_lshl_add_u64 v[206:207], v[212:213], 0, s[42:43]
	s_mov_b32 m0, s18
	s_nop 0
	global_load_lds_dwordx4 v[206:207], off
	s_waitcnt lgkmcnt(0)
	s_setprio 1
	s_barrier
	v_mfma_f32_16x16x32_bf16 v[60:63], v[92:95], v[144:147], v[60:63]
	v_mfma_f32_16x16x32_bf16 v[52:55], v[132:135], v[144:147], v[52:55]
	v_mfma_f32_16x16x32_bf16 v[44:47], v[92:95], v[152:155], v[44:47]
	v_mfma_f32_16x16x32_bf16 v[36:39], v[132:135], v[152:155], v[36:39]
	v_mfma_f32_16x16x32_bf16 v[28:31], v[92:95], v[174:177], v[28:31]
	v_mfma_f32_16x16x32_bf16 v[20:23], v[132:135], v[174:177], v[20:23]
	v_mfma_f32_16x16x32_bf16 v[12:15], v[92:95], v[182:185], v[12:15]
	v_mfma_f32_16x16x32_bf16 v[4:7], v[132:135], v[182:185], v[4:7]
	v_mfma_f32_16x16x32_bf16 v[60:63], v[112:115], v[148:151], v[60:63]
	v_mfma_f32_16x16x32_bf16 v[52:55], v[140:143], v[148:151], v[52:55]
	v_mfma_f32_16x16x32_bf16 v[44:47], v[112:115], v[170:173], v[44:47]
	v_mfma_f32_16x16x32_bf16 v[36:39], v[140:143], v[170:173], v[36:39]
	v_mfma_f32_16x16x32_bf16 v[28:31], v[112:115], v[178:181], v[28:31]
	v_mfma_f32_16x16x32_bf16 v[20:23], v[140:143], v[178:181], v[20:23]
	v_mfma_f32_16x16x32_bf16 v[12:15], v[112:115], v[186:189], v[12:15]
	v_mfma_f32_16x16x32_bf16 v[4:7], v[140:143], v[186:189], v[4:7]
	s_barrier
	s_setprio 0
	s_add_u32 s6, s8, 0x10080
	s_addc_u32 s7, s9, 0
	s_add_i32 s8, s21, s92
	v_lshl_add_u64 v[92:93], s[6:7], 0, v[158:159]
	s_mov_b32 m0, s8
	s_nop 0
	global_load_lds_dwordx4 v[92:93], off
	v_lshl_add_u64 v[92:93], s[6:7], 0, v[162:163]
	s_add_i32 m0, s8, 0x2000
	s_nop 0
	global_load_lds_dwordx4 v[92:93], off
	s_waitcnt vmcnt(6)
	s_setprio 1
	s_barrier
	v_mfma_f32_16x16x32_bf16 v[56:59], v[190:193], v[144:147], v[56:59]
	v_mfma_f32_16x16x32_bf16 v[48:51], v[198:201], v[144:147], v[48:51]
	v_mfma_f32_16x16x32_bf16 v[40:43], v[190:193], v[152:155], v[40:43]
	v_mfma_f32_16x16x32_bf16 v[32:35], v[198:201], v[152:155], v[32:35]
	v_mfma_f32_16x16x32_bf16 v[24:27], v[190:193], v[174:177], v[24:27]
	v_mfma_f32_16x16x32_bf16 v[16:19], v[198:201], v[174:177], v[16:19]
	v_mfma_f32_16x16x32_bf16 v[8:11], v[190:193], v[182:185], v[8:11]
	v_mfma_f32_16x16x32_bf16 v[0:3], v[198:201], v[182:185], v[0:3]
	v_mfma_f32_16x16x32_bf16 v[56:59], v[194:197], v[148:151], v[56:59]
	v_mfma_f32_16x16x32_bf16 v[48:51], v[202:205], v[148:151], v[48:51]
	v_mfma_f32_16x16x32_bf16 v[40:43], v[194:197], v[170:173], v[40:43]
	v_mfma_f32_16x16x32_bf16 v[32:35], v[202:205], v[170:173], v[32:35]
	v_mfma_f32_16x16x32_bf16 v[24:27], v[194:197], v[178:181], v[24:27]
	v_mfma_f32_16x16x32_bf16 v[16:19], v[202:205], v[178:181], v[16:19]
	v_mfma_f32_16x16x32_bf16 v[8:11], v[194:197], v[186:189], v[8:11]
	v_mfma_f32_16x16x32_bf16 v[0:3], v[202:205], v[186:189], v[0:3]
	s_add_u32 s64, s64, 0x100
	s_addc_u32 s65, s65, 0
	s_cmp_lt_i32 s66, s95
	s_mov_b64 s[6:7], s[4:5]
	s_mov_b32 s8, s66
	s_barrier
	s_setprio 0
	s_cbranch_scc0 .Lpeel_done_P4
.LBB0_461:
	ds_read_b128 v[92:95], v229
	ds_read_b128 v[112:115], v229 offset:1024
	ds_read_b128 v[132:135], v229 offset:2048
	ds_read_b128 v[140:143], v229 offset:3072
	s_add_i32 s66, s8, 2
	s_add_u32 s4, s6, 0x100
	s_addc_u32 s5, s7, 0
	s_cmp_eq_u32 s19, s8
	s_cselect_b32 s8, s55, s64
	s_cselect_b32 s61, s57, s5
	s_cselect_b32 s60, s56, s4
	s_cselect_b32 s9, s53, s65
	v_lshl_add_u64 v[190:191], s[6:7], 0, v[166:167]
	s_add_i32 m0, s93, 0xc000
	ds_read_b128 v[144:147], v230
	ds_read_b128 v[148:151], v230 offset:1024
	ds_read_b128 v[152:155], v230 offset:2048
	ds_read_b128 v[170:173], v230 offset:3072
	ds_read_b128 v[174:177], v230 offset:4096
	ds_read_b128 v[178:181], v230 offset:5120
	ds_read_b128 v[182:185], v230 offset:6144
	ds_read_b128 v[186:189], v230 offset:7168
	global_load_lds_dwordx4 v[190:191], off
	v_lshl_add_u64 v[190:191], s[6:7], 0, v[168:169]
	s_add_i32 m0, s93, 0xe000
	s_nop 0
	global_load_lds_dwordx4 v[190:191], off
	s_waitcnt lgkmcnt(8)
	s_setprio 1
	s_barrier
	s_waitcnt lgkmcnt(0)
	v_mfma_f32_16x16x32_bf16 v[136:139], v[92:95], v[144:147], v[136:139]
	v_mfma_f32_16x16x32_bf16 v[124:127], v[132:135], v[144:147], v[124:127]
	v_mfma_f32_16x16x32_bf16 v[116:119], v[92:95], v[152:155], v[116:119]
	v_mfma_f32_16x16x32_bf16 v[104:107], v[132:135], v[152:155], v[104:107]
	v_mfma_f32_16x16x32_bf16 v[96:99], v[92:95], v[174:177], v[96:99]
	v_mfma_f32_16x16x32_bf16 v[84:87], v[132:135], v[174:177], v[84:87]
	v_mfma_f32_16x16x32_bf16 v[76:79], v[92:95], v[182:185], v[76:79]
	v_mfma_f32_16x16x32_bf16 v[68:71], v[132:135], v[182:185], v[68:71]
	v_mfma_f32_16x16x32_bf16 v[136:139], v[112:115], v[148:151], v[136:139]
	v_mfma_f32_16x16x32_bf16 v[124:127], v[140:143], v[148:151], v[124:127]
	v_mfma_f32_16x16x32_bf16 v[116:119], v[112:115], v[170:173], v[116:119]
	v_mfma_f32_16x16x32_bf16 v[104:107], v[140:143], v[170:173], v[104:107]
	v_mfma_f32_16x16x32_bf16 v[96:99], v[112:115], v[178:181], v[96:99]
	v_mfma_f32_16x16x32_bf16 v[84:87], v[140:143], v[178:181], v[84:87]
	v_mfma_f32_16x16x32_bf16 v[76:79], v[112:115], v[186:189], v[76:79]
	v_mfma_f32_16x16x32_bf16 v[68:71], v[140:143], v[186:189], v[68:71]
	s_barrier
	s_setprio 0
	s_add_i32 s6, s88, s92
	v_lshl_add_u64 v[206:207], s[8:9], 0, v[158:159]
	s_mov_b32 m0, s6
	ds_read_b128 v[190:193], v231
	ds_read_b128 v[194:197], v231 offset:1024
	ds_read_b128 v[198:201], v231 offset:2048
	ds_read_b128 v[202:205], v231 offset:3072
	global_load_lds_dwordx4 v[206:207], off
	v_lshl_add_u64 v[208:209], s[8:9], 0, v[162:163]
	s_add_i32 m0, s6, 0x2000
	s_nop 0
	global_load_lds_dwordx4 v[208:209], off
	s_waitcnt lgkmcnt(0)
	s_setprio 1
	s_barrier
	v_mfma_f32_16x16x32_bf16 v[128:131], v[190:193], v[144:147], v[128:131]
	v_mfma_f32_16x16x32_bf16 v[120:123], v[198:201], v[144:147], v[120:123]
	v_mfma_f32_16x16x32_bf16 v[108:111], v[190:193], v[152:155], v[108:111]
	v_mfma_f32_16x16x32_bf16 v[100:103], v[198:201], v[152:155], v[100:103]
	v_mfma_f32_16x16x32_bf16 v[88:91], v[190:193], v[174:177], v[88:91]
	v_mfma_f32_16x16x32_bf16 v[80:83], v[198:201], v[174:177], v[80:83]
	v_mfma_f32_16x16x32_bf16 v[72:75], v[190:193], v[182:185], v[72:75]
	v_mfma_f32_16x16x32_bf16 v[64:67], v[198:201], v[182:185], v[64:67]
	v_mfma_f32_16x16x32_bf16 v[128:131], v[194:197], v[148:151], v[128:131]
	v_mfma_f32_16x16x32_bf16 v[120:123], v[202:205], v[148:151], v[120:123]
	v_mfma_f32_16x16x32_bf16 v[108:111], v[194:197], v[170:173], v[108:111]
	v_mfma_f32_16x16x32_bf16 v[100:103], v[202:205], v[170:173], v[100:103]
	v_mfma_f32_16x16x32_bf16 v[88:91], v[194:197], v[178:181], v[88:91]
	v_mfma_f32_16x16x32_bf16 v[80:83], v[202:205], v[178:181], v[80:83]
	v_mfma_f32_16x16x32_bf16 v[72:75], v[194:197], v[186:189], v[72:75]
	v_mfma_f32_16x16x32_bf16 v[64:67], v[202:205], v[186:189], v[64:67]
	s_mov_b32 m0, s93
	v_lshl_add_u64 v[210:211], s[60:61], 0, v[156:157]
	s_barrier
	s_setprio 0
	ds_read_b128 v[144:147], v230 offset:16384
	ds_read_b128 v[148:151], v230 offset:17408
	ds_read_b128 v[152:155], v230 offset:18432
	ds_read_b128 v[170:173], v230 offset:19456
	ds_read_b128 v[174:177], v230 offset:20480
	ds_read_b128 v[178:181], v230 offset:21504
	ds_read_b128 v[182:185], v230 offset:22528
	ds_read_b128 v[186:189], v230 offset:23552
	global_load_lds_dwordx4 v[210:211], off
	v_lshl_add_u64 v[212:213], s[60:61], 0, v[160:161]
	s_mov_b32 m0, s84
	s_nop 0
	global_load_lds_dwordx4 v[212:213], off
	s_waitcnt lgkmcnt(0)
	s_setprio 1
	s_barrier
	v_mfma_f32_16x16x32_bf16 v[60:63], v[92:95], v[144:147], v[60:63]
	v_mfma_f32_16x16x32_bf16 v[52:55], v[132:135], v[144:147], v[52:55]
	v_mfma_f32_16x16x32_bf16 v[44:47], v[92:95], v[152:155], v[44:47]
	v_mfma_f32_16x16x32_bf16 v[36:39], v[132:135], v[152:155], v[36:39]
	v_mfma_f32_16x16x32_bf16 v[28:31], v[92:95], v[174:177], v[28:31]
	v_mfma_f32_16x16x32_bf16 v[20:23], v[132:135], v[174:177], v[20:23]
	v_mfma_f32_16x16x32_bf16 v[12:15], v[92:95], v[182:185], v[12:15]
	v_mfma_f32_16x16x32_bf16 v[4:7], v[132:135], v[182:185], v[4:7]
	v_mfma_f32_16x16x32_bf16 v[60:63], v[112:115], v[148:151], v[60:63]
	v_mfma_f32_16x16x32_bf16 v[52:55], v[140:143], v[148:151], v[52:55]
	v_mfma_f32_16x16x32_bf16 v[44:47], v[112:115], v[170:173], v[44:47]
	v_mfma_f32_16x16x32_bf16 v[36:39], v[140:143], v[170:173], v[36:39]
	v_mfma_f32_16x16x32_bf16 v[28:31], v[112:115], v[178:181], v[28:31]
	v_mfma_f32_16x16x32_bf16 v[20:23], v[140:143], v[178:181], v[20:23]
	v_mfma_f32_16x16x32_bf16 v[12:15], v[112:115], v[186:189], v[12:15]
	v_mfma_f32_16x16x32_bf16 v[4:7], v[140:143], v[186:189], v[4:7]
	s_barrier
	s_setprio 0
	s_add_u32 s6, s8, 0x10000
	s_addc_u32 s7, s9, 0
	s_add_i32 s20, s89, s92
	v_lshl_add_u64 v[92:93], s[6:7], 0, v[158:159]
	s_mov_b32 m0, s20
	s_nop 0
	global_load_lds_dwordx4 v[92:93], off
	v_lshl_add_u64 v[92:93], s[6:7], 0, v[162:163]
	s_add_i32 m0, s20, 0x2000
	s_nop 0
	global_load_lds_dwordx4 v[92:93], off
	s_waitcnt vmcnt(6)
	s_setprio 1
	s_barrier
	v_mfma_f32_16x16x32_bf16 v[56:59], v[190:193], v[144:147], v[56:59]
	v_mfma_f32_16x16x32_bf16 v[48:51], v[198:201], v[144:147], v[48:51]
	v_mfma_f32_16x16x32_bf16 v[40:43], v[190:193], v[152:155], v[40:43]
	v_mfma_f32_16x16x32_bf16 v[32:35], v[198:201], v[152:155], v[32:35]
	v_mfma_f32_16x16x32_bf16 v[24:27], v[190:193], v[174:177], v[24:27]
	v_mfma_f32_16x16x32_bf16 v[16:19], v[198:201], v[174:177], v[16:19]
	v_mfma_f32_16x16x32_bf16 v[8:11], v[190:193], v[182:185], v[8:11]
	v_mfma_f32_16x16x32_bf16 v[0:3], v[198:201], v[182:185], v[0:3]
	v_mfma_f32_16x16x32_bf16 v[56:59], v[194:197], v[148:151], v[56:59]
	v_mfma_f32_16x16x32_bf16 v[48:51], v[202:205], v[148:151], v[48:51]
	v_mfma_f32_16x16x32_bf16 v[40:43], v[194:197], v[170:173], v[40:43]
	v_mfma_f32_16x16x32_bf16 v[32:35], v[202:205], v[170:173], v[32:35]
	v_mfma_f32_16x16x32_bf16 v[24:27], v[194:197], v[178:181], v[24:27]
	v_mfma_f32_16x16x32_bf16 v[16:19], v[202:205], v[178:181], v[16:19]
	v_mfma_f32_16x16x32_bf16 v[8:11], v[194:197], v[186:189], v[8:11]
	v_mfma_f32_16x16x32_bf16 v[0:3], v[202:205], v[186:189], v[0:3]
	s_add_i32 s20, 0, 0x18000
	v_add_u32_e32 v140, s20, v228
	s_barrier
	s_setprio 0
	ds_read_b128 v[92:95], v140
	ds_read_b128 v[112:115], v140 offset:1024
	ds_read_b128 v[132:135], v140 offset:2048
	ds_read_b128 v[140:143], v140 offset:3072
	s_add_u32 s6, s60, 0x2000
	s_addc_u32 s7, s61, 0
	s_mov_b32 m0, s86
	v_lshl_add_u64 v[190:191], s[6:7], 0, v[156:157]
	ds_read_b128 v[144:147], v230 offset:32768
	ds_read_b128 v[148:151], v230 offset:33792
	ds_read_b128 v[152:155], v230 offset:34816
	ds_read_b128 v[170:173], v230 offset:35840
	ds_read_b128 v[174:177], v230 offset:36864
	ds_read_b128 v[178:181], v230 offset:37888
	ds_read_b128 v[182:185], v230 offset:38912
	ds_read_b128 v[186:189], v230 offset:39936
	global_load_lds_dwordx4 v[190:191], off
	v_lshl_add_u64 v[190:191], s[6:7], 0, v[160:161]
	s_mov_b32 m0, s87
	s_nop 0
	global_load_lds_dwordx4 v[190:191], off
	s_waitcnt lgkmcnt(8)
	s_setprio 1
	s_barrier
	s_waitcnt lgkmcnt(0)
	v_mfma_f32_16x16x32_bf16 v[136:139], v[92:95], v[144:147], v[136:139]
	v_mfma_f32_16x16x32_bf16 v[124:127], v[132:135], v[144:147], v[124:127]
	v_mfma_f32_16x16x32_bf16 v[116:119], v[92:95], v[152:155], v[116:119]
	v_mfma_f32_16x16x32_bf16 v[104:107], v[132:135], v[152:155], v[104:107]
	v_mfma_f32_16x16x32_bf16 v[96:99], v[92:95], v[174:177], v[96:99]
	v_mfma_f32_16x16x32_bf16 v[84:87], v[132:135], v[174:177], v[84:87]
	v_mfma_f32_16x16x32_bf16 v[76:79], v[92:95], v[182:185], v[76:79]
	v_mfma_f32_16x16x32_bf16 v[68:71], v[132:135], v[182:185], v[68:71]
	v_mfma_f32_16x16x32_bf16 v[136:139], v[112:115], v[148:151], v[136:139]
	v_mfma_f32_16x16x32_bf16 v[124:127], v[140:143], v[148:151], v[124:127]
	v_mfma_f32_16x16x32_bf16 v[116:119], v[112:115], v[170:173], v[116:119]
	v_mfma_f32_16x16x32_bf16 v[104:107], v[140:143], v[170:173], v[104:107]
	v_mfma_f32_16x16x32_bf16 v[96:99], v[112:115], v[178:181], v[96:99]
	v_mfma_f32_16x16x32_bf16 v[84:87], v[140:143], v[178:181], v[84:87]
	v_mfma_f32_16x16x32_bf16 v[76:79], v[112:115], v[186:189], v[76:79]
	v_mfma_f32_16x16x32_bf16 v[68:71], v[140:143], v[186:189], v[68:71]
	s_barrier
	s_setprio 0
	s_add_i32 s21, 0, 0x1c000
	s_add_i32 s6, s20, s92
	v_add_u32_e32 v164, s21, v228
	v_lshl_add_u64 v[206:207], v[206:207], 0, s[42:43]
	s_mov_b32 m0, s6
	ds_read_b128 v[190:193], v164
	ds_read_b128 v[194:197], v164 offset:1024
	ds_read_b128 v[198:201], v164 offset:2048
	ds_read_b128 v[202:205], v164 offset:3072
	global_load_lds_dwordx4 v[206:207], off
	v_lshl_add_u64 v[206:207], v[208:209], 0, s[42:43]
	s_add_i32 m0, s6, 0x2000
	s_nop 0
	global_load_lds_dwordx4 v[206:207], off
	s_waitcnt lgkmcnt(0)
	s_setprio 1
	s_barrier
	v_mfma_f32_16x16x32_bf16 v[128:131], v[190:193], v[144:147], v[128:131]
	v_mfma_f32_16x16x32_bf16 v[120:123], v[198:201], v[144:147], v[120:123]
	v_mfma_f32_16x16x32_bf16 v[108:111], v[190:193], v[152:155], v[108:111]
	v_mfma_f32_16x16x32_bf16 v[100:103], v[198:201], v[152:155], v[100:103]
	v_mfma_f32_16x16x32_bf16 v[88:91], v[190:193], v[174:177], v[88:91]
	v_mfma_f32_16x16x32_bf16 v[80:83], v[198:201], v[174:177], v[80:83]
	v_mfma_f32_16x16x32_bf16 v[72:75], v[190:193], v[182:185], v[72:75]
	v_mfma_f32_16x16x32_bf16 v[64:67], v[198:201], v[182:185], v[64:67]
	v_mfma_f32_16x16x32_bf16 v[128:131], v[194:197], v[148:151], v[128:131]
	v_mfma_f32_16x16x32_bf16 v[120:123], v[202:205], v[148:151], v[120:123]
	v_mfma_f32_16x16x32_bf16 v[108:111], v[194:197], v[170:173], v[108:111]
	v_mfma_f32_16x16x32_bf16 v[100:103], v[202:205], v[170:173], v[100:103]
	v_mfma_f32_16x16x32_bf16 v[88:91], v[194:197], v[178:181], v[88:91]
	v_mfma_f32_16x16x32_bf16 v[80:83], v[202:205], v[178:181], v[80:83]
	v_mfma_f32_16x16x32_bf16 v[72:75], v[194:197], v[186:189], v[72:75]
	v_mfma_f32_16x16x32_bf16 v[64:67], v[202:205], v[186:189], v[64:67]
	s_mov_b32 m0, s97
	v_lshl_add_u64 v[206:207], v[210:211], 0, s[42:43]
	s_barrier
	s_setprio 0
	ds_read_b128 v[144:147], v230 offset:49152
	ds_read_b128 v[148:151], v230 offset:50176
	ds_read_b128 v[152:155], v230 offset:51200
	ds_read_b128 v[170:173], v230 offset:52224
	ds_read_b128 v[174:177], v230 offset:53248
	ds_read_b128 v[178:181], v230 offset:54272
	ds_read_b128 v[182:185], v230 offset:55296
	ds_read_b128 v[186:189], v230 offset:56320
	global_load_lds_dwordx4 v[206:207], off
	v_lshl_add_u64 v[206:207], v[212:213], 0, s[42:43]
	s_mov_b32 m0, s18
	s_nop 0
	global_load_lds_dwordx4 v[206:207], off
	s_waitcnt lgkmcnt(0)
	s_setprio 1
	s_barrier
	v_mfma_f32_16x16x32_bf16 v[60:63], v[92:95], v[144:147], v[60:63]
	v_mfma_f32_16x16x32_bf16 v[52:55], v[132:135], v[144:147], v[52:55]
	v_mfma_f32_16x16x32_bf16 v[44:47], v[92:95], v[152:155], v[44:47]
	v_mfma_f32_16x16x32_bf16 v[36:39], v[132:135], v[152:155], v[36:39]
	v_mfma_f32_16x16x32_bf16 v[28:31], v[92:95], v[174:177], v[28:31]
	v_mfma_f32_16x16x32_bf16 v[20:23], v[132:135], v[174:177], v[20:23]
	v_mfma_f32_16x16x32_bf16 v[12:15], v[92:95], v[182:185], v[12:15]
	v_mfma_f32_16x16x32_bf16 v[4:7], v[132:135], v[182:185], v[4:7]
	v_mfma_f32_16x16x32_bf16 v[60:63], v[112:115], v[148:151], v[60:63]
	v_mfma_f32_16x16x32_bf16 v[52:55], v[140:143], v[148:151], v[52:55]
	v_mfma_f32_16x16x32_bf16 v[44:47], v[112:115], v[170:173], v[44:47]
	v_mfma_f32_16x16x32_bf16 v[36:39], v[140:143], v[170:173], v[36:39]
	v_mfma_f32_16x16x32_bf16 v[28:31], v[112:115], v[178:181], v[28:31]
	v_mfma_f32_16x16x32_bf16 v[20:23], v[140:143], v[178:181], v[20:23]
	v_mfma_f32_16x16x32_bf16 v[12:15], v[112:115], v[186:189], v[12:15]
	v_mfma_f32_16x16x32_bf16 v[4:7], v[140:143], v[186:189], v[4:7]
	s_barrier
	s_setprio 0
	s_add_u32 s6, s8, 0x10080
	s_addc_u32 s7, s9, 0
	s_add_i32 s8, s21, s92
	v_lshl_add_u64 v[92:93], s[6:7], 0, v[158:159]
	s_mov_b32 m0, s8
	s_nop 0
	global_load_lds_dwordx4 v[92:93], off
	v_lshl_add_u64 v[92:93], s[6:7], 0, v[162:163]
	s_add_i32 m0, s8, 0x2000
	s_nop 0
	global_load_lds_dwordx4 v[92:93], off
	s_waitcnt vmcnt(6)
	s_setprio 1
	s_barrier
	v_mfma_f32_16x16x32_bf16 v[56:59], v[190:193], v[144:147], v[56:59]
	v_mfma_f32_16x16x32_bf16 v[48:51], v[198:201], v[144:147], v[48:51]
	v_mfma_f32_16x16x32_bf16 v[40:43], v[190:193], v[152:155], v[40:43]
	v_mfma_f32_16x16x32_bf16 v[32:35], v[198:201], v[152:155], v[32:35]
	v_mfma_f32_16x16x32_bf16 v[24:27], v[190:193], v[174:177], v[24:27]
	v_mfma_f32_16x16x32_bf16 v[16:19], v[198:201], v[174:177], v[16:19]
	v_mfma_f32_16x16x32_bf16 v[8:11], v[190:193], v[182:185], v[8:11]
	v_mfma_f32_16x16x32_bf16 v[0:3], v[198:201], v[182:185], v[0:3]
	v_mfma_f32_16x16x32_bf16 v[56:59], v[194:197], v[148:151], v[56:59]
	v_mfma_f32_16x16x32_bf16 v[48:51], v[202:205], v[148:151], v[48:51]
	v_mfma_f32_16x16x32_bf16 v[40:43], v[194:197], v[170:173], v[40:43]
	v_mfma_f32_16x16x32_bf16 v[32:35], v[202:205], v[170:173], v[32:35]
	v_mfma_f32_16x16x32_bf16 v[24:27], v[194:197], v[178:181], v[24:27]
	v_mfma_f32_16x16x32_bf16 v[16:19], v[202:205], v[178:181], v[16:19]
	v_mfma_f32_16x16x32_bf16 v[8:11], v[194:197], v[186:189], v[8:11]
	v_mfma_f32_16x16x32_bf16 v[0:3], v[202:205], v[186:189], v[0:3]
	s_add_u32 s64, s64, 0x100
	s_addc_u32 s65, s65, 0
	s_cmp_lt_i32 s66, s95
	s_mov_b64 s[6:7], s[4:5]
	s_mov_b32 s8, s66
	s_barrier
	s_setprio 0
	s_cbranch_scc1 .LBB0_461

.Lpz_P8:
	s_and_b64 s[12:13], s[12:13], exec
	s_cselect_b32 s3, s61, s67
	s_cselect_b32 s15, s60, s66
	s_cselect_b32 s16, s63, s65
	s_cselect_b32 s17, s62, s64
	s_add_u32 s12, s66, 0x40080
	s_addc_u32 s13, s67, 0
	s_add_u32 s18, s64, 0x100
	s_addc_u32 s19, s65, 0
	s_mov_b32 s57, 0
	ds_read_b128 v[0:3], v233
	ds_read_b128 v[4:7], v233 offset:1024
	ds_read_b128 v[8:11], v233 offset:2048
	ds_read_b128 v[12:15], v233 offset:3072
	s_add_i32 s59, s57, 2
	s_add_u32 s20, s12, 0xfffc0080
	s_addc_u32 s21, s13, -1
	s_cmp_eq_u32 s97, s57
	s_cselect_b32 s67, s3, s21
	s_cselect_b32 s66, s15, s20
	s_cselect_b32 s65, s16, s19
	s_cselect_b32 s64, s17, s18
	v_lshl_add_u64 v[190:191], s[12:13], 0, v[164:165]
	s_add_i32 m0, s74, 0xc000
	ds_read_b128 v[80:83], v234
	ds_read_b128 v[84:87], v234 offset:1024
	ds_read_b128 v[88:91], v234 offset:2048
	ds_read_b128 v[92:95], v234 offset:3072
	ds_read_b128 v[174:177], v234 offset:4096
	ds_read_b128 v[178:181], v234 offset:5120
	ds_read_b128 v[182:185], v234 offset:6144
	ds_read_b128 v[186:189], v234 offset:7168
	global_load_lds_dwordx4 v[190:191], off
	v_lshl_add_u64 v[190:191], s[12:13], 0, v[166:167]
	s_add_i32 m0, s74, 0xe000
	s_nop 0
	global_load_lds_dwordx4 v[190:191], off
	s_waitcnt lgkmcnt(8)
	s_setprio 1
	s_barrier
	s_waitcnt lgkmcnt(0)
	v_mfma_f32_16x16x32_bf16 v[156:159], v[0:3], v[80:83], 0
	v_mfma_f32_16x16x32_bf16 v[152:155], v[8:11], v[80:83], 0
	v_mfma_f32_16x16x32_bf16 v[140:143], v[0:3], v[88:91], 0
	v_mfma_f32_16x16x32_bf16 v[136:139], v[8:11], v[88:91], 0
	v_mfma_f32_16x16x32_bf16 v[124:127], v[0:3], v[174:177], 0
	v_mfma_f32_16x16x32_bf16 v[120:123], v[8:11], v[174:177], 0
	v_mfma_f32_16x16x32_bf16 v[108:111], v[0:3], v[182:185], 0
	v_mfma_f32_16x16x32_bf16 v[104:107], v[8:11], v[182:185], 0
	v_mfma_f32_16x16x32_bf16 v[156:159], v[4:7], v[84:87], v[156:159]
	v_mfma_f32_16x16x32_bf16 v[152:155], v[12:15], v[84:87], v[152:155]
	v_mfma_f32_16x16x32_bf16 v[140:143], v[4:7], v[92:95], v[140:143]
	v_mfma_f32_16x16x32_bf16 v[136:139], v[12:15], v[92:95], v[136:139]
	v_mfma_f32_16x16x32_bf16 v[124:127], v[4:7], v[178:181], v[124:127]
	v_mfma_f32_16x16x32_bf16 v[120:123], v[12:15], v[178:181], v[120:123]
	v_mfma_f32_16x16x32_bf16 v[108:111], v[4:7], v[186:189], v[108:111]
	v_mfma_f32_16x16x32_bf16 v[104:107], v[12:15], v[186:189], v[104:107]
	s_barrier
	s_setprio 0
	s_add_i32 s20, s88, s73
	v_lshl_add_u64 v[214:215], s[64:65], 0, v[160:161]
	s_mov_b32 m0, s20
	ds_read_b128 v[190:193], v235
	ds_read_b128 v[194:197], v235 offset:1024
	ds_read_b128 v[198:201], v235 offset:2048
	ds_read_b128 v[202:205], v235 offset:3072
	global_load_lds_dwordx4 v[214:215], off
	v_lshl_add_u64 v[216:217], s[64:65], 0, v[162:163]
	s_add_i32 m0, s20, 0x2000
	s_nop 0
	global_load_lds_dwordx4 v[216:217], off
	s_waitcnt lgkmcnt(0)
	s_setprio 1
	s_barrier
	v_mfma_f32_16x16x32_bf16 v[148:151], v[190:193], v[80:83], 0
	v_mfma_f32_16x16x32_bf16 v[80:83], v[198:201], v[80:83], 0
	v_mfma_f32_16x16x32_bf16 v[148:151], v[194:197], v[84:87], v[148:151]
	v_mfma_f32_16x16x32_bf16 v[80:83], v[202:205], v[84:87], v[80:83]
	v_mfma_f32_16x16x32_bf16 v[84:87], v[190:193], v[88:91], 0
	v_mfma_f32_16x16x32_bf16 v[88:91], v[198:201], v[88:91], 0
	v_mfma_f32_16x16x32_bf16 v[112:115], v[198:201], v[174:177], 0
	v_mfma_f32_16x16x32_bf16 v[100:103], v[190:193], v[182:185], 0
	v_mfma_f32_16x16x32_bf16 v[96:99], v[198:201], v[182:185], 0
	v_mfma_f32_16x16x32_bf16 v[84:87], v[194:197], v[92:95], v[84:87]
	v_mfma_f32_16x16x32_bf16 v[88:91], v[202:205], v[92:95], v[88:91]
	v_mfma_f32_16x16x32_bf16 v[92:95], v[190:193], v[174:177], 0
	v_mfma_f32_16x16x32_bf16 v[112:115], v[202:205], v[178:181], v[112:115]
	v_mfma_f32_16x16x32_bf16 v[100:103], v[194:197], v[186:189], v[100:103]
	v_mfma_f32_16x16x32_bf16 v[96:99], v[202:205], v[186:189], v[96:99]
	v_mfma_f32_16x16x32_bf16 v[92:95], v[194:197], v[178:181], v[92:95]
	s_mov_b32 m0, s74
	v_lshl_add_u64 v[218:219], s[66:67], 0, v[160:161]
	s_barrier
	s_setprio 0
	ds_read_b128 v[116:119], v234 offset:16384
	ds_read_b128 v[128:131], v234 offset:17408
	ds_read_b128 v[132:135], v234 offset:18432
	ds_read_b128 v[144:147], v234 offset:19456
	ds_read_b128 v[174:177], v234 offset:20480
	ds_read_b128 v[178:181], v234 offset:21504
	ds_read_b128 v[182:185], v234 offset:22528
	ds_read_b128 v[186:189], v234 offset:23552
	global_load_lds_dwordx4 v[218:219], off
	v_lshl_add_u64 v[220:221], s[66:67], 0, v[162:163]
	s_mov_b32 m0, s75
	s_nop 0
	global_load_lds_dwordx4 v[220:221], off
	s_waitcnt lgkmcnt(0)
	s_setprio 1
	s_barrier
	v_mfma_f32_16x16x32_bf16 v[76:79], v[0:3], v[116:119], 0
	v_mfma_f32_16x16x32_bf16 v[72:75], v[8:11], v[116:119], 0
	v_mfma_f32_16x16x32_bf16 v[60:63], v[0:3], v[132:135], 0
	v_mfma_f32_16x16x32_bf16 v[56:59], v[8:11], v[132:135], 0
	v_mfma_f32_16x16x32_bf16 v[44:47], v[0:3], v[174:177], 0
	v_mfma_f32_16x16x32_bf16 v[40:43], v[8:11], v[174:177], 0
	v_mfma_f32_16x16x32_bf16 v[0:3], v[0:3], v[182:185], 0
	v_mfma_f32_16x16x32_bf16 v[76:79], v[4:7], v[128:131], v[76:79]
	v_mfma_f32_16x16x32_bf16 v[72:75], v[12:15], v[128:131], v[72:75]
	v_mfma_f32_16x16x32_bf16 v[60:63], v[4:7], v[144:147], v[60:63]
	v_mfma_f32_16x16x32_bf16 v[56:59], v[12:15], v[144:147], v[56:59]
	v_mfma_f32_16x16x32_bf16 v[44:47], v[4:7], v[178:181], v[44:47]
	v_mfma_f32_16x16x32_bf16 v[40:43], v[12:15], v[178:181], v[40:43]
	v_mfma_f32_16x16x32_bf16 v[0:3], v[4:7], v[186:189], v[0:3]
	v_mfma_f32_16x16x32_bf16 v[4:7], v[8:11], v[182:185], 0
	v_mfma_f32_16x16x32_bf16 v[4:7], v[12:15], v[186:189], v[4:7]
	s_barrier
	s_setprio 0
	s_add_u32 s20, s64, 0x40000
	s_addc_u32 s21, s65, 0
	s_add_i32 s57, s89, s73
	v_lshl_add_u64 v[8:9], s[20:21], 0, v[160:161]
	s_mov_b32 m0, s57
	s_nop 0
	global_load_lds_dwordx4 v[8:9], off
	v_lshl_add_u64 v[8:9], s[20:21], 0, v[162:163]
	s_add_i32 m0, s57, 0x2000
	s_nop 0
	global_load_lds_dwordx4 v[8:9], off
	s_waitcnt vmcnt(6)
	s_setprio 1
	s_barrier
	v_mfma_f32_16x16x32_bf16 v[24:27], v[190:193], v[132:135], 0
	v_mfma_f32_16x16x32_bf16 v[52:55], v[194:197], v[144:147], v[24:27]
	v_mfma_f32_16x16x32_bf16 v[24:27], v[198:201], v[132:135], 0
	v_mfma_f32_16x16x32_bf16 v[48:51], v[202:205], v[144:147], v[24:27]
	v_mfma_f32_16x16x32_bf16 v[24:27], v[190:193], v[174:177], 0
	v_mfma_f32_16x16x32_bf16 v[36:39], v[194:197], v[178:181], v[24:27]
	v_mfma_f32_16x16x32_bf16 v[24:27], v[198:201], v[174:177], 0
	v_mfma_f32_16x16x32_bf16 v[20:23], v[190:193], v[182:185], 0
	v_mfma_f32_16x16x32_bf16 v[16:19], v[198:201], v[182:185], 0
	v_mfma_f32_16x16x32_bf16 v[8:11], v[190:193], v[116:119], 0
	v_mfma_f32_16x16x32_bf16 v[12:15], v[198:201], v[116:119], 0
	v_mfma_f32_16x16x32_bf16 v[32:35], v[202:205], v[178:181], v[24:27]
	v_mfma_f32_16x16x32_bf16 v[20:23], v[194:197], v[186:189], v[20:23]
	v_mfma_f32_16x16x32_bf16 v[16:19], v[202:205], v[186:189], v[16:19]
	v_mfma_f32_16x16x32_bf16 v[8:11], v[194:197], v[128:131], v[8:11]
	v_mfma_f32_16x16x32_bf16 v[12:15], v[202:205], v[128:131], v[12:15]
	s_add_i32 s57, 0, 0x18000
	v_add_u32_e32 v68, s57, v228
	s_barrier
	s_setprio 0
	ds_read_b128 v[24:27], v68
	ds_read_b128 v[28:31], v68 offset:1024
	ds_read_b128 v[64:67], v68 offset:2048
	ds_read_b128 v[68:71], v68 offset:3072
	s_add_u32 s20, s66, 0x40000
	s_addc_u32 s21, s67, 0
	s_mov_b32 m0, s76
	v_lshl_add_u64 v[132:133], s[20:21], 0, v[160:161]
	ds_read_b128 v[116:119], v234 offset:32768
	ds_read_b128 v[128:131], v234 offset:33792
	ds_read_b128 v[174:177], v234 offset:34816
	ds_read_b128 v[178:181], v234 offset:35840
	ds_read_b128 v[182:185], v234 offset:36864
	ds_read_b128 v[186:189], v234 offset:37888
	ds_read_b128 v[190:193], v234 offset:38912
	ds_read_b128 v[194:197], v234 offset:39936
	global_load_lds_dwordx4 v[132:133], off
	v_lshl_add_u64 v[132:133], s[20:21], 0, v[162:163]
	s_mov_b32 m0, s77
	s_nop 0
	global_load_lds_dwordx4 v[132:133], off
	s_waitcnt lgkmcnt(8)
	s_setprio 1
	s_barrier
	s_waitcnt lgkmcnt(0)
	v_mfma_f32_16x16x32_bf16 v[132:135], v[24:27], v[116:119], v[156:159]
	v_mfma_f32_16x16x32_bf16 v[156:159], v[28:31], v[128:131], v[132:135]
	v_mfma_f32_16x16x32_bf16 v[132:135], v[64:67], v[116:119], v[152:155]
	v_mfma_f32_16x16x32_bf16 v[152:155], v[68:71], v[128:131], v[132:135]
	v_mfma_f32_16x16x32_bf16 v[132:135], v[24:27], v[174:177], v[140:143]
	v_mfma_f32_16x16x32_bf16 v[140:143], v[28:31], v[178:181], v[132:135]
	v_mfma_f32_16x16x32_bf16 v[132:135], v[64:67], v[174:177], v[136:139]
	v_mfma_f32_16x16x32_bf16 v[124:127], v[24:27], v[182:185], v[124:127]
	v_mfma_f32_16x16x32_bf16 v[120:123], v[64:67], v[182:185], v[120:123]
	v_mfma_f32_16x16x32_bf16 v[108:111], v[24:27], v[190:193], v[108:111]
	v_mfma_f32_16x16x32_bf16 v[104:107], v[64:67], v[190:193], v[104:107]
	v_mfma_f32_16x16x32_bf16 v[136:139], v[68:71], v[178:181], v[132:135]
	v_mfma_f32_16x16x32_bf16 v[124:127], v[28:31], v[186:189], v[124:127]
	v_mfma_f32_16x16x32_bf16 v[120:123], v[68:71], v[186:189], v[120:123]
	v_mfma_f32_16x16x32_bf16 v[108:111], v[28:31], v[194:197], v[108:111]
	v_mfma_f32_16x16x32_bf16 v[104:107], v[68:71], v[194:197], v[104:107]
	s_barrier
	s_setprio 0
	s_add_i32 s66, 0, 0x1c000
	v_add_u32_e32 v132, s66, v228
	s_add_i32 s20, s57, s73
	ds_read_b128 v[198:201], v132
	ds_read_b128 v[202:205], v132 offset:1024
	ds_read_b128 v[206:209], v132 offset:2048
	ds_read_b128 v[210:213], v132 offset:3072
	v_lshl_add_u64 v[132:133], v[214:215], 0, s[44:45]
	s_mov_b32 m0, s20
	s_nop 0
	global_load_lds_dwordx4 v[132:133], off
	v_lshl_add_u64 v[132:133], v[216:217], 0, s[44:45]
	s_add_i32 m0, s20, 0x2000
	s_nop 0
	global_load_lds_dwordx4 v[132:133], off
	s_waitcnt lgkmcnt(0)
	s_setprio 1
	s_barrier
	v_mfma_f32_16x16x32_bf16 v[80:83], v[206:209], v[116:119], v[80:83]
	v_mfma_f32_16x16x32_bf16 v[132:135], v[198:201], v[116:119], v[148:151]
	v_mfma_f32_16x16x32_bf16 v[144:147], v[210:213], v[128:131], v[80:83]
	v_mfma_f32_16x16x32_bf16 v[80:83], v[198:201], v[174:177], v[84:87]
	v_mfma_f32_16x16x32_bf16 v[148:151], v[202:205], v[128:131], v[132:135]
	v_mfma_f32_16x16x32_bf16 v[132:135], v[202:205], v[178:181], v[80:83]
	v_mfma_f32_16x16x32_bf16 v[80:83], v[206:209], v[174:177], v[88:91]
	v_mfma_f32_16x16x32_bf16 v[128:131], v[210:213], v[178:181], v[80:83]
	v_mfma_f32_16x16x32_bf16 v[80:83], v[198:201], v[182:185], v[92:95]
	v_mfma_f32_16x16x32_bf16 v[116:119], v[202:205], v[186:189], v[80:83]
	v_mfma_f32_16x16x32_bf16 v[80:83], v[206:209], v[182:185], v[112:115]
	v_mfma_f32_16x16x32_bf16 v[112:115], v[210:213], v[186:189], v[80:83]
	v_mfma_f32_16x16x32_bf16 v[80:83], v[198:201], v[190:193], v[100:103]
	v_mfma_f32_16x16x32_bf16 v[100:103], v[202:205], v[194:197], v[80:83]
	v_mfma_f32_16x16x32_bf16 v[80:83], v[206:209], v[190:193], v[96:99]
	v_mfma_f32_16x16x32_bf16 v[96:99], v[210:213], v[194:197], v[80:83]
	s_mov_b32 m0, s95
	v_lshl_add_u64 v[190:191], v[218:219], 0, s[44:45]
	s_barrier
	s_setprio 0
	s_nop 2
	ds_read_b128 v[80:83], v234 offset:49152
	ds_read_b128 v[84:87], v234 offset:50176
	ds_read_b128 v[88:91], v234 offset:51200
	ds_read_b128 v[92:95], v234 offset:52224
	ds_read_b128 v[174:177], v234 offset:53248
	ds_read_b128 v[178:181], v234 offset:54272
	ds_read_b128 v[182:185], v234 offset:55296
	ds_read_b128 v[186:189], v234 offset:56320
	global_load_lds_dwordx4 v[190:191], off
	v_lshl_add_u64 v[190:191], v[220:221], 0, s[44:45]
	s_mov_b32 m0, s96
	s_nop 0
	global_load_lds_dwordx4 v[190:191], off
	s_waitcnt lgkmcnt(0)
	s_setprio 1
	s_barrier
	v_mfma_f32_16x16x32_bf16 v[76:79], v[24:27], v[80:83], v[76:79]
	v_mfma_f32_16x16x32_bf16 v[60:63], v[24:27], v[88:91], v[60:63]
	v_mfma_f32_16x16x32_bf16 v[44:47], v[24:27], v[174:177], v[44:47]
	v_mfma_f32_16x16x32_bf16 v[0:3], v[24:27], v[182:185], v[0:3]
	v_mfma_f32_16x16x32_bf16 v[76:79], v[28:31], v[84:87], v[76:79]
	v_mfma_f32_16x16x32_bf16 v[72:75], v[64:67], v[80:83], v[72:75]
	v_mfma_f32_16x16x32_bf16 v[60:63], v[28:31], v[92:95], v[60:63]
	v_mfma_f32_16x16x32_bf16 v[56:59], v[64:67], v[88:91], v[56:59]
	v_mfma_f32_16x16x32_bf16 v[44:47], v[28:31], v[178:181], v[44:47]
	v_mfma_f32_16x16x32_bf16 v[40:43], v[64:67], v[174:177], v[40:43]
	v_mfma_f32_16x16x32_bf16 v[28:31], v[28:31], v[186:189], v[0:3]
	v_mfma_f32_16x16x32_bf16 v[0:3], v[64:67], v[182:185], v[4:7]
	v_mfma_f32_16x16x32_bf16 v[72:75], v[68:71], v[84:87], v[72:75]
	v_mfma_f32_16x16x32_bf16 v[56:59], v[68:71], v[92:95], v[56:59]
	v_mfma_f32_16x16x32_bf16 v[40:43], v[68:71], v[178:181], v[40:43]
	v_mfma_f32_16x16x32_bf16 v[24:27], v[68:71], v[186:189], v[0:3]
	s_barrier
	s_setprio 0
	s_add_u32 s20, s64, 0x40080
	s_addc_u32 s21, s65, 0
	s_add_i32 s57, s66, s73
	v_lshl_add_u64 v[0:1], s[20:21], 0, v[160:161]
	s_mov_b32 m0, s57
	s_nop 0
	global_load_lds_dwordx4 v[0:1], off
	v_lshl_add_u64 v[0:1], s[20:21], 0, v[162:163]
	s_add_i32 m0, s57, 0x2000
	s_nop 0
	global_load_lds_dwordx4 v[0:1], off
	s_waitcnt vmcnt(6)
	s_setprio 1
	s_barrier
	v_mfma_f32_16x16x32_bf16 v[0:3], v[198:201], v[80:83], v[8:11]
	v_mfma_f32_16x16x32_bf16 v[68:71], v[202:205], v[84:87], v[0:3]
	v_mfma_f32_16x16x32_bf16 v[0:3], v[206:209], v[80:83], v[12:15]
	v_mfma_f32_16x16x32_bf16 v[64:67], v[210:213], v[84:87], v[0:3]
	v_mfma_f32_16x16x32_bf16 v[0:3], v[198:201], v[88:91], v[52:55]
	v_mfma_f32_16x16x32_bf16 v[52:55], v[202:205], v[92:95], v[0:3]
	v_mfma_f32_16x16x32_bf16 v[0:3], v[206:209], v[88:91], v[48:51]
	v_mfma_f32_16x16x32_bf16 v[48:51], v[210:213], v[92:95], v[0:3]
	v_mfma_f32_16x16x32_bf16 v[0:3], v[198:201], v[174:177], v[36:39]
	v_mfma_f32_16x16x32_bf16 v[36:39], v[202:205], v[178:181], v[0:3]
	v_mfma_f32_16x16x32_bf16 v[0:3], v[206:209], v[174:177], v[32:35]
	v_mfma_f32_16x16x32_bf16 v[32:35], v[210:213], v[178:181], v[0:3]
	v_mfma_f32_16x16x32_bf16 v[0:3], v[198:201], v[182:185], v[20:23]
	v_mfma_f32_16x16x32_bf16 v[20:23], v[202:205], v[186:189], v[0:3]
	v_mfma_f32_16x16x32_bf16 v[0:3], v[206:209], v[182:185], v[16:19]
	v_mfma_f32_16x16x32_bf16 v[16:19], v[210:213], v[186:189], v[0:3]
	s_add_u32 s12, s12, 0x100
	s_addc_u32 s13, s13, 0
	s_add_u32 s18, s18, 0x100
	s_addc_u32 s19, s19, 0
	s_cmp_lt_i32 s59, s93
	s_mov_b32 s57, s59
	s_barrier
	s_setprio 0
	s_cbranch_scc0 .Lpeel_done_P8
.LBB0_605:
	ds_read_b128 v[0:3], v233
	ds_read_b128 v[4:7], v233 offset:1024
	ds_read_b128 v[8:11], v233 offset:2048
	ds_read_b128 v[12:15], v233 offset:3072
	s_add_i32 s59, s57, 2
	s_add_u32 s20, s12, 0xfffc0080
	s_addc_u32 s21, s13, -1
	s_cmp_eq_u32 s97, s57
	s_cselect_b32 s67, s3, s21
	s_cselect_b32 s66, s15, s20
	s_cselect_b32 s65, s16, s19
	s_cselect_b32 s64, s17, s18
	v_lshl_add_u64 v[190:191], s[12:13], 0, v[164:165]
	s_add_i32 m0, s74, 0xc000
	ds_read_b128 v[80:83], v234
	ds_read_b128 v[84:87], v234 offset:1024
	ds_read_b128 v[88:91], v234 offset:2048
	ds_read_b128 v[92:95], v234 offset:3072
	ds_read_b128 v[174:177], v234 offset:4096
	ds_read_b128 v[178:181], v234 offset:5120
	ds_read_b128 v[182:185], v234 offset:6144
	ds_read_b128 v[186:189], v234 offset:7168
	global_load_lds_dwordx4 v[190:191], off
	v_lshl_add_u64 v[190:191], s[12:13], 0, v[166:167]
	s_add_i32 m0, s74, 0xe000
	s_nop 0
	global_load_lds_dwordx4 v[190:191], off
	s_waitcnt lgkmcnt(8)
	s_setprio 1
	s_barrier
	s_waitcnt lgkmcnt(0)
	v_mfma_f32_16x16x32_bf16 v[156:159], v[0:3], v[80:83], v[156:159]
	v_mfma_f32_16x16x32_bf16 v[152:155], v[8:11], v[80:83], v[152:155]
	v_mfma_f32_16x16x32_bf16 v[140:143], v[0:3], v[88:91], v[140:143]
	v_mfma_f32_16x16x32_bf16 v[136:139], v[8:11], v[88:91], v[136:139]
	v_mfma_f32_16x16x32_bf16 v[124:127], v[0:3], v[174:177], v[124:127]
	v_mfma_f32_16x16x32_bf16 v[120:123], v[8:11], v[174:177], v[120:123]
	v_mfma_f32_16x16x32_bf16 v[108:111], v[0:3], v[182:185], v[108:111]
	v_mfma_f32_16x16x32_bf16 v[104:107], v[8:11], v[182:185], v[104:107]
	v_mfma_f32_16x16x32_bf16 v[156:159], v[4:7], v[84:87], v[156:159]
	v_mfma_f32_16x16x32_bf16 v[152:155], v[12:15], v[84:87], v[152:155]
	v_mfma_f32_16x16x32_bf16 v[140:143], v[4:7], v[92:95], v[140:143]
	v_mfma_f32_16x16x32_bf16 v[136:139], v[12:15], v[92:95], v[136:139]
	v_mfma_f32_16x16x32_bf16 v[124:127], v[4:7], v[178:181], v[124:127]
	v_mfma_f32_16x16x32_bf16 v[120:123], v[12:15], v[178:181], v[120:123]
	v_mfma_f32_16x16x32_bf16 v[108:111], v[4:7], v[186:189], v[108:111]
	v_mfma_f32_16x16x32_bf16 v[104:107], v[12:15], v[186:189], v[104:107]
	s_barrier
	s_setprio 0
	s_add_i32 s20, s88, s73
	v_lshl_add_u64 v[214:215], s[64:65], 0, v[160:161]
	s_mov_b32 m0, s20
	ds_read_b128 v[190:193], v235
	ds_read_b128 v[194:197], v235 offset:1024
	ds_read_b128 v[198:201], v235 offset:2048
	ds_read_b128 v[202:205], v235 offset:3072
	global_load_lds_dwordx4 v[214:215], off
	v_lshl_add_u64 v[216:217], s[64:65], 0, v[162:163]
	s_add_i32 m0, s20, 0x2000
	s_nop 0
	global_load_lds_dwordx4 v[216:217], off
	s_waitcnt lgkmcnt(0)
	s_setprio 1
	s_barrier
	v_mfma_f32_16x16x32_bf16 v[148:151], v[190:193], v[80:83], v[148:151]
	v_mfma_f32_16x16x32_bf16 v[80:83], v[198:201], v[80:83], v[144:147]
	v_mfma_f32_16x16x32_bf16 v[148:151], v[194:197], v[84:87], v[148:151]
	v_mfma_f32_16x16x32_bf16 v[80:83], v[202:205], v[84:87], v[80:83]
	v_mfma_f32_16x16x32_bf16 v[84:87], v[190:193], v[88:91], v[132:135]
	v_mfma_f32_16x16x32_bf16 v[88:91], v[198:201], v[88:91], v[128:131]
	v_mfma_f32_16x16x32_bf16 v[112:115], v[198:201], v[174:177], v[112:115]
	v_mfma_f32_16x16x32_bf16 v[100:103], v[190:193], v[182:185], v[100:103]
	v_mfma_f32_16x16x32_bf16 v[96:99], v[198:201], v[182:185], v[96:99]
	v_mfma_f32_16x16x32_bf16 v[84:87], v[194:197], v[92:95], v[84:87]
	v_mfma_f32_16x16x32_bf16 v[88:91], v[202:205], v[92:95], v[88:91]
	v_mfma_f32_16x16x32_bf16 v[92:95], v[190:193], v[174:177], v[116:119]
	v_mfma_f32_16x16x32_bf16 v[112:115], v[202:205], v[178:181], v[112:115]
	v_mfma_f32_16x16x32_bf16 v[100:103], v[194:197], v[186:189], v[100:103]
	v_mfma_f32_16x16x32_bf16 v[96:99], v[202:205], v[186:189], v[96:99]
	v_mfma_f32_16x16x32_bf16 v[92:95], v[194:197], v[178:181], v[92:95]
	s_mov_b32 m0, s74
	v_lshl_add_u64 v[218:219], s[66:67], 0, v[160:161]
	s_barrier
	s_setprio 0
	ds_read_b128 v[116:119], v234 offset:16384
	ds_read_b128 v[128:131], v234 offset:17408
	ds_read_b128 v[132:135], v234 offset:18432
	ds_read_b128 v[144:147], v234 offset:19456
	ds_read_b128 v[174:177], v234 offset:20480
	ds_read_b128 v[178:181], v234 offset:21504
	ds_read_b128 v[182:185], v234 offset:22528
	ds_read_b128 v[186:189], v234 offset:23552
	global_load_lds_dwordx4 v[218:219], off
	v_lshl_add_u64 v[220:221], s[66:67], 0, v[162:163]
	s_mov_b32 m0, s75
	s_nop 0
	global_load_lds_dwordx4 v[220:221], off
	s_waitcnt lgkmcnt(0)
	s_setprio 1
	s_barrier
	v_mfma_f32_16x16x32_bf16 v[76:79], v[0:3], v[116:119], v[76:79]
	v_mfma_f32_16x16x32_bf16 v[72:75], v[8:11], v[116:119], v[72:75]
	v_mfma_f32_16x16x32_bf16 v[60:63], v[0:3], v[132:135], v[60:63]
	v_mfma_f32_16x16x32_bf16 v[56:59], v[8:11], v[132:135], v[56:59]
	v_mfma_f32_16x16x32_bf16 v[44:47], v[0:3], v[174:177], v[44:47]
	v_mfma_f32_16x16x32_bf16 v[40:43], v[8:11], v[174:177], v[40:43]
	v_mfma_f32_16x16x32_bf16 v[0:3], v[0:3], v[182:185], v[28:31]
	v_mfma_f32_16x16x32_bf16 v[76:79], v[4:7], v[128:131], v[76:79]
	v_mfma_f32_16x16x32_bf16 v[72:75], v[12:15], v[128:131], v[72:75]
	v_mfma_f32_16x16x32_bf16 v[60:63], v[4:7], v[144:147], v[60:63]
	v_mfma_f32_16x16x32_bf16 v[56:59], v[12:15], v[144:147], v[56:59]
	v_mfma_f32_16x16x32_bf16 v[44:47], v[4:7], v[178:181], v[44:47]
	v_mfma_f32_16x16x32_bf16 v[40:43], v[12:15], v[178:181], v[40:43]
	v_mfma_f32_16x16x32_bf16 v[0:3], v[4:7], v[186:189], v[0:3]
	v_mfma_f32_16x16x32_bf16 v[4:7], v[8:11], v[182:185], v[24:27]
	v_mfma_f32_16x16x32_bf16 v[4:7], v[12:15], v[186:189], v[4:7]
	s_barrier
	s_setprio 0
	s_add_u32 s20, s64, 0x40000
	s_addc_u32 s21, s65, 0
	s_add_i32 s57, s89, s73
	v_lshl_add_u64 v[8:9], s[20:21], 0, v[160:161]
	s_mov_b32 m0, s57
	s_nop 0
	global_load_lds_dwordx4 v[8:9], off
	v_lshl_add_u64 v[8:9], s[20:21], 0, v[162:163]
	s_add_i32 m0, s57, 0x2000
	s_nop 0
	global_load_lds_dwordx4 v[8:9], off
	s_waitcnt vmcnt(6)
	s_setprio 1
	s_barrier
	v_mfma_f32_16x16x32_bf16 v[24:27], v[190:193], v[132:135], v[52:55]
	v_mfma_f32_16x16x32_bf16 v[52:55], v[194:197], v[144:147], v[24:27]
	v_mfma_f32_16x16x32_bf16 v[24:27], v[198:201], v[132:135], v[48:51]
	v_mfma_f32_16x16x32_bf16 v[48:51], v[202:205], v[144:147], v[24:27]
	v_mfma_f32_16x16x32_bf16 v[24:27], v[190:193], v[174:177], v[36:39]
	v_mfma_f32_16x16x32_bf16 v[36:39], v[194:197], v[178:181], v[24:27]
	v_mfma_f32_16x16x32_bf16 v[24:27], v[198:201], v[174:177], v[32:35]
	v_mfma_f32_16x16x32_bf16 v[20:23], v[190:193], v[182:185], v[20:23]
	v_mfma_f32_16x16x32_bf16 v[16:19], v[198:201], v[182:185], v[16:19]
	v_mfma_f32_16x16x32_bf16 v[8:11], v[190:193], v[116:119], v[68:71]
	v_mfma_f32_16x16x32_bf16 v[12:15], v[198:201], v[116:119], v[64:67]
	v_mfma_f32_16x16x32_bf16 v[32:35], v[202:205], v[178:181], v[24:27]
	v_mfma_f32_16x16x32_bf16 v[20:23], v[194:197], v[186:189], v[20:23]
	v_mfma_f32_16x16x32_bf16 v[16:19], v[202:205], v[186:189], v[16:19]
	v_mfma_f32_16x16x32_bf16 v[8:11], v[194:197], v[128:131], v[8:11]
	v_mfma_f32_16x16x32_bf16 v[12:15], v[202:205], v[128:131], v[12:15]
	s_add_i32 s57, 0, 0x18000
	v_add_u32_e32 v68, s57, v228
	s_barrier
	s_setprio 0
	ds_read_b128 v[24:27], v68
	ds_read_b128 v[28:31], v68 offset:1024
	ds_read_b128 v[64:67], v68 offset:2048
	ds_read_b128 v[68:71], v68 offset:3072
	s_add_u32 s20, s66, 0x40000
	s_addc_u32 s21, s67, 0
	s_mov_b32 m0, s76
	v_lshl_add_u64 v[132:133], s[20:21], 0, v[160:161]
	ds_read_b128 v[116:119], v234 offset:32768
	ds_read_b128 v[128:131], v234 offset:33792
	ds_read_b128 v[174:177], v234 offset:34816
	ds_read_b128 v[178:181], v234 offset:35840
	ds_read_b128 v[182:185], v234 offset:36864
	ds_read_b128 v[186:189], v234 offset:37888
	ds_read_b128 v[190:193], v234 offset:38912
	ds_read_b128 v[194:197], v234 offset:39936
	global_load_lds_dwordx4 v[132:133], off
	v_lshl_add_u64 v[132:133], s[20:21], 0, v[162:163]
	s_mov_b32 m0, s77
	s_nop 0
	global_load_lds_dwordx4 v[132:133], off
	s_waitcnt lgkmcnt(8)
	s_setprio 1
	s_barrier
	s_waitcnt lgkmcnt(0)
	v_mfma_f32_16x16x32_bf16 v[132:135], v[24:27], v[116:119], v[156:159]
	v_mfma_f32_16x16x32_bf16 v[156:159], v[28:31], v[128:131], v[132:135]
	v_mfma_f32_16x16x32_bf16 v[132:135], v[64:67], v[116:119], v[152:155]
	v_mfma_f32_16x16x32_bf16 v[152:155], v[68:71], v[128:131], v[132:135]
	v_mfma_f32_16x16x32_bf16 v[132:135], v[24:27], v[174:177], v[140:143]
	v_mfma_f32_16x16x32_bf16 v[140:143], v[28:31], v[178:181], v[132:135]
	v_mfma_f32_16x16x32_bf16 v[132:135], v[64:67], v[174:177], v[136:139]
	v_mfma_f32_16x16x32_bf16 v[124:127], v[24:27], v[182:185], v[124:127]
	v_mfma_f32_16x16x32_bf16 v[120:123], v[64:67], v[182:185], v[120:123]
	v_mfma_f32_16x16x32_bf16 v[108:111], v[24:27], v[190:193], v[108:111]
	v_mfma_f32_16x16x32_bf16 v[104:107], v[64:67], v[190:193], v[104:107]
	v_mfma_f32_16x16x32_bf16 v[136:139], v[68:71], v[178:181], v[132:135]
	v_mfma_f32_16x16x32_bf16 v[124:127], v[28:31], v[186:189], v[124:127]
	v_mfma_f32_16x16x32_bf16 v[120:123], v[68:71], v[186:189], v[120:123]
	v_mfma_f32_16x16x32_bf16 v[108:111], v[28:31], v[194:197], v[108:111]
	v_mfma_f32_16x16x32_bf16 v[104:107], v[68:71], v[194:197], v[104:107]
	s_barrier
	s_setprio 0
	s_add_i32 s66, 0, 0x1c000
	v_add_u32_e32 v132, s66, v228
	s_add_i32 s20, s57, s73
	ds_read_b128 v[198:201], v132
	ds_read_b128 v[202:205], v132 offset:1024
	ds_read_b128 v[206:209], v132 offset:2048
	ds_read_b128 v[210:213], v132 offset:3072
	v_lshl_add_u64 v[132:133], v[214:215], 0, s[44:45]
	s_mov_b32 m0, s20
	s_nop 0
	global_load_lds_dwordx4 v[132:133], off
	v_lshl_add_u64 v[132:133], v[216:217], 0, s[44:45]
	s_add_i32 m0, s20, 0x2000
	s_nop 0
	global_load_lds_dwordx4 v[132:133], off
	s_waitcnt lgkmcnt(0)
	s_setprio 1
	s_barrier
	v_mfma_f32_16x16x32_bf16 v[80:83], v[206:209], v[116:119], v[80:83]
	v_mfma_f32_16x16x32_bf16 v[132:135], v[198:201], v[116:119], v[148:151]
	v_mfma_f32_16x16x32_bf16 v[144:147], v[210:213], v[128:131], v[80:83]
	v_mfma_f32_16x16x32_bf16 v[80:83], v[198:201], v[174:177], v[84:87]
	v_mfma_f32_16x16x32_bf16 v[148:151], v[202:205], v[128:131], v[132:135]
	v_mfma_f32_16x16x32_bf16 v[132:135], v[202:205], v[178:181], v[80:83]
	v_mfma_f32_16x16x32_bf16 v[80:83], v[206:209], v[174:177], v[88:91]
	v_mfma_f32_16x16x32_bf16 v[128:131], v[210:213], v[178:181], v[80:83]
	v_mfma_f32_16x16x32_bf16 v[80:83], v[198:201], v[182:185], v[92:95]
	v_mfma_f32_16x16x32_bf16 v[116:119], v[202:205], v[186:189], v[80:83]
	v_mfma_f32_16x16x32_bf16 v[80:83], v[206:209], v[182:185], v[112:115]
	v_mfma_f32_16x16x32_bf16 v[112:115], v[210:213], v[186:189], v[80:83]
	v_mfma_f32_16x16x32_bf16 v[80:83], v[198:201], v[190:193], v[100:103]
	v_mfma_f32_16x16x32_bf16 v[100:103], v[202:205], v[194:197], v[80:83]
	v_mfma_f32_16x16x32_bf16 v[80:83], v[206:209], v[190:193], v[96:99]
	v_mfma_f32_16x16x32_bf16 v[96:99], v[210:213], v[194:197], v[80:83]
	s_mov_b32 m0, s95
	v_lshl_add_u64 v[190:191], v[218:219], 0, s[44:45]
	s_barrier
	s_setprio 0
	s_nop 2
	ds_read_b128 v[80:83], v234 offset:49152
	ds_read_b128 v[84:87], v234 offset:50176
	ds_read_b128 v[88:91], v234 offset:51200
	ds_read_b128 v[92:95], v234 offset:52224
	ds_read_b128 v[174:177], v234 offset:53248
	ds_read_b128 v[178:181], v234 offset:54272
	ds_read_b128 v[182:185], v234 offset:55296
	ds_read_b128 v[186:189], v234 offset:56320
	global_load_lds_dwordx4 v[190:191], off
	v_lshl_add_u64 v[190:191], v[220:221], 0, s[44:45]
	s_mov_b32 m0, s96
	s_nop 0
	global_load_lds_dwordx4 v[190:191], off
	s_waitcnt lgkmcnt(0)
	s_setprio 1
	s_barrier
	v_mfma_f32_16x16x32_bf16 v[76:79], v[24:27], v[80:83], v[76:79]
	v_mfma_f32_16x16x32_bf16 v[60:63], v[24:27], v[88:91], v[60:63]
	v_mfma_f32_16x16x32_bf16 v[44:47], v[24:27], v[174:177], v[44:47]
	v_mfma_f32_16x16x32_bf16 v[0:3], v[24:27], v[182:185], v[0:3]
	v_mfma_f32_16x16x32_bf16 v[76:79], v[28:31], v[84:87], v[76:79]
	v_mfma_f32_16x16x32_bf16 v[72:75], v[64:67], v[80:83], v[72:75]
	v_mfma_f32_16x16x32_bf16 v[60:63], v[28:31], v[92:95], v[60:63]
	v_mfma_f32_16x16x32_bf16 v[56:59], v[64:67], v[88:91], v[56:59]
	v_mfma_f32_16x16x32_bf16 v[44:47], v[28:31], v[178:181], v[44:47]
	v_mfma_f32_16x16x32_bf16 v[40:43], v[64:67], v[174:177], v[40:43]
	v_mfma_f32_16x16x32_bf16 v[28:31], v[28:31], v[186:189], v[0:3]
	v_mfma_f32_16x16x32_bf16 v[0:3], v[64:67], v[182:185], v[4:7]
	v_mfma_f32_16x16x32_bf16 v[72:75], v[68:71], v[84:87], v[72:75]
	v_mfma_f32_16x16x32_bf16 v[56:59], v[68:71], v[92:95], v[56:59]
	v_mfma_f32_16x16x32_bf16 v[40:43], v[68:71], v[178:181], v[40:43]
	v_mfma_f32_16x16x32_bf16 v[24:27], v[68:71], v[186:189], v[0:3]
	s_barrier
	s_setprio 0
	s_add_u32 s20, s64, 0x40080
	s_addc_u32 s21, s65, 0
	s_add_i32 s57, s66, s73
	v_lshl_add_u64 v[0:1], s[20:21], 0, v[160:161]
	s_mov_b32 m0, s57
	s_nop 0
	global_load_lds_dwordx4 v[0:1], off
	v_lshl_add_u64 v[0:1], s[20:21], 0, v[162:163]
	s_add_i32 m0, s57, 0x2000
	s_nop 0
	global_load_lds_dwordx4 v[0:1], off
	s_waitcnt vmcnt(6)
	s_setprio 1
	s_barrier
	v_mfma_f32_16x16x32_bf16 v[0:3], v[198:201], v[80:83], v[8:11]
	v_mfma_f32_16x16x32_bf16 v[68:71], v[202:205], v[84:87], v[0:3]
	v_mfma_f32_16x16x32_bf16 v[0:3], v[206:209], v[80:83], v[12:15]
	v_mfma_f32_16x16x32_bf16 v[64:67], v[210:213], v[84:87], v[0:3]
	v_mfma_f32_16x16x32_bf16 v[0:3], v[198:201], v[88:91], v[52:55]
	v_mfma_f32_16x16x32_bf16 v[52:55], v[202:205], v[92:95], v[0:3]
	v_mfma_f32_16x16x32_bf16 v[0:3], v[206:209], v[88:91], v[48:51]
	v_mfma_f32_16x16x32_bf16 v[48:51], v[210:213], v[92:95], v[0:3]
	v_mfma_f32_16x16x32_bf16 v[0:3], v[198:201], v[174:177], v[36:39]
	v_mfma_f32_16x16x32_bf16 v[36:39], v[202:205], v[178:181], v[0:3]
	v_mfma_f32_16x16x32_bf16 v[0:3], v[206:209], v[174:177], v[32:35]
	v_mfma_f32_16x16x32_bf16 v[32:35], v[210:213], v[178:181], v[0:3]
	v_mfma_f32_16x16x32_bf16 v[0:3], v[198:201], v[182:185], v[20:23]
	v_mfma_f32_16x16x32_bf16 v[20:23], v[202:205], v[186:189], v[0:3]
	v_mfma_f32_16x16x32_bf16 v[0:3], v[206:209], v[182:185], v[16:19]
	v_mfma_f32_16x16x32_bf16 v[16:19], v[210:213], v[186:189], v[0:3]
	s_add_u32 s12, s12, 0x100
	s_addc_u32 s13, s13, 0
	s_add_u32 s18, s18, 0x100
	s_addc_u32 s19, s19, 0
	s_cmp_lt_i32 s59, s93
	s_mov_b32 s57, s59
	s_barrier
	s_setprio 0
	s_cbranch_scc1 .LBB0_605

.Lzskip_P10:
	v_cmp_lt_i64_e32 vcc, s[46:47], v[136:137]
	s_and_b64 s[20:21], vcc, exec
	s_cselect_b32 s31, s37, s43
	s_cselect_b32 s35, s36, s42
	s_cselect_b32 s58, s39, s45
	s_cselect_b32 s59, s38, s44
	s_add_u32 s42, s42, 0x20080
	s_addc_u32 s43, s43, 0
	s_add_u32 s60, s44, 0x100
	s_addc_u32 s61, s45, 0
	s_mov_b32 s44, 0
	v_add_u32_e32 v152, s88, v167
	ds_read_b128 v[140:143], v152
	ds_read_b128 v[144:147], v152 offset:1024
	ds_read_b128 v[148:151], v152 offset:2048
	ds_read_b128 v[152:155], v152 offset:3072
	s_add_i32 s62, s44, 2
	s_add_u32 s20, s42, 0xfffe0080
	s_addc_u32 s21, s43, -1
	s_cmp_eq_u32 s55, s44
	s_cselect_b32 s44, s59, s60
	s_cselect_b32 s47, s31, s21
	s_cselect_b32 s46, s35, s20
	s_cselect_b32 s45, s58, s61
	v_lshl_add_u64 v[198:199], s[42:43], 0, v[132:133]
	s_add_i32 m0, s41, 0xc000
	ds_read_b128 v[156:159], v172
	ds_read_b128 v[160:163], v172 offset:1024
	ds_read_b128 v[174:177], v172 offset:2048
	ds_read_b128 v[178:181], v172 offset:3072
	ds_read_b128 v[182:185], v172 offset:4096
	ds_read_b128 v[186:189], v172 offset:5120
	ds_read_b128 v[190:193], v172 offset:6144
	ds_read_b128 v[194:197], v172 offset:7168
	global_load_lds_dwordx4 v[198:199], off
	v_lshl_add_u64 v[198:199], s[42:43], 0, v[134:135]
	s_add_i32 m0, s41, 0xe000
	s_nop 0
	global_load_lds_dwordx4 v[198:199], off
	s_waitcnt lgkmcnt(8)
	s_setprio 1
	s_barrier
	s_waitcnt lgkmcnt(0)
	v_mfma_i32_16x16x64_i8 v[124:127], v[140:143], v[156:159], 0
	v_mfma_i32_16x16x64_i8 v[120:123], v[148:151], v[156:159], 0
	v_mfma_i32_16x16x64_i8 v[116:119], v[140:143], v[174:177], 0
	v_mfma_i32_16x16x64_i8 v[112:115], v[148:151], v[174:177], 0
	v_mfma_i32_16x16x64_i8 v[108:111], v[140:143], v[182:185], 0
	v_mfma_i32_16x16x64_i8 v[104:107], v[148:151], v[182:185], 0
	v_mfma_i32_16x16x64_i8 v[100:103], v[140:143], v[190:193], 0
	v_mfma_i32_16x16x64_i8 v[96:99], v[148:151], v[190:193], 0
	v_mfma_i32_16x16x64_i8 v[124:127], v[144:147], v[160:163], v[124:127]
	v_mfma_i32_16x16x64_i8 v[120:123], v[152:155], v[160:163], v[120:123]
	v_mfma_i32_16x16x64_i8 v[116:119], v[144:147], v[178:181], v[116:119]
	v_mfma_i32_16x16x64_i8 v[112:115], v[152:155], v[178:181], v[112:115]
	v_mfma_i32_16x16x64_i8 v[108:111], v[144:147], v[186:189], v[108:111]
	v_mfma_i32_16x16x64_i8 v[104:107], v[152:155], v[186:189], v[104:107]
	v_mfma_i32_16x16x64_i8 v[100:103], v[144:147], v[194:197], v[100:103]
	v_mfma_i32_16x16x64_i8 v[96:99], v[152:155], v[194:197], v[96:99]
	s_barrier
	s_setprio 0
	s_add_i32 s20, s88, s18
	v_add_u32_e32 v164, s89, v167
	v_lshl_add_u64 v[214:215], s[44:45], 0, v[130:131]
	s_mov_b32 m0, s20
	ds_read_b128 v[198:201], v164
	ds_read_b128 v[202:205], v164 offset:1024
	ds_read_b128 v[206:209], v164 offset:2048
	ds_read_b128 v[210:213], v164 offset:3072
	global_load_lds_dwordx4 v[214:215], off
	v_lshl_add_u64 v[216:217], s[44:45], 0, v[128:129]
	s_add_i32 m0, s20, 0x2000
	s_nop 0
	global_load_lds_dwordx4 v[216:217], off
	s_waitcnt lgkmcnt(0)
	s_setprio 1
	s_barrier
	v_mfma_i32_16x16x64_i8 v[92:95], v[198:201], v[156:159], 0
	v_mfma_i32_16x16x64_i8 v[88:91], v[206:209], v[156:159], 0
	v_mfma_i32_16x16x64_i8 v[84:87], v[198:201], v[174:177], 0
	v_mfma_i32_16x16x64_i8 v[80:83], v[206:209], v[174:177], 0
	v_mfma_i32_16x16x64_i8 v[76:79], v[198:201], v[182:185], 0
	v_mfma_i32_16x16x64_i8 v[72:75], v[206:209], v[182:185], 0
	v_mfma_i32_16x16x64_i8 v[68:71], v[198:201], v[190:193], 0
	v_mfma_i32_16x16x64_i8 v[64:67], v[206:209], v[190:193], 0
	v_mfma_i32_16x16x64_i8 v[92:95], v[202:205], v[160:163], v[92:95]
	v_mfma_i32_16x16x64_i8 v[88:91], v[210:213], v[160:163], v[88:91]
	v_mfma_i32_16x16x64_i8 v[84:87], v[202:205], v[178:181], v[84:87]
	v_mfma_i32_16x16x64_i8 v[80:83], v[210:213], v[178:181], v[80:83]
	v_mfma_i32_16x16x64_i8 v[76:79], v[202:205], v[186:189], v[76:79]
	v_mfma_i32_16x16x64_i8 v[72:75], v[210:213], v[186:189], v[72:75]
	v_mfma_i32_16x16x64_i8 v[68:71], v[202:205], v[194:197], v[68:71]
	v_mfma_i32_16x16x64_i8 v[64:67], v[210:213], v[194:197], v[64:67]
	s_mov_b32 m0, s41
	v_lshl_add_u64 v[218:219], s[46:47], 0, v[130:131]
	s_barrier
	s_setprio 0
	ds_read_b128 v[156:159], v172 offset:16384
	ds_read_b128 v[160:163], v172 offset:17408
	ds_read_b128 v[174:177], v172 offset:18432
	ds_read_b128 v[178:181], v172 offset:19456
	ds_read_b128 v[182:185], v172 offset:20480
	ds_read_b128 v[186:189], v172 offset:21504
	ds_read_b128 v[190:193], v172 offset:22528
	ds_read_b128 v[194:197], v172 offset:23552
	global_load_lds_dwordx4 v[218:219], off
	v_lshl_add_u64 v[220:221], s[46:47], 0, v[128:129]
	s_mov_b32 m0, s48
	s_nop 0
	global_load_lds_dwordx4 v[220:221], off
	s_waitcnt lgkmcnt(0)
	s_setprio 1
	s_barrier
	v_mfma_i32_16x16x64_i8 v[60:63], v[140:143], v[156:159], 0
	v_mfma_i32_16x16x64_i8 v[56:59], v[148:151], v[156:159], 0
	v_mfma_i32_16x16x64_i8 v[52:55], v[140:143], v[174:177], 0
	v_mfma_i32_16x16x64_i8 v[48:51], v[148:151], v[174:177], 0
	v_mfma_i32_16x16x64_i8 v[44:47], v[140:143], v[182:185], 0
	v_mfma_i32_16x16x64_i8 v[40:43], v[148:151], v[182:185], 0
	v_mfma_i32_16x16x64_i8 v[36:39], v[140:143], v[190:193], 0
	v_mfma_i32_16x16x64_i8 v[32:35], v[148:151], v[190:193], 0
	v_mfma_i32_16x16x64_i8 v[60:63], v[144:147], v[160:163], v[60:63]
	v_mfma_i32_16x16x64_i8 v[56:59], v[152:155], v[160:163], v[56:59]
	v_mfma_i32_16x16x64_i8 v[52:55], v[144:147], v[178:181], v[52:55]
	v_mfma_i32_16x16x64_i8 v[48:51], v[152:155], v[178:181], v[48:51]
	v_mfma_i32_16x16x64_i8 v[44:47], v[144:147], v[186:189], v[44:47]
	v_mfma_i32_16x16x64_i8 v[40:43], v[152:155], v[186:189], v[40:43]
	v_mfma_i32_16x16x64_i8 v[36:39], v[144:147], v[194:197], v[36:39]
	v_mfma_i32_16x16x64_i8 v[32:35], v[152:155], v[194:197], v[32:35]
	s_barrier
	s_setprio 0
	s_add_u32 s20, s44, 0x20000
	s_addc_u32 s21, s45, 0
	s_add_i32 s63, s89, s18
	v_lshl_add_u64 v[140:141], s[20:21], 0, v[130:131]
	s_mov_b32 m0, s63
	s_nop 0
	global_load_lds_dwordx4 v[140:141], off
	v_lshl_add_u64 v[140:141], s[20:21], 0, v[128:129]
	s_add_i32 m0, s63, 0x2000
	s_nop 0
	global_load_lds_dwordx4 v[140:141], off
	s_waitcnt vmcnt(6)
	s_setprio 1
	s_barrier
	v_mfma_i32_16x16x64_i8 v[28:31], v[198:201], v[156:159], 0
	v_mfma_i32_16x16x64_i8 v[24:27], v[206:209], v[156:159], 0
	v_mfma_i32_16x16x64_i8 v[20:23], v[198:201], v[174:177], 0
	v_mfma_i32_16x16x64_i8 v[16:19], v[206:209], v[174:177], 0
	v_mfma_i32_16x16x64_i8 v[12:15], v[198:201], v[182:185], 0
	v_mfma_i32_16x16x64_i8 v[8:11], v[206:209], v[182:185], 0
	v_mfma_i32_16x16x64_i8 v[4:7], v[198:201], v[190:193], 0
	v_mfma_i32_16x16x64_i8 v[0:3], v[206:209], v[190:193], 0
	v_mfma_i32_16x16x64_i8 v[28:31], v[202:205], v[160:163], v[28:31]
	v_mfma_i32_16x16x64_i8 v[24:27], v[210:213], v[160:163], v[24:27]
	v_mfma_i32_16x16x64_i8 v[20:23], v[202:205], v[178:181], v[20:23]
	v_mfma_i32_16x16x64_i8 v[16:19], v[210:213], v[178:181], v[16:19]
	v_mfma_i32_16x16x64_i8 v[12:15], v[202:205], v[186:189], v[12:15]
	v_mfma_i32_16x16x64_i8 v[8:11], v[210:213], v[186:189], v[8:11]
	v_mfma_i32_16x16x64_i8 v[4:7], v[202:205], v[194:197], v[4:7]
	v_mfma_i32_16x16x64_i8 v[0:3], v[210:213], v[194:197], v[0:3]
	s_add_i32 s63, 0, 0x18000
	v_add_u32_e32 v152, s63, v167
	s_barrier
	s_setprio 0
	ds_read_b128 v[140:143], v152
	ds_read_b128 v[144:147], v152 offset:1024
	ds_read_b128 v[148:151], v152 offset:2048
	ds_read_b128 v[152:155], v152 offset:3072
	s_add_u32 s20, s46, 0x20000
	s_addc_u32 s21, s47, 0
	s_mov_b32 m0, s49
	v_lshl_add_u64 v[198:199], s[20:21], 0, v[130:131]
	ds_read_b128 v[156:159], v172 offset:32768
	ds_read_b128 v[160:163], v172 offset:33792
	ds_read_b128 v[174:177], v172 offset:34816
	ds_read_b128 v[178:181], v172 offset:35840
	ds_read_b128 v[182:185], v172 offset:36864
	ds_read_b128 v[186:189], v172 offset:37888
	ds_read_b128 v[190:193], v172 offset:38912
	ds_read_b128 v[194:197], v172 offset:39936
	global_load_lds_dwordx4 v[198:199], off
	v_lshl_add_u64 v[198:199], s[20:21], 0, v[128:129]
	s_mov_b32 m0, s50
	s_nop 0
	global_load_lds_dwordx4 v[198:199], off
	s_waitcnt lgkmcnt(8)
	s_setprio 1
	s_barrier
	s_waitcnt lgkmcnt(0)
	v_mfma_i32_16x16x64_i8 v[124:127], v[140:143], v[156:159], v[124:127]
	v_mfma_i32_16x16x64_i8 v[120:123], v[148:151], v[156:159], v[120:123]
	v_mfma_i32_16x16x64_i8 v[116:119], v[140:143], v[174:177], v[116:119]
	v_mfma_i32_16x16x64_i8 v[112:115], v[148:151], v[174:177], v[112:115]
	v_mfma_i32_16x16x64_i8 v[108:111], v[140:143], v[182:185], v[108:111]
	v_mfma_i32_16x16x64_i8 v[104:107], v[148:151], v[182:185], v[104:107]
	v_mfma_i32_16x16x64_i8 v[100:103], v[140:143], v[190:193], v[100:103]
	v_mfma_i32_16x16x64_i8 v[96:99], v[148:151], v[190:193], v[96:99]
	v_mfma_i32_16x16x64_i8 v[124:127], v[144:147], v[160:163], v[124:127]
	v_mfma_i32_16x16x64_i8 v[120:123], v[152:155], v[160:163], v[120:123]
	v_mfma_i32_16x16x64_i8 v[116:119], v[144:147], v[178:181], v[116:119]
	v_mfma_i32_16x16x64_i8 v[112:115], v[152:155], v[178:181], v[112:115]
	v_mfma_i32_16x16x64_i8 v[108:111], v[144:147], v[186:189], v[108:111]
	v_mfma_i32_16x16x64_i8 v[104:107], v[152:155], v[186:189], v[104:107]
	v_mfma_i32_16x16x64_i8 v[100:103], v[144:147], v[194:197], v[100:103]
	v_mfma_i32_16x16x64_i8 v[96:99], v[152:155], v[194:197], v[96:99]
	s_barrier
	s_setprio 0
	s_add_i32 s46, 0, 0x1c000
	s_add_i32 s20, s63, s18
	v_add_u32_e32 v164, s46, v167
	v_lshl_add_u64 v[214:215], v[214:215], 0, s[26:27]
	s_mov_b32 m0, s20
	ds_read_b128 v[198:201], v164
	ds_read_b128 v[202:205], v164 offset:1024
	ds_read_b128 v[206:209], v164 offset:2048
	ds_read_b128 v[210:213], v164 offset:3072
	global_load_lds_dwordx4 v[214:215], off
	v_lshl_add_u64 v[214:215], v[216:217], 0, s[26:27]
	s_add_i32 m0, s20, 0x2000
	s_nop 0
	global_load_lds_dwordx4 v[214:215], off
	s_waitcnt lgkmcnt(0)
	s_setprio 1
	s_barrier
	v_mfma_i32_16x16x64_i8 v[92:95], v[198:201], v[156:159], v[92:95]
	v_mfma_i32_16x16x64_i8 v[88:91], v[206:209], v[156:159], v[88:91]
	v_mfma_i32_16x16x64_i8 v[84:87], v[198:201], v[174:177], v[84:87]
	v_mfma_i32_16x16x64_i8 v[80:83], v[206:209], v[174:177], v[80:83]
	v_mfma_i32_16x16x64_i8 v[76:79], v[198:201], v[182:185], v[76:79]
	v_mfma_i32_16x16x64_i8 v[72:75], v[206:209], v[182:185], v[72:75]
	v_mfma_i32_16x16x64_i8 v[68:71], v[198:201], v[190:193], v[68:71]
	v_mfma_i32_16x16x64_i8 v[64:67], v[206:209], v[190:193], v[64:67]
	v_mfma_i32_16x16x64_i8 v[92:95], v[202:205], v[160:163], v[92:95]
	v_mfma_i32_16x16x64_i8 v[88:91], v[210:213], v[160:163], v[88:91]
	v_mfma_i32_16x16x64_i8 v[84:87], v[202:205], v[178:181], v[84:87]
	v_mfma_i32_16x16x64_i8 v[80:83], v[210:213], v[178:181], v[80:83]
	v_mfma_i32_16x16x64_i8 v[76:79], v[202:205], v[186:189], v[76:79]
	v_mfma_i32_16x16x64_i8 v[72:75], v[210:213], v[186:189], v[72:75]
	v_mfma_i32_16x16x64_i8 v[68:71], v[202:205], v[194:197], v[68:71]
	v_mfma_i32_16x16x64_i8 v[64:67], v[210:213], v[194:197], v[64:67]
	s_mov_b32 m0, s53
	v_lshl_add_u64 v[214:215], v[218:219], 0, s[26:27]
	s_barrier
	s_setprio 0
	ds_read_b128 v[156:159], v172 offset:49152
	ds_read_b128 v[160:163], v172 offset:50176
	ds_read_b128 v[174:177], v172 offset:51200
	ds_read_b128 v[178:181], v172 offset:52224
	ds_read_b128 v[182:185], v172 offset:53248
	ds_read_b128 v[186:189], v172 offset:54272
	ds_read_b128 v[190:193], v172 offset:55296
	ds_read_b128 v[194:197], v172 offset:56320
	global_load_lds_dwordx4 v[214:215], off
	v_lshl_add_u64 v[214:215], v[220:221], 0, s[26:27]
	s_mov_b32 m0, s54
	s_nop 0
	global_load_lds_dwordx4 v[214:215], off
	s_waitcnt lgkmcnt(0)
	s_setprio 1
	s_barrier
	v_mfma_i32_16x16x64_i8 v[60:63], v[140:143], v[156:159], v[60:63]
	v_mfma_i32_16x16x64_i8 v[56:59], v[148:151], v[156:159], v[56:59]
	v_mfma_i32_16x16x64_i8 v[52:55], v[140:143], v[174:177], v[52:55]
	v_mfma_i32_16x16x64_i8 v[48:51], v[148:151], v[174:177], v[48:51]
	v_mfma_i32_16x16x64_i8 v[44:47], v[140:143], v[182:185], v[44:47]
	v_mfma_i32_16x16x64_i8 v[40:43], v[148:151], v[182:185], v[40:43]
	v_mfma_i32_16x16x64_i8 v[36:39], v[140:143], v[190:193], v[36:39]
	v_mfma_i32_16x16x64_i8 v[32:35], v[148:151], v[190:193], v[32:35]
	v_mfma_i32_16x16x64_i8 v[60:63], v[144:147], v[160:163], v[60:63]
	v_mfma_i32_16x16x64_i8 v[56:59], v[152:155], v[160:163], v[56:59]
	v_mfma_i32_16x16x64_i8 v[52:55], v[144:147], v[178:181], v[52:55]
	v_mfma_i32_16x16x64_i8 v[48:51], v[152:155], v[178:181], v[48:51]
	v_mfma_i32_16x16x64_i8 v[44:47], v[144:147], v[186:189], v[44:47]
	v_mfma_i32_16x16x64_i8 v[40:43], v[152:155], v[186:189], v[40:43]
	v_mfma_i32_16x16x64_i8 v[36:39], v[144:147], v[194:197], v[36:39]
	v_mfma_i32_16x16x64_i8 v[32:35], v[152:155], v[194:197], v[32:35]
	s_barrier
	s_setprio 0
	s_add_u32 s20, s44, 0x20080
	s_addc_u32 s21, s45, 0
	s_add_i32 s44, s46, s18
	v_lshl_add_u64 v[140:141], s[20:21], 0, v[130:131]
	s_mov_b32 m0, s44
	s_nop 0
	global_load_lds_dwordx4 v[140:141], off
	v_lshl_add_u64 v[140:141], s[20:21], 0, v[128:129]
	s_add_i32 m0, s44, 0x2000
	s_nop 0
	global_load_lds_dwordx4 v[140:141], off
	s_waitcnt vmcnt(6)
	s_setprio 1
	s_barrier
	v_mfma_i32_16x16x64_i8 v[28:31], v[198:201], v[156:159], v[28:31]
	v_mfma_i32_16x16x64_i8 v[24:27], v[206:209], v[156:159], v[24:27]
	v_mfma_i32_16x16x64_i8 v[20:23], v[198:201], v[174:177], v[20:23]
	v_mfma_i32_16x16x64_i8 v[16:19], v[206:209], v[174:177], v[16:19]
	v_mfma_i32_16x16x64_i8 v[12:15], v[198:201], v[182:185], v[12:15]
	v_mfma_i32_16x16x64_i8 v[8:11], v[206:209], v[182:185], v[8:11]
	v_mfma_i32_16x16x64_i8 v[4:7], v[198:201], v[190:193], v[4:7]
	v_mfma_i32_16x16x64_i8 v[0:3], v[206:209], v[190:193], v[0:3]
	v_mfma_i32_16x16x64_i8 v[28:31], v[202:205], v[160:163], v[28:31]
	v_mfma_i32_16x16x64_i8 v[24:27], v[210:213], v[160:163], v[24:27]
	v_mfma_i32_16x16x64_i8 v[20:23], v[202:205], v[178:181], v[20:23]
	v_mfma_i32_16x16x64_i8 v[16:19], v[210:213], v[178:181], v[16:19]
	v_mfma_i32_16x16x64_i8 v[12:15], v[202:205], v[186:189], v[12:15]
	v_mfma_i32_16x16x64_i8 v[8:11], v[210:213], v[186:189], v[8:11]
	v_mfma_i32_16x16x64_i8 v[4:7], v[202:205], v[194:197], v[4:7]
	v_mfma_i32_16x16x64_i8 v[0:3], v[210:213], v[194:197], v[0:3]
	s_add_u32 s42, s42, 0x100
	s_addc_u32 s43, s43, 0
	s_add_u32 s60, s60, 0x100
	s_addc_u32 s61, s61, 0
	s_cmp_ge_i32 s62, s52
	s_mov_b32 s44, s62
	s_barrier
	s_setprio 0
	s_cbranch_scc1 .Lpeel_done_P10
.LBB0_716:
	v_add_u32_e32 v152, s88, v167
	ds_read_b128 v[140:143], v152
	ds_read_b128 v[144:147], v152 offset:1024
	ds_read_b128 v[148:151], v152 offset:2048
	ds_read_b128 v[152:155], v152 offset:3072
	s_add_i32 s62, s44, 2
	s_add_u32 s20, s42, 0xfffe0080
	s_addc_u32 s21, s43, -1
	s_cmp_eq_u32 s55, s44
	s_cselect_b32 s44, s59, s60
	s_cselect_b32 s47, s31, s21
	s_cselect_b32 s46, s35, s20
	s_cselect_b32 s45, s58, s61
	v_lshl_add_u64 v[198:199], s[42:43], 0, v[132:133]
	s_add_i32 m0, s41, 0xc000
	ds_read_b128 v[156:159], v172
	ds_read_b128 v[160:163], v172 offset:1024
	ds_read_b128 v[174:177], v172 offset:2048
	ds_read_b128 v[178:181], v172 offset:3072
	ds_read_b128 v[182:185], v172 offset:4096
	ds_read_b128 v[186:189], v172 offset:5120
	ds_read_b128 v[190:193], v172 offset:6144
	ds_read_b128 v[194:197], v172 offset:7168
	global_load_lds_dwordx4 v[198:199], off
	v_lshl_add_u64 v[198:199], s[42:43], 0, v[134:135]
	s_add_i32 m0, s41, 0xe000
	s_nop 0
	global_load_lds_dwordx4 v[198:199], off
	s_waitcnt lgkmcnt(8)
	s_setprio 1
	s_barrier
	s_waitcnt lgkmcnt(0)
	v_mfma_i32_16x16x64_i8 v[124:127], v[140:143], v[156:159], v[124:127]
	v_mfma_i32_16x16x64_i8 v[120:123], v[148:151], v[156:159], v[120:123]
	v_mfma_i32_16x16x64_i8 v[116:119], v[140:143], v[174:177], v[116:119]
	v_mfma_i32_16x16x64_i8 v[112:115], v[148:151], v[174:177], v[112:115]
	v_mfma_i32_16x16x64_i8 v[108:111], v[140:143], v[182:185], v[108:111]
	v_mfma_i32_16x16x64_i8 v[104:107], v[148:151], v[182:185], v[104:107]
	v_mfma_i32_16x16x64_i8 v[100:103], v[140:143], v[190:193], v[100:103]
	v_mfma_i32_16x16x64_i8 v[96:99], v[148:151], v[190:193], v[96:99]
	v_mfma_i32_16x16x64_i8 v[124:127], v[144:147], v[160:163], v[124:127]
	v_mfma_i32_16x16x64_i8 v[120:123], v[152:155], v[160:163], v[120:123]
	v_mfma_i32_16x16x64_i8 v[116:119], v[144:147], v[178:181], v[116:119]
	v_mfma_i32_16x16x64_i8 v[112:115], v[152:155], v[178:181], v[112:115]
	v_mfma_i32_16x16x64_i8 v[108:111], v[144:147], v[186:189], v[108:111]
	v_mfma_i32_16x16x64_i8 v[104:107], v[152:155], v[186:189], v[104:107]
	v_mfma_i32_16x16x64_i8 v[100:103], v[144:147], v[194:197], v[100:103]
	v_mfma_i32_16x16x64_i8 v[96:99], v[152:155], v[194:197], v[96:99]
	s_barrier
	s_setprio 0
	s_add_i32 s20, s88, s18
	v_add_u32_e32 v164, s89, v167
	v_lshl_add_u64 v[214:215], s[44:45], 0, v[130:131]
	s_mov_b32 m0, s20
	ds_read_b128 v[198:201], v164
	ds_read_b128 v[202:205], v164 offset:1024
	ds_read_b128 v[206:209], v164 offset:2048
	ds_read_b128 v[210:213], v164 offset:3072
	global_load_lds_dwordx4 v[214:215], off
	v_lshl_add_u64 v[216:217], s[44:45], 0, v[128:129]
	s_add_i32 m0, s20, 0x2000
	s_nop 0
	global_load_lds_dwordx4 v[216:217], off
	s_waitcnt lgkmcnt(0)
	s_setprio 1
	s_barrier
	v_mfma_i32_16x16x64_i8 v[92:95], v[198:201], v[156:159], v[92:95]
	v_mfma_i32_16x16x64_i8 v[88:91], v[206:209], v[156:159], v[88:91]
	v_mfma_i32_16x16x64_i8 v[84:87], v[198:201], v[174:177], v[84:87]
	v_mfma_i32_16x16x64_i8 v[80:83], v[206:209], v[174:177], v[80:83]
	v_mfma_i32_16x16x64_i8 v[76:79], v[198:201], v[182:185], v[76:79]
	v_mfma_i32_16x16x64_i8 v[72:75], v[206:209], v[182:185], v[72:75]
	v_mfma_i32_16x16x64_i8 v[68:71], v[198:201], v[190:193], v[68:71]
	v_mfma_i32_16x16x64_i8 v[64:67], v[206:209], v[190:193], v[64:67]
	v_mfma_i32_16x16x64_i8 v[92:95], v[202:205], v[160:163], v[92:95]
	v_mfma_i32_16x16x64_i8 v[88:91], v[210:213], v[160:163], v[88:91]
	v_mfma_i32_16x16x64_i8 v[84:87], v[202:205], v[178:181], v[84:87]
	v_mfma_i32_16x16x64_i8 v[80:83], v[210:213], v[178:181], v[80:83]
	v_mfma_i32_16x16x64_i8 v[76:79], v[202:205], v[186:189], v[76:79]
	v_mfma_i32_16x16x64_i8 v[72:75], v[210:213], v[186:189], v[72:75]
	v_mfma_i32_16x16x64_i8 v[68:71], v[202:205], v[194:197], v[68:71]
	v_mfma_i32_16x16x64_i8 v[64:67], v[210:213], v[194:197], v[64:67]
	s_mov_b32 m0, s41
	v_lshl_add_u64 v[218:219], s[46:47], 0, v[130:131]
	s_barrier
	s_setprio 0
	ds_read_b128 v[156:159], v172 offset:16384
	ds_read_b128 v[160:163], v172 offset:17408
	ds_read_b128 v[174:177], v172 offset:18432
	ds_read_b128 v[178:181], v172 offset:19456
	ds_read_b128 v[182:185], v172 offset:20480
	ds_read_b128 v[186:189], v172 offset:21504
	ds_read_b128 v[190:193], v172 offset:22528
	ds_read_b128 v[194:197], v172 offset:23552
	global_load_lds_dwordx4 v[218:219], off
	v_lshl_add_u64 v[220:221], s[46:47], 0, v[128:129]
	s_mov_b32 m0, s48
	s_nop 0
	global_load_lds_dwordx4 v[220:221], off
	s_waitcnt lgkmcnt(0)
	s_setprio 1
	s_barrier
	v_mfma_i32_16x16x64_i8 v[60:63], v[140:143], v[156:159], v[60:63]
	v_mfma_i32_16x16x64_i8 v[56:59], v[148:151], v[156:159], v[56:59]
	v_mfma_i32_16x16x64_i8 v[52:55], v[140:143], v[174:177], v[52:55]
	v_mfma_i32_16x16x64_i8 v[48:51], v[148:151], v[174:177], v[48:51]
	v_mfma_i32_16x16x64_i8 v[44:47], v[140:143], v[182:185], v[44:47]
	v_mfma_i32_16x16x64_i8 v[40:43], v[148:151], v[182:185], v[40:43]
	v_mfma_i32_16x16x64_i8 v[36:39], v[140:143], v[190:193], v[36:39]
	v_mfma_i32_16x16x64_i8 v[32:35], v[148:151], v[190:193], v[32:35]
	v_mfma_i32_16x16x64_i8 v[60:63], v[144:147], v[160:163], v[60:63]
	v_mfma_i32_16x16x64_i8 v[56:59], v[152:155], v[160:163], v[56:59]
	v_mfma_i32_16x16x64_i8 v[52:55], v[144:147], v[178:181], v[52:55]
	v_mfma_i32_16x16x64_i8 v[48:51], v[152:155], v[178:181], v[48:51]
	v_mfma_i32_16x16x64_i8 v[44:47], v[144:147], v[186:189], v[44:47]
	v_mfma_i32_16x16x64_i8 v[40:43], v[152:155], v[186:189], v[40:43]
	v_mfma_i32_16x16x64_i8 v[36:39], v[144:147], v[194:197], v[36:39]
	v_mfma_i32_16x16x64_i8 v[32:35], v[152:155], v[194:197], v[32:35]
	s_barrier
	s_setprio 0
	s_add_u32 s20, s44, 0x20000
	s_addc_u32 s21, s45, 0
	s_add_i32 s63, s89, s18
	v_lshl_add_u64 v[140:141], s[20:21], 0, v[130:131]
	s_mov_b32 m0, s63
	s_nop 0
	global_load_lds_dwordx4 v[140:141], off
	v_lshl_add_u64 v[140:141], s[20:21], 0, v[128:129]
	s_add_i32 m0, s63, 0x2000
	s_nop 0
	global_load_lds_dwordx4 v[140:141], off
	s_waitcnt vmcnt(6)
	s_setprio 1
	s_barrier
	v_mfma_i32_16x16x64_i8 v[28:31], v[198:201], v[156:159], v[28:31]
	v_mfma_i32_16x16x64_i8 v[24:27], v[206:209], v[156:159], v[24:27]
	v_mfma_i32_16x16x64_i8 v[20:23], v[198:201], v[174:177], v[20:23]
	v_mfma_i32_16x16x64_i8 v[16:19], v[206:209], v[174:177], v[16:19]
	v_mfma_i32_16x16x64_i8 v[12:15], v[198:201], v[182:185], v[12:15]
	v_mfma_i32_16x16x64_i8 v[8:11], v[206:209], v[182:185], v[8:11]
	v_mfma_i32_16x16x64_i8 v[4:7], v[198:201], v[190:193], v[4:7]
	v_mfma_i32_16x16x64_i8 v[0:3], v[206:209], v[190:193], v[0:3]
	v_mfma_i32_16x16x64_i8 v[28:31], v[202:205], v[160:163], v[28:31]
	v_mfma_i32_16x16x64_i8 v[24:27], v[210:213], v[160:163], v[24:27]
	v_mfma_i32_16x16x64_i8 v[20:23], v[202:205], v[178:181], v[20:23]
	v_mfma_i32_16x16x64_i8 v[16:19], v[210:213], v[178:181], v[16:19]
	v_mfma_i32_16x16x64_i8 v[12:15], v[202:205], v[186:189], v[12:15]
	v_mfma_i32_16x16x64_i8 v[8:11], v[210:213], v[186:189], v[8:11]
	v_mfma_i32_16x16x64_i8 v[4:7], v[202:205], v[194:197], v[4:7]
	v_mfma_i32_16x16x64_i8 v[0:3], v[210:213], v[194:197], v[0:3]
	s_add_i32 s63, 0, 0x18000
	v_add_u32_e32 v152, s63, v167
	s_barrier
	s_setprio 0
	ds_read_b128 v[140:143], v152
	ds_read_b128 v[144:147], v152 offset:1024
	ds_read_b128 v[148:151], v152 offset:2048
	ds_read_b128 v[152:155], v152 offset:3072
	s_add_u32 s20, s46, 0x20000
	s_addc_u32 s21, s47, 0
	s_mov_b32 m0, s49
	v_lshl_add_u64 v[198:199], s[20:21], 0, v[130:131]
	ds_read_b128 v[156:159], v172 offset:32768
	ds_read_b128 v[160:163], v172 offset:33792
	ds_read_b128 v[174:177], v172 offset:34816
	ds_read_b128 v[178:181], v172 offset:35840
	ds_read_b128 v[182:185], v172 offset:36864
	ds_read_b128 v[186:189], v172 offset:37888
	ds_read_b128 v[190:193], v172 offset:38912
	ds_read_b128 v[194:197], v172 offset:39936
	global_load_lds_dwordx4 v[198:199], off
	v_lshl_add_u64 v[198:199], s[20:21], 0, v[128:129]
	s_mov_b32 m0, s50
	s_nop 0
	global_load_lds_dwordx4 v[198:199], off
	s_waitcnt lgkmcnt(8)
	s_setprio 1
	s_barrier
	s_waitcnt lgkmcnt(0)
	v_mfma_i32_16x16x64_i8 v[124:127], v[140:143], v[156:159], v[124:127]
	v_mfma_i32_16x16x64_i8 v[120:123], v[148:151], v[156:159], v[120:123]
	v_mfma_i32_16x16x64_i8 v[116:119], v[140:143], v[174:177], v[116:119]
	v_mfma_i32_16x16x64_i8 v[112:115], v[148:151], v[174:177], v[112:115]
	v_mfma_i32_16x16x64_i8 v[108:111], v[140:143], v[182:185], v[108:111]
	v_mfma_i32_16x16x64_i8 v[104:107], v[148:151], v[182:185], v[104:107]
	v_mfma_i32_16x16x64_i8 v[100:103], v[140:143], v[190:193], v[100:103]
	v_mfma_i32_16x16x64_i8 v[96:99], v[148:151], v[190:193], v[96:99]
	v_mfma_i32_16x16x64_i8 v[124:127], v[144:147], v[160:163], v[124:127]
	v_mfma_i32_16x16x64_i8 v[120:123], v[152:155], v[160:163], v[120:123]
	v_mfma_i32_16x16x64_i8 v[116:119], v[144:147], v[178:181], v[116:119]
	v_mfma_i32_16x16x64_i8 v[112:115], v[152:155], v[178:181], v[112:115]
	v_mfma_i32_16x16x64_i8 v[108:111], v[144:147], v[186:189], v[108:111]
	v_mfma_i32_16x16x64_i8 v[104:107], v[152:155], v[186:189], v[104:107]
	v_mfma_i32_16x16x64_i8 v[100:103], v[144:147], v[194:197], v[100:103]
	v_mfma_i32_16x16x64_i8 v[96:99], v[152:155], v[194:197], v[96:99]
	s_barrier
	s_setprio 0
	s_add_i32 s46, 0, 0x1c000
	s_add_i32 s20, s63, s18
	v_add_u32_e32 v164, s46, v167
	v_lshl_add_u64 v[214:215], v[214:215], 0, s[26:27]
	s_mov_b32 m0, s20
	ds_read_b128 v[198:201], v164
	ds_read_b128 v[202:205], v164 offset:1024
	ds_read_b128 v[206:209], v164 offset:2048
	ds_read_b128 v[210:213], v164 offset:3072
	global_load_lds_dwordx4 v[214:215], off
	v_lshl_add_u64 v[214:215], v[216:217], 0, s[26:27]
	s_add_i32 m0, s20, 0x2000
	s_nop 0
	global_load_lds_dwordx4 v[214:215], off
	s_waitcnt lgkmcnt(0)
	s_setprio 1
	s_barrier
	v_mfma_i32_16x16x64_i8 v[92:95], v[198:201], v[156:159], v[92:95]
	v_mfma_i32_16x16x64_i8 v[88:91], v[206:209], v[156:159], v[88:91]
	v_mfma_i32_16x16x64_i8 v[84:87], v[198:201], v[174:177], v[84:87]
	v_mfma_i32_16x16x64_i8 v[80:83], v[206:209], v[174:177], v[80:83]
	v_mfma_i32_16x16x64_i8 v[76:79], v[198:201], v[182:185], v[76:79]
	v_mfma_i32_16x16x64_i8 v[72:75], v[206:209], v[182:185], v[72:75]
	v_mfma_i32_16x16x64_i8 v[68:71], v[198:201], v[190:193], v[68:71]
	v_mfma_i32_16x16x64_i8 v[64:67], v[206:209], v[190:193], v[64:67]
	v_mfma_i32_16x16x64_i8 v[92:95], v[202:205], v[160:163], v[92:95]
	v_mfma_i32_16x16x64_i8 v[88:91], v[210:213], v[160:163], v[88:91]
	v_mfma_i32_16x16x64_i8 v[84:87], v[202:205], v[178:181], v[84:87]
	v_mfma_i32_16x16x64_i8 v[80:83], v[210:213], v[178:181], v[80:83]
	v_mfma_i32_16x16x64_i8 v[76:79], v[202:205], v[186:189], v[76:79]
	v_mfma_i32_16x16x64_i8 v[72:75], v[210:213], v[186:189], v[72:75]
	v_mfma_i32_16x16x64_i8 v[68:71], v[202:205], v[194:197], v[68:71]
	v_mfma_i32_16x16x64_i8 v[64:67], v[210:213], v[194:197], v[64:67]
	s_mov_b32 m0, s53
	v_lshl_add_u64 v[214:215], v[218:219], 0, s[26:27]
	s_barrier
	s_setprio 0
	ds_read_b128 v[156:159], v172 offset:49152
	ds_read_b128 v[160:163], v172 offset:50176
	ds_read_b128 v[174:177], v172 offset:51200
	ds_read_b128 v[178:181], v172 offset:52224
	ds_read_b128 v[182:185], v172 offset:53248
	ds_read_b128 v[186:189], v172 offset:54272
	ds_read_b128 v[190:193], v172 offset:55296
	ds_read_b128 v[194:197], v172 offset:56320
	global_load_lds_dwordx4 v[214:215], off
	v_lshl_add_u64 v[214:215], v[220:221], 0, s[26:27]
	s_mov_b32 m0, s54
	s_nop 0
	global_load_lds_dwordx4 v[214:215], off
	s_waitcnt lgkmcnt(0)
	s_setprio 1
	s_barrier
	v_mfma_i32_16x16x64_i8 v[60:63], v[140:143], v[156:159], v[60:63]
	v_mfma_i32_16x16x64_i8 v[56:59], v[148:151], v[156:159], v[56:59]
	v_mfma_i32_16x16x64_i8 v[52:55], v[140:143], v[174:177], v[52:55]
	v_mfma_i32_16x16x64_i8 v[48:51], v[148:151], v[174:177], v[48:51]
	v_mfma_i32_16x16x64_i8 v[44:47], v[140:143], v[182:185], v[44:47]
	v_mfma_i32_16x16x64_i8 v[40:43], v[148:151], v[182:185], v[40:43]
	v_mfma_i32_16x16x64_i8 v[36:39], v[140:143], v[190:193], v[36:39]
	v_mfma_i32_16x16x64_i8 v[32:35], v[148:151], v[190:193], v[32:35]
	v_mfma_i32_16x16x64_i8 v[60:63], v[144:147], v[160:163], v[60:63]
	v_mfma_i32_16x16x64_i8 v[56:59], v[152:155], v[160:163], v[56:59]
	v_mfma_i32_16x16x64_i8 v[52:55], v[144:147], v[178:181], v[52:55]
	v_mfma_i32_16x16x64_i8 v[48:51], v[152:155], v[178:181], v[48:51]
	v_mfma_i32_16x16x64_i8 v[44:47], v[144:147], v[186:189], v[44:47]
	v_mfma_i32_16x16x64_i8 v[40:43], v[152:155], v[186:189], v[40:43]
	v_mfma_i32_16x16x64_i8 v[36:39], v[144:147], v[194:197], v[36:39]
	v_mfma_i32_16x16x64_i8 v[32:35], v[152:155], v[194:197], v[32:35]
	s_barrier
	s_setprio 0
	s_add_u32 s20, s44, 0x20080
	s_addc_u32 s21, s45, 0
	s_add_i32 s44, s46, s18
	v_lshl_add_u64 v[140:141], s[20:21], 0, v[130:131]
	s_mov_b32 m0, s44
	s_nop 0
	global_load_lds_dwordx4 v[140:141], off
	v_lshl_add_u64 v[140:141], s[20:21], 0, v[128:129]
	s_add_i32 m0, s44, 0x2000
	s_nop 0
	global_load_lds_dwordx4 v[140:141], off
	s_waitcnt vmcnt(6)
	s_setprio 1
	s_barrier
	v_mfma_i32_16x16x64_i8 v[28:31], v[198:201], v[156:159], v[28:31]
	v_mfma_i32_16x16x64_i8 v[24:27], v[206:209], v[156:159], v[24:27]
	v_mfma_i32_16x16x64_i8 v[20:23], v[198:201], v[174:177], v[20:23]
	v_mfma_i32_16x16x64_i8 v[16:19], v[206:209], v[174:177], v[16:19]
	v_mfma_i32_16x16x64_i8 v[12:15], v[198:201], v[182:185], v[12:15]
	v_mfma_i32_16x16x64_i8 v[8:11], v[206:209], v[182:185], v[8:11]
	v_mfma_i32_16x16x64_i8 v[4:7], v[198:201], v[190:193], v[4:7]
	v_mfma_i32_16x16x64_i8 v[0:3], v[206:209], v[190:193], v[0:3]
	v_mfma_i32_16x16x64_i8 v[28:31], v[202:205], v[160:163], v[28:31]
	v_mfma_i32_16x16x64_i8 v[24:27], v[210:213], v[160:163], v[24:27]
	v_mfma_i32_16x16x64_i8 v[20:23], v[202:205], v[178:181], v[20:23]
	v_mfma_i32_16x16x64_i8 v[16:19], v[210:213], v[178:181], v[16:19]
	v_mfma_i32_16x16x64_i8 v[12:15], v[202:205], v[186:189], v[12:15]
	v_mfma_i32_16x16x64_i8 v[8:11], v[210:213], v[186:189], v[8:11]
	v_mfma_i32_16x16x64_i8 v[4:7], v[202:205], v[194:197], v[4:7]
	v_mfma_i32_16x16x64_i8 v[0:3], v[210:213], v[194:197], v[0:3]
	s_add_u32 s42, s42, 0x100
	s_addc_u32 s43, s43, 0
	s_add_u32 s60, s60, 0x100
	s_addc_u32 s61, s61, 0
	s_cmp_ge_i32 s62, s52
	s_mov_b32 s44, s62
	s_barrier
	s_setprio 0
	s_cbranch_scc0 .LBB0_716

.Lpz_P11:
	s_add_u32 s14, s12, 0x100
	s_addc_u32 s15, s13, 0
	s_mov_b32 s8, 0
	ds_read_b128 v[56:59], v181
	ds_read_b128 v[68:71], v181 offset:1024
	ds_read_b128 v[72:75], v181 offset:2048
	ds_read_b128 v[76:79], v181 offset:3072
	s_add_i32 s16, s8, 2
	s_add_u32 s6, s10, 0x100
	s_addc_u32 s7, s11, 0
	s_cmp_eq_u32 s66, s8
	s_cselect_b32 s8, s48, s14
	s_cselect_b32 s13, s47, s7
	s_cselect_b32 s12, s46, s6
	s_cselect_b32 s9, s49, s15
	v_lshl_add_u64 v[196:197], s[10:11], 0, v[164:165]
	s_add_i32 m0, s53, 0xc000
	ds_read_b128 v[144:147], v182
	ds_read_b128 v[148:151], v182 offset:1024
	ds_read_b128 v[152:155], v182 offset:2048
	ds_read_b128 v[156:159], v182 offset:3072
	ds_read_b128 v[172:175], v182 offset:4096
	ds_read_b128 v[184:187], v182 offset:5120
	ds_read_b128 v[188:191], v182 offset:6144
	ds_read_b128 v[192:195], v182 offset:7168
	global_load_lds_dwordx4 v[196:197], off
	v_lshl_add_u64 v[196:197], s[10:11], 0, v[166:167]
	s_add_i32 m0, s53, 0xe000
	s_nop 0
	global_load_lds_dwordx4 v[196:197], off
	s_waitcnt lgkmcnt(8)
	s_setprio 1
	s_barrier
	s_waitcnt lgkmcnt(0)
	v_mfma_f32_16x16x32_bf16 v[136:139], v[56:59], v[144:147], 0
	v_mfma_f32_16x16x32_bf16 v[140:143], v[72:75], v[144:147], 0
	v_mfma_f32_16x16x32_bf16 v[124:127], v[56:59], v[152:155], 0
	v_mfma_f32_16x16x32_bf16 v[120:123], v[72:75], v[152:155], 0
	v_mfma_f32_16x16x32_bf16 v[108:111], v[56:59], v[172:175], 0
	v_mfma_f32_16x16x32_bf16 v[104:107], v[72:75], v[172:175], 0
	v_mfma_f32_16x16x32_bf16 v[92:95], v[56:59], v[188:191], 0
	v_mfma_f32_16x16x32_bf16 v[88:91], v[72:75], v[188:191], 0
	v_mfma_f32_16x16x32_bf16 v[136:139], v[68:71], v[148:151], v[136:139]
	v_mfma_f32_16x16x32_bf16 v[140:143], v[76:79], v[148:151], v[140:143]
	v_mfma_f32_16x16x32_bf16 v[124:127], v[68:71], v[156:159], v[124:127]
	v_mfma_f32_16x16x32_bf16 v[120:123], v[76:79], v[156:159], v[120:123]
	v_mfma_f32_16x16x32_bf16 v[108:111], v[68:71], v[184:187], v[108:111]
	v_mfma_f32_16x16x32_bf16 v[104:107], v[76:79], v[184:187], v[104:107]
	v_mfma_f32_16x16x32_bf16 v[92:95], v[68:71], v[192:195], v[92:95]
	v_mfma_f32_16x16x32_bf16 v[88:91], v[76:79], v[192:195], v[88:91]
	s_barrier
	s_setprio 0
	s_add_i32 s10, s88, s52
	v_lshl_add_u64 v[212:213], s[8:9], 0, v[160:161]
	s_mov_b32 m0, s10
	ds_read_b128 v[196:199], v183
	ds_read_b128 v[200:203], v183 offset:1024
	ds_read_b128 v[204:207], v183 offset:2048
	ds_read_b128 v[208:211], v183 offset:3072
	global_load_lds_dwordx4 v[212:213], off
	v_lshl_add_u64 v[214:215], s[8:9], 0, v[162:163]
	s_add_i32 m0, s10, 0x2000
	s_nop 0
	global_load_lds_dwordx4 v[214:215], off
	s_waitcnt lgkmcnt(0)
	s_setprio 1
	s_barrier
	v_mfma_f32_16x16x32_bf16 v[132:135], v[196:199], v[144:147], 0
	v_mfma_f32_16x16x32_bf16 v[128:131], v[204:207], v[144:147], 0
	v_mfma_f32_16x16x32_bf16 v[116:119], v[196:199], v[152:155], 0
	v_mfma_f32_16x16x32_bf16 v[112:115], v[204:207], v[152:155], 0
	v_mfma_f32_16x16x32_bf16 v[100:103], v[196:199], v[172:175], 0
	v_mfma_f32_16x16x32_bf16 v[96:99], v[204:207], v[172:175], 0
	v_mfma_f32_16x16x32_bf16 v[84:87], v[196:199], v[188:191], 0
	v_mfma_f32_16x16x32_bf16 v[80:83], v[204:207], v[188:191], 0
	v_mfma_f32_16x16x32_bf16 v[132:135], v[200:203], v[148:151], v[132:135]
	v_mfma_f32_16x16x32_bf16 v[128:131], v[208:211], v[148:151], v[128:131]
	v_mfma_f32_16x16x32_bf16 v[116:119], v[200:203], v[156:159], v[116:119]
	v_mfma_f32_16x16x32_bf16 v[112:115], v[208:211], v[156:159], v[112:115]
	v_mfma_f32_16x16x32_bf16 v[100:103], v[200:203], v[184:187], v[100:103]
	v_mfma_f32_16x16x32_bf16 v[96:99], v[208:211], v[184:187], v[96:99]
	v_mfma_f32_16x16x32_bf16 v[84:87], v[200:203], v[192:195], v[84:87]
	v_mfma_f32_16x16x32_bf16 v[80:83], v[208:211], v[192:195], v[80:83]
	s_mov_b32 m0, s53
	v_lshl_add_u64 v[216:217], s[12:13], 0, v[160:161]
	s_barrier
	s_setprio 0
	ds_read_b128 v[144:147], v182 offset:16384
	ds_read_b128 v[148:151], v182 offset:17408
	ds_read_b128 v[152:155], v182 offset:18432
	ds_read_b128 v[156:159], v182 offset:19456
	ds_read_b128 v[172:175], v182 offset:20480
	ds_read_b128 v[184:187], v182 offset:21504
	ds_read_b128 v[188:191], v182 offset:22528
	ds_read_b128 v[192:195], v182 offset:23552
	global_load_lds_dwordx4 v[216:217], off
	v_lshl_add_u64 v[218:219], s[12:13], 0, v[162:163]
	s_mov_b32 m0, s54
	s_nop 0
	global_load_lds_dwordx4 v[218:219], off
	s_waitcnt lgkmcnt(0)
	s_setprio 1
	s_barrier
	v_mfma_f32_16x16x32_bf16 v[64:67], v[56:59], v[144:147], 0
	v_mfma_f32_16x16x32_bf16 v[60:63], v[72:75], v[144:147], 0
	v_mfma_f32_16x16x32_bf16 v[44:47], v[56:59], v[152:155], 0
	v_mfma_f32_16x16x32_bf16 v[40:43], v[72:75], v[152:155], 0
	v_mfma_f32_16x16x32_bf16 v[28:31], v[56:59], v[172:175], 0
	v_mfma_f32_16x16x32_bf16 v[24:27], v[72:75], v[172:175], 0
	v_mfma_f32_16x16x32_bf16 v[12:15], v[56:59], v[188:191], 0
	v_mfma_f32_16x16x32_bf16 v[8:11], v[72:75], v[188:191], 0
	v_mfma_f32_16x16x32_bf16 v[64:67], v[68:71], v[148:151], v[64:67]
	v_mfma_f32_16x16x32_bf16 v[60:63], v[76:79], v[148:151], v[60:63]
	v_mfma_f32_16x16x32_bf16 v[44:47], v[68:71], v[156:159], v[44:47]
	v_mfma_f32_16x16x32_bf16 v[40:43], v[76:79], v[156:159], v[40:43]
	v_mfma_f32_16x16x32_bf16 v[28:31], v[68:71], v[184:187], v[28:31]
	v_mfma_f32_16x16x32_bf16 v[24:27], v[76:79], v[184:187], v[24:27]
	v_mfma_f32_16x16x32_bf16 v[12:15], v[68:71], v[192:195], v[12:15]
	v_mfma_f32_16x16x32_bf16 v[8:11], v[76:79], v[192:195], v[8:11]
	s_barrier
	s_setprio 0
	s_add_u32 s10, s8, 0xb0000
	s_addc_u32 s11, s9, 0
	s_add_i32 s17, s89, s52
	v_lshl_add_u64 v[56:57], s[10:11], 0, v[160:161]
	s_mov_b32 m0, s17
	s_nop 0
	global_load_lds_dwordx4 v[56:57], off
	v_lshl_add_u64 v[56:57], s[10:11], 0, v[162:163]
	s_add_i32 m0, s17, 0x2000
	s_nop 0
	global_load_lds_dwordx4 v[56:57], off
	s_waitcnt vmcnt(6)
	s_setprio 1
	s_barrier
	v_mfma_f32_16x16x32_bf16 v[52:55], v[196:199], v[144:147], 0
	v_mfma_f32_16x16x32_bf16 v[48:51], v[204:207], v[144:147], 0
	v_mfma_f32_16x16x32_bf16 v[36:39], v[196:199], v[152:155], 0
	v_mfma_f32_16x16x32_bf16 v[32:35], v[204:207], v[152:155], 0
	v_mfma_f32_16x16x32_bf16 v[20:23], v[196:199], v[172:175], 0
	v_mfma_f32_16x16x32_bf16 v[16:19], v[204:207], v[172:175], 0
	v_mfma_f32_16x16x32_bf16 v[4:7], v[196:199], v[188:191], 0
	v_mfma_f32_16x16x32_bf16 v[0:3], v[204:207], v[188:191], 0
	v_mfma_f32_16x16x32_bf16 v[52:55], v[200:203], v[148:151], v[52:55]
	v_mfma_f32_16x16x32_bf16 v[48:51], v[208:211], v[148:151], v[48:51]
	v_mfma_f32_16x16x32_bf16 v[36:39], v[200:203], v[156:159], v[36:39]
	v_mfma_f32_16x16x32_bf16 v[32:35], v[208:211], v[156:159], v[32:35]
	v_mfma_f32_16x16x32_bf16 v[20:23], v[200:203], v[184:187], v[20:23]
	v_mfma_f32_16x16x32_bf16 v[16:19], v[208:211], v[184:187], v[16:19]
	v_mfma_f32_16x16x32_bf16 v[4:7], v[200:203], v[192:195], v[4:7]
	v_mfma_f32_16x16x32_bf16 v[0:3], v[208:211], v[192:195], v[0:3]
	s_add_i32 s17, 0, 0x18000
	v_add_u32_e32 v76, s17, v177
	s_barrier
	s_setprio 0
	ds_read_b128 v[56:59], v76
	ds_read_b128 v[68:71], v76 offset:1024
	ds_read_b128 v[72:75], v76 offset:2048
	ds_read_b128 v[76:79], v76 offset:3072
	s_add_u32 s10, s12, 0xb0000
	s_addc_u32 s11, s13, 0
	s_mov_b32 m0, s55
	v_lshl_add_u64 v[196:197], s[10:11], 0, v[160:161]
	ds_read_b128 v[144:147], v182 offset:32768
	ds_read_b128 v[148:151], v182 offset:33792
	ds_read_b128 v[152:155], v182 offset:34816
	ds_read_b128 v[156:159], v182 offset:35840
	ds_read_b128 v[172:175], v182 offset:36864
	ds_read_b128 v[184:187], v182 offset:37888
	ds_read_b128 v[188:191], v182 offset:38912
	ds_read_b128 v[192:195], v182 offset:39936
	global_load_lds_dwordx4 v[196:197], off
	v_lshl_add_u64 v[196:197], s[10:11], 0, v[162:163]
	s_mov_b32 m0, s56
	s_nop 0
	global_load_lds_dwordx4 v[196:197], off
	s_waitcnt lgkmcnt(8)
	s_setprio 1
	s_barrier
	s_waitcnt lgkmcnt(0)
	v_mfma_f32_16x16x32_bf16 v[136:139], v[56:59], v[144:147], v[136:139]
	v_mfma_f32_16x16x32_bf16 v[140:143], v[72:75], v[144:147], v[140:143]
	v_mfma_f32_16x16x32_bf16 v[124:127], v[56:59], v[152:155], v[124:127]
	v_mfma_f32_16x16x32_bf16 v[120:123], v[72:75], v[152:155], v[120:123]
	v_mfma_f32_16x16x32_bf16 v[108:111], v[56:59], v[172:175], v[108:111]
	v_mfma_f32_16x16x32_bf16 v[104:107], v[72:75], v[172:175], v[104:107]
	v_mfma_f32_16x16x32_bf16 v[92:95], v[56:59], v[188:191], v[92:95]
	v_mfma_f32_16x16x32_bf16 v[88:91], v[72:75], v[188:191], v[88:91]
	v_mfma_f32_16x16x32_bf16 v[136:139], v[68:71], v[148:151], v[136:139]
	v_mfma_f32_16x16x32_bf16 v[140:143], v[76:79], v[148:151], v[140:143]
	v_mfma_f32_16x16x32_bf16 v[124:127], v[68:71], v[156:159], v[124:127]
	v_mfma_f32_16x16x32_bf16 v[120:123], v[76:79], v[156:159], v[120:123]
	v_mfma_f32_16x16x32_bf16 v[108:111], v[68:71], v[184:187], v[108:111]
	v_mfma_f32_16x16x32_bf16 v[104:107], v[76:79], v[184:187], v[104:107]
	v_mfma_f32_16x16x32_bf16 v[92:95], v[68:71], v[192:195], v[92:95]
	v_mfma_f32_16x16x32_bf16 v[88:91], v[76:79], v[192:195], v[88:91]
	s_barrier
	s_setprio 0
	s_add_i32 s10, 0, 0x1c000
	s_add_i32 s11, s17, s52
	v_add_u32_e32 v208, s10, v177
	v_lshl_add_u64 v[212:213], v[212:213], 0, s[36:37]
	s_mov_b32 m0, s11
	ds_read_b128 v[196:199], v208
	ds_read_b128 v[200:203], v208 offset:1024
	ds_read_b128 v[204:207], v208 offset:2048
	ds_read_b128 v[208:211], v208 offset:3072
	global_load_lds_dwordx4 v[212:213], off
	v_lshl_add_u64 v[212:213], v[214:215], 0, s[36:37]
	s_add_i32 m0, s11, 0x2000
	s_nop 0
	global_load_lds_dwordx4 v[212:213], off
	s_waitcnt lgkmcnt(0)
	s_setprio 1
	s_barrier
	v_mfma_f32_16x16x32_bf16 v[132:135], v[196:199], v[144:147], v[132:135]
	v_mfma_f32_16x16x32_bf16 v[128:131], v[204:207], v[144:147], v[128:131]
	v_mfma_f32_16x16x32_bf16 v[116:119], v[196:199], v[152:155], v[116:119]
	v_mfma_f32_16x16x32_bf16 v[112:115], v[204:207], v[152:155], v[112:115]
	v_mfma_f32_16x16x32_bf16 v[100:103], v[196:199], v[172:175], v[100:103]
	v_mfma_f32_16x16x32_bf16 v[96:99], v[204:207], v[172:175], v[96:99]
	v_mfma_f32_16x16x32_bf16 v[84:87], v[196:199], v[188:191], v[84:87]
	v_mfma_f32_16x16x32_bf16 v[80:83], v[204:207], v[188:191], v[80:83]
	v_mfma_f32_16x16x32_bf16 v[132:135], v[200:203], v[148:151], v[132:135]
	v_mfma_f32_16x16x32_bf16 v[128:131], v[208:211], v[148:151], v[128:131]
	v_mfma_f32_16x16x32_bf16 v[116:119], v[200:203], v[156:159], v[116:119]
	v_mfma_f32_16x16x32_bf16 v[112:115], v[208:211], v[156:159], v[112:115]
	v_mfma_f32_16x16x32_bf16 v[100:103], v[200:203], v[184:187], v[100:103]
	v_mfma_f32_16x16x32_bf16 v[96:99], v[208:211], v[184:187], v[96:99]
	v_mfma_f32_16x16x32_bf16 v[84:87], v[200:203], v[192:195], v[84:87]
	v_mfma_f32_16x16x32_bf16 v[80:83], v[208:211], v[192:195], v[80:83]
	s_mov_b32 m0, s64
	v_lshl_add_u64 v[212:213], v[216:217], 0, s[36:37]
	s_barrier
	s_setprio 0
	ds_read_b128 v[144:147], v182 offset:49152
	ds_read_b128 v[148:151], v182 offset:50176
	ds_read_b128 v[152:155], v182 offset:51200
	ds_read_b128 v[156:159], v182 offset:52224
	ds_read_b128 v[172:175], v182 offset:53248
	ds_read_b128 v[184:187], v182 offset:54272
	ds_read_b128 v[188:191], v182 offset:55296
	ds_read_b128 v[192:195], v182 offset:56320
	global_load_lds_dwordx4 v[212:213], off
	v_lshl_add_u64 v[212:213], v[218:219], 0, s[36:37]
	s_mov_b32 m0, s65
	s_nop 0
	global_load_lds_dwordx4 v[212:213], off
	s_waitcnt lgkmcnt(0)
	s_setprio 1
	s_barrier
	v_mfma_f32_16x16x32_bf16 v[64:67], v[56:59], v[144:147], v[64:67]
	v_mfma_f32_16x16x32_bf16 v[60:63], v[72:75], v[144:147], v[60:63]
	v_mfma_f32_16x16x32_bf16 v[44:47], v[56:59], v[152:155], v[44:47]
	v_mfma_f32_16x16x32_bf16 v[40:43], v[72:75], v[152:155], v[40:43]
	v_mfma_f32_16x16x32_bf16 v[28:31], v[56:59], v[172:175], v[28:31]
	v_mfma_f32_16x16x32_bf16 v[24:27], v[72:75], v[172:175], v[24:27]
	v_mfma_f32_16x16x32_bf16 v[12:15], v[56:59], v[188:191], v[12:15]
	v_mfma_f32_16x16x32_bf16 v[8:11], v[72:75], v[188:191], v[8:11]
	v_mfma_f32_16x16x32_bf16 v[64:67], v[68:71], v[148:151], v[64:67]
	v_mfma_f32_16x16x32_bf16 v[60:63], v[76:79], v[148:151], v[60:63]
	v_mfma_f32_16x16x32_bf16 v[44:47], v[68:71], v[156:159], v[44:47]
	v_mfma_f32_16x16x32_bf16 v[40:43], v[76:79], v[156:159], v[40:43]
	v_mfma_f32_16x16x32_bf16 v[28:31], v[68:71], v[184:187], v[28:31]
	v_mfma_f32_16x16x32_bf16 v[24:27], v[76:79], v[184:187], v[24:27]
	v_mfma_f32_16x16x32_bf16 v[12:15], v[68:71], v[192:195], v[12:15]
	v_mfma_f32_16x16x32_bf16 v[8:11], v[76:79], v[192:195], v[8:11]
	s_barrier
	s_setprio 0
	s_add_u32 s8, s8, 0xb0080
	s_addc_u32 s9, s9, 0
	s_add_i32 s10, s10, s52
	v_lshl_add_u64 v[56:57], s[8:9], 0, v[160:161]
	s_mov_b32 m0, s10
	s_nop 0
	global_load_lds_dwordx4 v[56:57], off
	v_lshl_add_u64 v[56:57], s[8:9], 0, v[162:163]
	s_add_i32 m0, s10, 0x2000
	s_nop 0
	global_load_lds_dwordx4 v[56:57], off
	s_waitcnt vmcnt(6)
	s_setprio 1
	s_barrier
	v_mfma_f32_16x16x32_bf16 v[52:55], v[196:199], v[144:147], v[52:55]
	v_mfma_f32_16x16x32_bf16 v[48:51], v[204:207], v[144:147], v[48:51]
	v_mfma_f32_16x16x32_bf16 v[36:39], v[196:199], v[152:155], v[36:39]
	v_mfma_f32_16x16x32_bf16 v[32:35], v[204:207], v[152:155], v[32:35]
	v_mfma_f32_16x16x32_bf16 v[20:23], v[196:199], v[172:175], v[20:23]
	v_mfma_f32_16x16x32_bf16 v[16:19], v[204:207], v[172:175], v[16:19]
	v_mfma_f32_16x16x32_bf16 v[4:7], v[196:199], v[188:191], v[4:7]
	v_mfma_f32_16x16x32_bf16 v[0:3], v[204:207], v[188:191], v[0:3]
	v_mfma_f32_16x16x32_bf16 v[52:55], v[200:203], v[148:151], v[52:55]
	v_mfma_f32_16x16x32_bf16 v[48:51], v[208:211], v[148:151], v[48:51]
	v_mfma_f32_16x16x32_bf16 v[36:39], v[200:203], v[156:159], v[36:39]
	v_mfma_f32_16x16x32_bf16 v[32:35], v[208:211], v[156:159], v[32:35]
	v_mfma_f32_16x16x32_bf16 v[20:23], v[200:203], v[184:187], v[20:23]
	v_mfma_f32_16x16x32_bf16 v[16:19], v[208:211], v[184:187], v[16:19]
	v_mfma_f32_16x16x32_bf16 v[4:7], v[200:203], v[192:195], v[4:7]
	v_mfma_f32_16x16x32_bf16 v[0:3], v[208:211], v[192:195], v[0:3]
	s_add_u32 s14, s14, 0x100
	s_addc_u32 s15, s15, 0
	s_cmp_lt_i32 s16, s62
	s_mov_b64 s[10:11], s[6:7]
	s_mov_b32 s8, s16
	s_barrier
	s_setprio 0
	s_cbranch_scc0 .Lpeel_done_P11
.LBB0_798:
	ds_read_b128 v[56:59], v181
	ds_read_b128 v[68:71], v181 offset:1024
	ds_read_b128 v[72:75], v181 offset:2048
	ds_read_b128 v[76:79], v181 offset:3072
	s_add_i32 s16, s8, 2
	s_add_u32 s6, s10, 0x100
	s_addc_u32 s7, s11, 0
	s_cmp_eq_u32 s66, s8
	s_cselect_b32 s8, s48, s14
	s_cselect_b32 s13, s47, s7
	s_cselect_b32 s12, s46, s6
	s_cselect_b32 s9, s49, s15
	v_lshl_add_u64 v[196:197], s[10:11], 0, v[164:165]
	s_add_i32 m0, s53, 0xc000
	ds_read_b128 v[144:147], v182
	ds_read_b128 v[148:151], v182 offset:1024
	ds_read_b128 v[152:155], v182 offset:2048
	ds_read_b128 v[156:159], v182 offset:3072
	ds_read_b128 v[172:175], v182 offset:4096
	ds_read_b128 v[184:187], v182 offset:5120
	ds_read_b128 v[188:191], v182 offset:6144
	ds_read_b128 v[192:195], v182 offset:7168
	global_load_lds_dwordx4 v[196:197], off
	v_lshl_add_u64 v[196:197], s[10:11], 0, v[166:167]
	s_add_i32 m0, s53, 0xe000
	s_nop 0
	global_load_lds_dwordx4 v[196:197], off
	s_waitcnt lgkmcnt(8)
	s_setprio 1
	s_barrier
	s_waitcnt lgkmcnt(0)
	v_mfma_f32_16x16x32_bf16 v[136:139], v[56:59], v[144:147], v[136:139]
	v_mfma_f32_16x16x32_bf16 v[140:143], v[72:75], v[144:147], v[140:143]
	v_mfma_f32_16x16x32_bf16 v[124:127], v[56:59], v[152:155], v[124:127]
	v_mfma_f32_16x16x32_bf16 v[120:123], v[72:75], v[152:155], v[120:123]
	v_mfma_f32_16x16x32_bf16 v[108:111], v[56:59], v[172:175], v[108:111]
	v_mfma_f32_16x16x32_bf16 v[104:107], v[72:75], v[172:175], v[104:107]
	v_mfma_f32_16x16x32_bf16 v[92:95], v[56:59], v[188:191], v[92:95]
	v_mfma_f32_16x16x32_bf16 v[88:91], v[72:75], v[188:191], v[88:91]
	v_mfma_f32_16x16x32_bf16 v[136:139], v[68:71], v[148:151], v[136:139]
	v_mfma_f32_16x16x32_bf16 v[140:143], v[76:79], v[148:151], v[140:143]
	v_mfma_f32_16x16x32_bf16 v[124:127], v[68:71], v[156:159], v[124:127]
	v_mfma_f32_16x16x32_bf16 v[120:123], v[76:79], v[156:159], v[120:123]
	v_mfma_f32_16x16x32_bf16 v[108:111], v[68:71], v[184:187], v[108:111]
	v_mfma_f32_16x16x32_bf16 v[104:107], v[76:79], v[184:187], v[104:107]
	v_mfma_f32_16x16x32_bf16 v[92:95], v[68:71], v[192:195], v[92:95]
	v_mfma_f32_16x16x32_bf16 v[88:91], v[76:79], v[192:195], v[88:91]
	s_barrier
	s_setprio 0
	s_add_i32 s10, s88, s52
	v_lshl_add_u64 v[212:213], s[8:9], 0, v[160:161]
	s_mov_b32 m0, s10
	ds_read_b128 v[196:199], v183
	ds_read_b128 v[200:203], v183 offset:1024
	ds_read_b128 v[204:207], v183 offset:2048
	ds_read_b128 v[208:211], v183 offset:3072
	global_load_lds_dwordx4 v[212:213], off
	v_lshl_add_u64 v[214:215], s[8:9], 0, v[162:163]
	s_add_i32 m0, s10, 0x2000
	s_nop 0
	global_load_lds_dwordx4 v[214:215], off
	s_waitcnt lgkmcnt(0)
	s_setprio 1
	s_barrier
	v_mfma_f32_16x16x32_bf16 v[132:135], v[196:199], v[144:147], v[132:135]
	v_mfma_f32_16x16x32_bf16 v[128:131], v[204:207], v[144:147], v[128:131]
	v_mfma_f32_16x16x32_bf16 v[116:119], v[196:199], v[152:155], v[116:119]
	v_mfma_f32_16x16x32_bf16 v[112:115], v[204:207], v[152:155], v[112:115]
	v_mfma_f32_16x16x32_bf16 v[100:103], v[196:199], v[172:175], v[100:103]
	v_mfma_f32_16x16x32_bf16 v[96:99], v[204:207], v[172:175], v[96:99]
	v_mfma_f32_16x16x32_bf16 v[84:87], v[196:199], v[188:191], v[84:87]
	v_mfma_f32_16x16x32_bf16 v[80:83], v[204:207], v[188:191], v[80:83]
	v_mfma_f32_16x16x32_bf16 v[132:135], v[200:203], v[148:151], v[132:135]
	v_mfma_f32_16x16x32_bf16 v[128:131], v[208:211], v[148:151], v[128:131]
	v_mfma_f32_16x16x32_bf16 v[116:119], v[200:203], v[156:159], v[116:119]
	v_mfma_f32_16x16x32_bf16 v[112:115], v[208:211], v[156:159], v[112:115]
	v_mfma_f32_16x16x32_bf16 v[100:103], v[200:203], v[184:187], v[100:103]
	v_mfma_f32_16x16x32_bf16 v[96:99], v[208:211], v[184:187], v[96:99]
	v_mfma_f32_16x16x32_bf16 v[84:87], v[200:203], v[192:195], v[84:87]
	v_mfma_f32_16x16x32_bf16 v[80:83], v[208:211], v[192:195], v[80:83]
	s_mov_b32 m0, s53
	v_lshl_add_u64 v[216:217], s[12:13], 0, v[160:161]
	s_barrier
	s_setprio 0
	ds_read_b128 v[144:147], v182 offset:16384
	ds_read_b128 v[148:151], v182 offset:17408
	ds_read_b128 v[152:155], v182 offset:18432
	ds_read_b128 v[156:159], v182 offset:19456
	ds_read_b128 v[172:175], v182 offset:20480
	ds_read_b128 v[184:187], v182 offset:21504
	ds_read_b128 v[188:191], v182 offset:22528
	ds_read_b128 v[192:195], v182 offset:23552
	global_load_lds_dwordx4 v[216:217], off
	v_lshl_add_u64 v[218:219], s[12:13], 0, v[162:163]
	s_mov_b32 m0, s54
	s_nop 0
	global_load_lds_dwordx4 v[218:219], off
	s_waitcnt lgkmcnt(0)
	s_setprio 1
	s_barrier
	v_mfma_f32_16x16x32_bf16 v[64:67], v[56:59], v[144:147], v[64:67]
	v_mfma_f32_16x16x32_bf16 v[60:63], v[72:75], v[144:147], v[60:63]
	v_mfma_f32_16x16x32_bf16 v[44:47], v[56:59], v[152:155], v[44:47]
	v_mfma_f32_16x16x32_bf16 v[40:43], v[72:75], v[152:155], v[40:43]
	v_mfma_f32_16x16x32_bf16 v[28:31], v[56:59], v[172:175], v[28:31]
	v_mfma_f32_16x16x32_bf16 v[24:27], v[72:75], v[172:175], v[24:27]
	v_mfma_f32_16x16x32_bf16 v[12:15], v[56:59], v[188:191], v[12:15]
	v_mfma_f32_16x16x32_bf16 v[8:11], v[72:75], v[188:191], v[8:11]
	v_mfma_f32_16x16x32_bf16 v[64:67], v[68:71], v[148:151], v[64:67]
	v_mfma_f32_16x16x32_bf16 v[60:63], v[76:79], v[148:151], v[60:63]
	v_mfma_f32_16x16x32_bf16 v[44:47], v[68:71], v[156:159], v[44:47]
	v_mfma_f32_16x16x32_bf16 v[40:43], v[76:79], v[156:159], v[40:43]
	v_mfma_f32_16x16x32_bf16 v[28:31], v[68:71], v[184:187], v[28:31]
	v_mfma_f32_16x16x32_bf16 v[24:27], v[76:79], v[184:187], v[24:27]
	v_mfma_f32_16x16x32_bf16 v[12:15], v[68:71], v[192:195], v[12:15]
	v_mfma_f32_16x16x32_bf16 v[8:11], v[76:79], v[192:195], v[8:11]
	s_barrier
	s_setprio 0
	s_add_u32 s10, s8, 0xb0000
	s_addc_u32 s11, s9, 0
	s_add_i32 s17, s89, s52
	v_lshl_add_u64 v[56:57], s[10:11], 0, v[160:161]
	s_mov_b32 m0, s17
	s_nop 0
	global_load_lds_dwordx4 v[56:57], off
	v_lshl_add_u64 v[56:57], s[10:11], 0, v[162:163]
	s_add_i32 m0, s17, 0x2000
	s_nop 0
	global_load_lds_dwordx4 v[56:57], off
	s_waitcnt vmcnt(6)
	s_setprio 1
	s_barrier
	v_mfma_f32_16x16x32_bf16 v[52:55], v[196:199], v[144:147], v[52:55]
	v_mfma_f32_16x16x32_bf16 v[48:51], v[204:207], v[144:147], v[48:51]
	v_mfma_f32_16x16x32_bf16 v[36:39], v[196:199], v[152:155], v[36:39]
	v_mfma_f32_16x16x32_bf16 v[32:35], v[204:207], v[152:155], v[32:35]
	v_mfma_f32_16x16x32_bf16 v[20:23], v[196:199], v[172:175], v[20:23]
	v_mfma_f32_16x16x32_bf16 v[16:19], v[204:207], v[172:175], v[16:19]
	v_mfma_f32_16x16x32_bf16 v[4:7], v[196:199], v[188:191], v[4:7]
	v_mfma_f32_16x16x32_bf16 v[0:3], v[204:207], v[188:191], v[0:3]
	v_mfma_f32_16x16x32_bf16 v[52:55], v[200:203], v[148:151], v[52:55]
	v_mfma_f32_16x16x32_bf16 v[48:51], v[208:211], v[148:151], v[48:51]
	v_mfma_f32_16x16x32_bf16 v[36:39], v[200:203], v[156:159], v[36:39]
	v_mfma_f32_16x16x32_bf16 v[32:35], v[208:211], v[156:159], v[32:35]
	v_mfma_f32_16x16x32_bf16 v[20:23], v[200:203], v[184:187], v[20:23]
	v_mfma_f32_16x16x32_bf16 v[16:19], v[208:211], v[184:187], v[16:19]
	v_mfma_f32_16x16x32_bf16 v[4:7], v[200:203], v[192:195], v[4:7]
	v_mfma_f32_16x16x32_bf16 v[0:3], v[208:211], v[192:195], v[0:3]
	s_add_i32 s17, 0, 0x18000
	v_add_u32_e32 v76, s17, v177
	s_barrier
	s_setprio 0
	ds_read_b128 v[56:59], v76
	ds_read_b128 v[68:71], v76 offset:1024
	ds_read_b128 v[72:75], v76 offset:2048
	ds_read_b128 v[76:79], v76 offset:3072
	s_add_u32 s10, s12, 0xb0000
	s_addc_u32 s11, s13, 0
	s_mov_b32 m0, s55
	v_lshl_add_u64 v[196:197], s[10:11], 0, v[160:161]
	ds_read_b128 v[144:147], v182 offset:32768
	ds_read_b128 v[148:151], v182 offset:33792
	ds_read_b128 v[152:155], v182 offset:34816
	ds_read_b128 v[156:159], v182 offset:35840
	ds_read_b128 v[172:175], v182 offset:36864
	ds_read_b128 v[184:187], v182 offset:37888
	ds_read_b128 v[188:191], v182 offset:38912
	ds_read_b128 v[192:195], v182 offset:39936
	global_load_lds_dwordx4 v[196:197], off
	v_lshl_add_u64 v[196:197], s[10:11], 0, v[162:163]
	s_mov_b32 m0, s56
	s_nop 0
	global_load_lds_dwordx4 v[196:197], off
	s_waitcnt lgkmcnt(8)
	s_setprio 1
	s_barrier
	s_waitcnt lgkmcnt(0)
	v_mfma_f32_16x16x32_bf16 v[136:139], v[56:59], v[144:147], v[136:139]
	v_mfma_f32_16x16x32_bf16 v[140:143], v[72:75], v[144:147], v[140:143]
	v_mfma_f32_16x16x32_bf16 v[124:127], v[56:59], v[152:155], v[124:127]
	v_mfma_f32_16x16x32_bf16 v[120:123], v[72:75], v[152:155], v[120:123]
	v_mfma_f32_16x16x32_bf16 v[108:111], v[56:59], v[172:175], v[108:111]
	v_mfma_f32_16x16x32_bf16 v[104:107], v[72:75], v[172:175], v[104:107]
	v_mfma_f32_16x16x32_bf16 v[92:95], v[56:59], v[188:191], v[92:95]
	v_mfma_f32_16x16x32_bf16 v[88:91], v[72:75], v[188:191], v[88:91]
	v_mfma_f32_16x16x32_bf16 v[136:139], v[68:71], v[148:151], v[136:139]
	v_mfma_f32_16x16x32_bf16 v[140:143], v[76:79], v[148:151], v[140:143]
	v_mfma_f32_16x16x32_bf16 v[124:127], v[68:71], v[156:159], v[124:127]
	v_mfma_f32_16x16x32_bf16 v[120:123], v[76:79], v[156:159], v[120:123]
	v_mfma_f32_16x16x32_bf16 v[108:111], v[68:71], v[184:187], v[108:111]
	v_mfma_f32_16x16x32_bf16 v[104:107], v[76:79], v[184:187], v[104:107]
	v_mfma_f32_16x16x32_bf16 v[92:95], v[68:71], v[192:195], v[92:95]
	v_mfma_f32_16x16x32_bf16 v[88:91], v[76:79], v[192:195], v[88:91]
	s_barrier
	s_setprio 0
	s_add_i32 s10, 0, 0x1c000
	s_add_i32 s11, s17, s52
	v_add_u32_e32 v208, s10, v177
	v_lshl_add_u64 v[212:213], v[212:213], 0, s[36:37]
	s_mov_b32 m0, s11
	ds_read_b128 v[196:199], v208
	ds_read_b128 v[200:203], v208 offset:1024
	ds_read_b128 v[204:207], v208 offset:2048
	ds_read_b128 v[208:211], v208 offset:3072
	global_load_lds_dwordx4 v[212:213], off
	v_lshl_add_u64 v[212:213], v[214:215], 0, s[36:37]
	s_add_i32 m0, s11, 0x2000
	s_nop 0
	global_load_lds_dwordx4 v[212:213], off
	s_waitcnt lgkmcnt(0)
	s_setprio 1
	s_barrier
	v_mfma_f32_16x16x32_bf16 v[132:135], v[196:199], v[144:147], v[132:135]
	v_mfma_f32_16x16x32_bf16 v[128:131], v[204:207], v[144:147], v[128:131]
	v_mfma_f32_16x16x32_bf16 v[116:119], v[196:199], v[152:155], v[116:119]
	v_mfma_f32_16x16x32_bf16 v[112:115], v[204:207], v[152:155], v[112:115]
	v_mfma_f32_16x16x32_bf16 v[100:103], v[196:199], v[172:175], v[100:103]
	v_mfma_f32_16x16x32_bf16 v[96:99], v[204:207], v[172:175], v[96:99]
	v_mfma_f32_16x16x32_bf16 v[84:87], v[196:199], v[188:191], v[84:87]
	v_mfma_f32_16x16x32_bf16 v[80:83], v[204:207], v[188:191], v[80:83]
	v_mfma_f32_16x16x32_bf16 v[132:135], v[200:203], v[148:151], v[132:135]
	v_mfma_f32_16x16x32_bf16 v[128:131], v[208:211], v[148:151], v[128:131]
	v_mfma_f32_16x16x32_bf16 v[116:119], v[200:203], v[156:159], v[116:119]
	v_mfma_f32_16x16x32_bf16 v[112:115], v[208:211], v[156:159], v[112:115]
	v_mfma_f32_16x16x32_bf16 v[100:103], v[200:203], v[184:187], v[100:103]
	v_mfma_f32_16x16x32_bf16 v[96:99], v[208:211], v[184:187], v[96:99]
	v_mfma_f32_16x16x32_bf16 v[84:87], v[200:203], v[192:195], v[84:87]
	v_mfma_f32_16x16x32_bf16 v[80:83], v[208:211], v[192:195], v[80:83]
	s_mov_b32 m0, s64
	v_lshl_add_u64 v[212:213], v[216:217], 0, s[36:37]
	s_barrier
	s_setprio 0
	ds_read_b128 v[144:147], v182 offset:49152
	ds_read_b128 v[148:151], v182 offset:50176
	ds_read_b128 v[152:155], v182 offset:51200
	ds_read_b128 v[156:159], v182 offset:52224
	ds_read_b128 v[172:175], v182 offset:53248
	ds_read_b128 v[184:187], v182 offset:54272
	ds_read_b128 v[188:191], v182 offset:55296
	ds_read_b128 v[192:195], v182 offset:56320
	global_load_lds_dwordx4 v[212:213], off
	v_lshl_add_u64 v[212:213], v[218:219], 0, s[36:37]
	s_mov_b32 m0, s65
	s_nop 0
	global_load_lds_dwordx4 v[212:213], off
	s_waitcnt lgkmcnt(0)
	s_setprio 1
	s_barrier
	v_mfma_f32_16x16x32_bf16 v[64:67], v[56:59], v[144:147], v[64:67]
	v_mfma_f32_16x16x32_bf16 v[60:63], v[72:75], v[144:147], v[60:63]
	v_mfma_f32_16x16x32_bf16 v[44:47], v[56:59], v[152:155], v[44:47]
	v_mfma_f32_16x16x32_bf16 v[40:43], v[72:75], v[152:155], v[40:43]
	v_mfma_f32_16x16x32_bf16 v[28:31], v[56:59], v[172:175], v[28:31]
	v_mfma_f32_16x16x32_bf16 v[24:27], v[72:75], v[172:175], v[24:27]
	v_mfma_f32_16x16x32_bf16 v[12:15], v[56:59], v[188:191], v[12:15]
	v_mfma_f32_16x16x32_bf16 v[8:11], v[72:75], v[188:191], v[8:11]
	v_mfma_f32_16x16x32_bf16 v[64:67], v[68:71], v[148:151], v[64:67]
	v_mfma_f32_16x16x32_bf16 v[60:63], v[76:79], v[148:151], v[60:63]
	v_mfma_f32_16x16x32_bf16 v[44:47], v[68:71], v[156:159], v[44:47]
	v_mfma_f32_16x16x32_bf16 v[40:43], v[76:79], v[156:159], v[40:43]
	v_mfma_f32_16x16x32_bf16 v[28:31], v[68:71], v[184:187], v[28:31]
	v_mfma_f32_16x16x32_bf16 v[24:27], v[76:79], v[184:187], v[24:27]
	v_mfma_f32_16x16x32_bf16 v[12:15], v[68:71], v[192:195], v[12:15]
	v_mfma_f32_16x16x32_bf16 v[8:11], v[76:79], v[192:195], v[8:11]
	s_barrier
	s_setprio 0
	s_add_u32 s8, s8, 0xb0080
	s_addc_u32 s9, s9, 0
	s_add_i32 s10, s10, s52
	v_lshl_add_u64 v[56:57], s[8:9], 0, v[160:161]
	s_mov_b32 m0, s10
	s_nop 0
	global_load_lds_dwordx4 v[56:57], off
	v_lshl_add_u64 v[56:57], s[8:9], 0, v[162:163]
	s_add_i32 m0, s10, 0x2000
	s_nop 0
	global_load_lds_dwordx4 v[56:57], off
	s_waitcnt vmcnt(6)
	s_setprio 1
	s_barrier
	v_mfma_f32_16x16x32_bf16 v[52:55], v[196:199], v[144:147], v[52:55]
	v_mfma_f32_16x16x32_bf16 v[48:51], v[204:207], v[144:147], v[48:51]
	v_mfma_f32_16x16x32_bf16 v[36:39], v[196:199], v[152:155], v[36:39]
	v_mfma_f32_16x16x32_bf16 v[32:35], v[204:207], v[152:155], v[32:35]
	v_mfma_f32_16x16x32_bf16 v[20:23], v[196:199], v[172:175], v[20:23]
	v_mfma_f32_16x16x32_bf16 v[16:19], v[204:207], v[172:175], v[16:19]
	v_mfma_f32_16x16x32_bf16 v[4:7], v[196:199], v[188:191], v[4:7]
	v_mfma_f32_16x16x32_bf16 v[0:3], v[204:207], v[188:191], v[0:3]
	v_mfma_f32_16x16x32_bf16 v[52:55], v[200:203], v[148:151], v[52:55]
	v_mfma_f32_16x16x32_bf16 v[48:51], v[208:211], v[148:151], v[48:51]
	v_mfma_f32_16x16x32_bf16 v[36:39], v[200:203], v[156:159], v[36:39]
	v_mfma_f32_16x16x32_bf16 v[32:35], v[208:211], v[156:159], v[32:35]
	v_mfma_f32_16x16x32_bf16 v[20:23], v[200:203], v[184:187], v[20:23]
	v_mfma_f32_16x16x32_bf16 v[16:19], v[208:211], v[184:187], v[16:19]
	v_mfma_f32_16x16x32_bf16 v[4:7], v[200:203], v[192:195], v[4:7]
	v_mfma_f32_16x16x32_bf16 v[0:3], v[208:211], v[192:195], v[0:3]
	s_add_u32 s14, s14, 0x100
	s_addc_u32 s15, s15, 0
	s_cmp_lt_i32 s16, s62
	s_mov_b64 s[10:11], s[6:7]
	s_mov_b32 s8, s16
	s_barrier
	s_setprio 0
	s_cbranch_scc1 .LBB0_798
